# v5 with the LDS staging writes moved earlier inside the converted gates k-tile segments
# baseline (speedup 1.0000x reference)
.LBB0_749:
	s_and_b32 s3, s2, 0xffff
	s_mul_i32 s3, s3, 0xaaab
	s_lshr_b32 s3, s3, 18
	s_mul_i32 s10, s3, 6
	s_sub_i32 s2, s2, s10
	s_and_b32 s2, s2, 0xffff
	s_add_i32 s2, s6, s2
	s_lshl_b32 s10, s2, 7
	v_or_b32_e32 v2, s10, v91
	v_lshlrev_b32_e32 v66, 11, v2
	v_lshl_add_u64 v[74:75], v[68:69], 0, v[66:67]
	v_add_lshl_u32 v66, s10, v92, 11
	s_add_i32 s3, s8, s3
	v_lshl_add_u64 v[76:77], v[68:69], 0, v[66:67]
	v_add_lshl_u32 v66, s10, v93, 11
	s_lshl_b32 s11, s3, 7
	v_lshl_add_u64 v[78:79], v[68:69], 0, v[66:67]
	v_add_lshl_u32 v66, s10, v94, 11
	v_lshl_add_u64 v[80:81], v[68:69], 0, v[66:67]
	v_or_b32_e32 v66, s11, v91
	v_lshlrev_b64 v[2:3], 11, v[66:67]
	v_add_u32_e32 v66, s11, v92
	v_lshl_add_u64 v[82:83], v[70:71], 0, v[2:3]
	v_lshlrev_b64 v[2:3], 11, v[66:67]
	v_add_u32_e32 v66, s11, v93
	v_lshl_add_u64 v[84:85], v[70:71], 0, v[2:3]
	v_lshlrev_b64 v[2:3], 11, v[66:67]
	v_add_u32_e32 v66, s11, v94
	v_lshl_add_u64 v[86:87], v[70:71], 0, v[2:3]
	v_lshlrev_b64 v[2:3], 11, v[66:67]
	v_lshl_add_u64 v[88:89], v[70:71], 0, v[2:3]
	global_load_dwordx4 v[2:5], v[74:75], off
	global_load_dwordx4 v[6:9], v[76:77], off
	global_load_dwordx4 v[10:13], v[78:79], off
	global_load_dwordx4 v[14:17], v[80:81], off
	global_load_dwordx4 v[18:21], v[82:83], off
	global_load_dwordx4 v[22:25], v[84:85], off
	global_load_dwordx4 v[26:29], v[86:87], off
	global_load_dwordx4 v[30:33], v[88:89], off
	global_load_dwordx4 v[102:105], v[74:75], off offset:128
	global_load_dwordx4 v[106:109], v[76:77], off offset:128
	global_load_dwordx4 v[110:113], v[78:79], off offset:128
	global_load_dwordx4 v[114:117], v[80:81], off offset:128
	global_load_dwordx4 v[118:121], v[82:83], off offset:128
	global_load_dwordx4 v[122:125], v[84:85], off offset:128
	global_load_dwordx4 v[126:129], v[86:87], off offset:128
	global_load_dwordx4 v[136:139], v[88:89], off offset:128
	s_waitcnt vmcnt(15)
	ds_write_b128 v98, v[2:5]
	s_waitcnt vmcnt(14)
	ds_write_b128 v98, v[6:9] offset:4608
	s_waitcnt vmcnt(13)
	ds_write_b128 v98, v[10:13] offset:9216
	s_waitcnt vmcnt(12)
	ds_write_b128 v98, v[14:17] offset:13824
	s_waitcnt vmcnt(11)
	ds_write_b128 v98, v[18:21] offset:36864
	s_waitcnt vmcnt(10)
	ds_write_b128 v98, v[22:25] offset:41472
	s_waitcnt vmcnt(9)
	ds_write_b128 v98, v[26:29] offset:46080
	s_waitcnt vmcnt(8)
	ds_write_b128 v98, v[30:33] offset:50688
	s_waitcnt lgkmcnt(0)
	s_barrier
	global_load_dwordx4 v[140:143], v[74:75], off offset:256
	global_load_dwordx4 v[144:147], v[76:77], off offset:256
	global_load_dwordx4 v[148:151], v[78:79], off offset:256
	global_load_dwordx4 v[152:155], v[80:81], off offset:256
	global_load_dwordx4 v[156:159], v[82:83], off offset:256
	global_load_dwordx4 v[160:163], v[84:85], off offset:256
	global_load_dwordx4 v[164:167], v[86:87], off offset:256
	global_load_dwordx4 v[168:171], v[88:89], off offset:256
	v_and_b32_e32 v246, 15, v1
	v_add_u32_e32 v246, 4, v246
	v_bfe_u32 v246, v246, 3, 1
	v_bfe_u32 v249, v1, 4, 2
	v_xor_b32_e32 v246, v246, v249
	v_bfe_u32 v249, v1, 5, 1
	v_sub_u32_e32 v246, v246, v249
	v_lshlrev_b32_e32 v246, 4, v246
	v_bfe_u32 v249, v1, 4, 1
	v_mul_u32_u24_e32 v249, 0x900, v249
	v_sub_u32_e32 v246, v246, v249
	v_add_u32_e32 v244, v246, v96
	v_add_u32_e32 v245, v246, v97
	ds_read_b128 v[212:215], v245 offset:36864
	ds_read_b128 v[196:199], v244
	ds_read_b128 v[216:219], v245 offset:39168
	ds_read_b128 v[220:223], v245 offset:41472
	ds_read_b128 v[224:227], v245 offset:43776
	ds_read_b128 v[200:203], v244 offset:2304
	ds_read_b128 v[204:207], v244 offset:4608
	ds_read_b128 v[208:211], v244 offset:6912
	s_waitcnt lgkmcnt(6)
	v_mfma_f32_16x16x32_bf16 v[50:53], v[196:199], v[212:215], 0
	ds_read_b128 v[228:231], v245 offset:36928
	s_waitcnt lgkmcnt(6)
	v_mfma_f32_16x16x32_bf16 v[54:57], v[196:199], v[216:219], 0
	ds_read_b128 v[232:235], v245 offset:39232
	s_waitcnt lgkmcnt(6)
	v_mfma_f32_16x16x32_bf16 v[18:21], v[196:199], v[220:223], 0
	ds_read_b128 v[236:239], v245 offset:41536
	s_waitcnt lgkmcnt(6)
	v_mfma_f32_16x16x32_bf16 v[22:25], v[196:199], v[224:227], 0
	ds_read_b128 v[240:243], v245 offset:43840
	ds_read_b128 v[196:199], v244 offset:64
	s_waitcnt lgkmcnt(7)
	v_mfma_f32_16x16x32_bf16 v[58:61], v[200:203], v[212:215], 0
	v_mfma_f32_16x16x32_bf16 v[62:65], v[200:203], v[216:219], 0
	v_mfma_f32_16x16x32_bf16 v[26:29], v[200:203], v[220:223], 0
	v_mfma_f32_16x16x32_bf16 v[30:33], v[200:203], v[224:227], 0
	ds_read_b128 v[200:203], v244 offset:2368
	s_waitcnt lgkmcnt(7)
	v_mfma_f32_16x16x32_bf16 v[34:37], v[204:207], v[212:215], 0
	v_mfma_f32_16x16x32_bf16 v[38:41], v[204:207], v[216:219], 0
	v_mfma_f32_16x16x32_bf16 v[2:5], v[204:207], v[220:223], 0
	v_mfma_f32_16x16x32_bf16 v[6:9], v[204:207], v[224:227], 0
	ds_read_b128 v[204:207], v244 offset:4672
	s_waitcnt vmcnt(15)
	ds_write_b128 v98, v[102:105] offset:18432
	s_waitcnt vmcnt(14)
	ds_write_b128 v98, v[106:109] offset:23040
	s_waitcnt lgkmcnt(9)
	v_mfma_f32_16x16x32_bf16 v[42:45], v[208:211], v[212:215], 0
	v_mfma_f32_16x16x32_bf16 v[46:49], v[208:211], v[216:219], 0
	v_mfma_f32_16x16x32_bf16 v[10:13], v[208:211], v[220:223], 0
	v_mfma_f32_16x16x32_bf16 v[14:17], v[208:211], v[224:227], 0
	ds_read_b128 v[208:211], v244 offset:6976
	s_waitcnt vmcnt(13)
	ds_write_b128 v98, v[110:113] offset:27648
	s_waitcnt vmcnt(12)
	ds_write_b128 v98, v[114:117] offset:32256
	s_waitcnt lgkmcnt(7)
	v_mfma_f32_16x16x32_bf16 v[50:53], v[196:199], v[228:231], v[50:53]
	v_mfma_f32_16x16x32_bf16 v[54:57], v[196:199], v[232:235], v[54:57]
	v_mfma_f32_16x16x32_bf16 v[18:21], v[196:199], v[236:239], v[18:21]
	v_mfma_f32_16x16x32_bf16 v[22:25], v[196:199], v[240:243], v[22:25]
	s_waitcnt vmcnt(11)
	ds_write_b128 v98, v[118:121] offset:55296
	s_waitcnt vmcnt(10)
	ds_write_b128 v98, v[122:125] offset:59904
	s_waitcnt lgkmcnt(8)
	v_mfma_f32_16x16x32_bf16 v[58:61], v[200:203], v[228:231], v[58:61]
	v_mfma_f32_16x16x32_bf16 v[62:65], v[200:203], v[232:235], v[62:65]
	v_mfma_f32_16x16x32_bf16 v[26:29], v[200:203], v[236:239], v[26:29]
	v_mfma_f32_16x16x32_bf16 v[30:33], v[200:203], v[240:243], v[30:33]
	s_waitcnt vmcnt(9)
	ds_write_b128 v98, v[126:129] offset:64512
	s_waitcnt vmcnt(8)
	ds_write_b128 v99, v[136:139] offset:32256
	s_waitcnt lgkmcnt(9)
	v_mfma_f32_16x16x32_bf16 v[34:37], v[204:207], v[228:231], v[34:37]
	v_mfma_f32_16x16x32_bf16 v[38:41], v[204:207], v[232:235], v[38:41]
	v_mfma_f32_16x16x32_bf16 v[2:5], v[204:207], v[236:239], v[2:5]
	v_mfma_f32_16x16x32_bf16 v[6:9], v[204:207], v[240:243], v[6:9]
	s_waitcnt lgkmcnt(6)
	v_mfma_f32_16x16x32_bf16 v[42:45], v[208:211], v[228:231], v[42:45]
	v_mfma_f32_16x16x32_bf16 v[46:49], v[208:211], v[232:235], v[46:49]
	v_mfma_f32_16x16x32_bf16 v[10:13], v[208:211], v[236:239], v[10:13]
	v_mfma_f32_16x16x32_bf16 v[14:17], v[208:211], v[240:243], v[14:17]
	s_waitcnt lgkmcnt(0)
	s_barrier
	global_load_dwordx4 v[102:105], v[74:75], off offset:384
	global_load_dwordx4 v[106:109], v[76:77], off offset:384
	global_load_dwordx4 v[110:113], v[78:79], off offset:384
	global_load_dwordx4 v[114:117], v[80:81], off offset:384
	global_load_dwordx4 v[118:121], v[82:83], off offset:384
	global_load_dwordx4 v[122:125], v[84:85], off offset:384
	global_load_dwordx4 v[126:129], v[86:87], off offset:384
	global_load_dwordx4 v[136:139], v[88:89], off offset:384
	ds_read_b128 v[212:215], v245 offset:55296
	ds_read_b128 v[196:199], v244 offset:18432
	ds_read_b128 v[216:219], v245 offset:57600
	ds_read_b128 v[220:223], v245 offset:59904
	ds_read_b128 v[224:227], v245 offset:62208
	ds_read_b128 v[200:203], v244 offset:20736
	ds_read_b128 v[204:207], v244 offset:23040
	ds_read_b128 v[208:211], v244 offset:25344
	s_waitcnt lgkmcnt(6)
	v_mfma_f32_16x16x32_bf16 v[50:53], v[196:199], v[212:215], v[50:53]
	ds_read_b128 v[228:231], v245 offset:55360
	s_waitcnt lgkmcnt(6)
	v_mfma_f32_16x16x32_bf16 v[54:57], v[196:199], v[216:219], v[54:57]
	ds_read_b128 v[232:235], v245 offset:57664
	s_waitcnt lgkmcnt(6)
	v_mfma_f32_16x16x32_bf16 v[18:21], v[196:199], v[220:223], v[18:21]
	ds_read_b128 v[236:239], v245 offset:59968
	s_waitcnt lgkmcnt(6)
	v_mfma_f32_16x16x32_bf16 v[22:25], v[196:199], v[224:227], v[22:25]
	ds_read_b128 v[240:243], v245 offset:62272
	ds_read_b128 v[196:199], v244 offset:18496
	s_waitcnt lgkmcnt(7)
	v_mfma_f32_16x16x32_bf16 v[58:61], v[200:203], v[212:215], v[58:61]
	v_mfma_f32_16x16x32_bf16 v[62:65], v[200:203], v[216:219], v[62:65]
	v_mfma_f32_16x16x32_bf16 v[26:29], v[200:203], v[220:223], v[26:29]
	v_mfma_f32_16x16x32_bf16 v[30:33], v[200:203], v[224:227], v[30:33]
	ds_read_b128 v[200:203], v244 offset:20800
	s_waitcnt lgkmcnt(7)
	v_mfma_f32_16x16x32_bf16 v[34:37], v[204:207], v[212:215], v[34:37]
	v_mfma_f32_16x16x32_bf16 v[38:41], v[204:207], v[216:219], v[38:41]
	v_mfma_f32_16x16x32_bf16 v[2:5], v[204:207], v[220:223], v[2:5]
	v_mfma_f32_16x16x32_bf16 v[6:9], v[204:207], v[224:227], v[6:9]
	ds_read_b128 v[204:207], v244 offset:23104
	s_waitcnt vmcnt(15)
	ds_write_b128 v98, v[140:143]
	s_waitcnt vmcnt(14)
	ds_write_b128 v98, v[144:147] offset:4608
	s_waitcnt lgkmcnt(9)
	v_mfma_f32_16x16x32_bf16 v[42:45], v[208:211], v[212:215], v[42:45]
	v_mfma_f32_16x16x32_bf16 v[46:49], v[208:211], v[216:219], v[46:49]
	v_mfma_f32_16x16x32_bf16 v[10:13], v[208:211], v[220:223], v[10:13]
	v_mfma_f32_16x16x32_bf16 v[14:17], v[208:211], v[224:227], v[14:17]
	ds_read_b128 v[208:211], v244 offset:25408
	s_waitcnt vmcnt(13)
	ds_write_b128 v98, v[148:151] offset:9216
	s_waitcnt vmcnt(12)
	ds_write_b128 v98, v[152:155] offset:13824
	s_waitcnt lgkmcnt(7)
	v_mfma_f32_16x16x32_bf16 v[50:53], v[196:199], v[228:231], v[50:53]
	v_mfma_f32_16x16x32_bf16 v[54:57], v[196:199], v[232:235], v[54:57]
	v_mfma_f32_16x16x32_bf16 v[18:21], v[196:199], v[236:239], v[18:21]
	v_mfma_f32_16x16x32_bf16 v[22:25], v[196:199], v[240:243], v[22:25]
	s_waitcnt vmcnt(11)
	ds_write_b128 v98, v[156:159] offset:36864
	s_waitcnt vmcnt(10)
	ds_write_b128 v98, v[160:163] offset:41472
	s_waitcnt lgkmcnt(8)
	v_mfma_f32_16x16x32_bf16 v[58:61], v[200:203], v[228:231], v[58:61]
	v_mfma_f32_16x16x32_bf16 v[62:65], v[200:203], v[232:235], v[62:65]
	v_mfma_f32_16x16x32_bf16 v[26:29], v[200:203], v[236:239], v[26:29]
	v_mfma_f32_16x16x32_bf16 v[30:33], v[200:203], v[240:243], v[30:33]
	s_waitcnt vmcnt(9)
	ds_write_b128 v98, v[164:167] offset:46080
	s_waitcnt vmcnt(8)
	ds_write_b128 v98, v[168:171] offset:50688
	s_waitcnt lgkmcnt(9)
	v_mfma_f32_16x16x32_bf16 v[34:37], v[204:207], v[228:231], v[34:37]
	v_mfma_f32_16x16x32_bf16 v[38:41], v[204:207], v[232:235], v[38:41]
	v_mfma_f32_16x16x32_bf16 v[2:5], v[204:207], v[236:239], v[2:5]
	v_mfma_f32_16x16x32_bf16 v[6:9], v[204:207], v[240:243], v[6:9]
	s_waitcnt lgkmcnt(6)
	v_mfma_f32_16x16x32_bf16 v[42:45], v[208:211], v[228:231], v[42:45]
	v_mfma_f32_16x16x32_bf16 v[46:49], v[208:211], v[232:235], v[46:49]
	v_mfma_f32_16x16x32_bf16 v[10:13], v[208:211], v[236:239], v[10:13]
	v_mfma_f32_16x16x32_bf16 v[14:17], v[208:211], v[240:243], v[14:17]
	s_waitcnt lgkmcnt(0)
	s_barrier
	global_load_dwordx4 v[140:143], v[74:75], off offset:512
	global_load_dwordx4 v[144:147], v[76:77], off offset:512
	global_load_dwordx4 v[148:151], v[78:79], off offset:512
	global_load_dwordx4 v[152:155], v[80:81], off offset:512
	global_load_dwordx4 v[156:159], v[82:83], off offset:512
	global_load_dwordx4 v[160:163], v[84:85], off offset:512
	global_load_dwordx4 v[164:167], v[86:87], off offset:512
	global_load_dwordx4 v[168:171], v[88:89], off offset:512
	ds_read_b128 v[212:215], v245 offset:36864
	ds_read_b128 v[196:199], v244
	ds_read_b128 v[216:219], v245 offset:39168
	ds_read_b128 v[220:223], v245 offset:41472
	ds_read_b128 v[224:227], v245 offset:43776
	ds_read_b128 v[200:203], v244 offset:2304
	ds_read_b128 v[204:207], v244 offset:4608
	ds_read_b128 v[208:211], v244 offset:6912
	s_waitcnt lgkmcnt(6)
	v_mfma_f32_16x16x32_bf16 v[50:53], v[196:199], v[212:215], v[50:53]
	ds_read_b128 v[228:231], v245 offset:36928
	s_waitcnt lgkmcnt(6)
	v_mfma_f32_16x16x32_bf16 v[54:57], v[196:199], v[216:219], v[54:57]
	ds_read_b128 v[232:235], v245 offset:39232
	s_waitcnt lgkmcnt(6)
	v_mfma_f32_16x16x32_bf16 v[18:21], v[196:199], v[220:223], v[18:21]
	ds_read_b128 v[236:239], v245 offset:41536
	s_waitcnt lgkmcnt(6)
	v_mfma_f32_16x16x32_bf16 v[22:25], v[196:199], v[224:227], v[22:25]
	ds_read_b128 v[240:243], v245 offset:43840
	ds_read_b128 v[196:199], v244 offset:64
	s_waitcnt lgkmcnt(7)
	v_mfma_f32_16x16x32_bf16 v[58:61], v[200:203], v[212:215], v[58:61]
	v_mfma_f32_16x16x32_bf16 v[62:65], v[200:203], v[216:219], v[62:65]
	v_mfma_f32_16x16x32_bf16 v[26:29], v[200:203], v[220:223], v[26:29]
	v_mfma_f32_16x16x32_bf16 v[30:33], v[200:203], v[224:227], v[30:33]
	ds_read_b128 v[200:203], v244 offset:2368
	s_waitcnt lgkmcnt(7)
	v_mfma_f32_16x16x32_bf16 v[34:37], v[204:207], v[212:215], v[34:37]
	v_mfma_f32_16x16x32_bf16 v[38:41], v[204:207], v[216:219], v[38:41]
	v_mfma_f32_16x16x32_bf16 v[2:5], v[204:207], v[220:223], v[2:5]
	v_mfma_f32_16x16x32_bf16 v[6:9], v[204:207], v[224:227], v[6:9]
	ds_read_b128 v[204:207], v244 offset:4672
	s_waitcnt vmcnt(15)
	ds_write_b128 v98, v[102:105] offset:18432
	s_waitcnt vmcnt(14)
	ds_write_b128 v98, v[106:109] offset:23040
	s_waitcnt lgkmcnt(9)
	v_mfma_f32_16x16x32_bf16 v[42:45], v[208:211], v[212:215], v[42:45]
	v_mfma_f32_16x16x32_bf16 v[46:49], v[208:211], v[216:219], v[46:49]
	v_mfma_f32_16x16x32_bf16 v[10:13], v[208:211], v[220:223], v[10:13]
	v_mfma_f32_16x16x32_bf16 v[14:17], v[208:211], v[224:227], v[14:17]
	ds_read_b128 v[208:211], v244 offset:6976
	s_waitcnt vmcnt(13)
	ds_write_b128 v98, v[110:113] offset:27648
	s_waitcnt vmcnt(12)
	ds_write_b128 v98, v[114:117] offset:32256
	s_waitcnt lgkmcnt(7)
	v_mfma_f32_16x16x32_bf16 v[50:53], v[196:199], v[228:231], v[50:53]
	v_mfma_f32_16x16x32_bf16 v[54:57], v[196:199], v[232:235], v[54:57]
	v_mfma_f32_16x16x32_bf16 v[18:21], v[196:199], v[236:239], v[18:21]
	v_mfma_f32_16x16x32_bf16 v[22:25], v[196:199], v[240:243], v[22:25]
	s_waitcnt vmcnt(11)
	ds_write_b128 v98, v[118:121] offset:55296
	s_waitcnt vmcnt(10)
	ds_write_b128 v98, v[122:125] offset:59904
	s_waitcnt lgkmcnt(8)
	v_mfma_f32_16x16x32_bf16 v[58:61], v[200:203], v[228:231], v[58:61]
	v_mfma_f32_16x16x32_bf16 v[62:65], v[200:203], v[232:235], v[62:65]
	v_mfma_f32_16x16x32_bf16 v[26:29], v[200:203], v[236:239], v[26:29]
	v_mfma_f32_16x16x32_bf16 v[30:33], v[200:203], v[240:243], v[30:33]
	s_waitcnt vmcnt(9)
	ds_write_b128 v98, v[126:129] offset:64512
	s_waitcnt vmcnt(8)
	ds_write_b128 v99, v[136:139] offset:32256
	s_waitcnt lgkmcnt(9)
	v_mfma_f32_16x16x32_bf16 v[34:37], v[204:207], v[228:231], v[34:37]
	v_mfma_f32_16x16x32_bf16 v[38:41], v[204:207], v[232:235], v[38:41]
	v_mfma_f32_16x16x32_bf16 v[2:5], v[204:207], v[236:239], v[2:5]
	v_mfma_f32_16x16x32_bf16 v[6:9], v[204:207], v[240:243], v[6:9]
	s_waitcnt lgkmcnt(6)
	v_mfma_f32_16x16x32_bf16 v[42:45], v[208:211], v[228:231], v[42:45]
	v_mfma_f32_16x16x32_bf16 v[46:49], v[208:211], v[232:235], v[46:49]
	v_mfma_f32_16x16x32_bf16 v[10:13], v[208:211], v[236:239], v[10:13]
	v_mfma_f32_16x16x32_bf16 v[14:17], v[208:211], v[240:243], v[14:17]
	s_waitcnt lgkmcnt(0)
	s_barrier
	global_load_dwordx4 v[102:105], v[74:75], off offset:640
	global_load_dwordx4 v[106:109], v[76:77], off offset:640
	global_load_dwordx4 v[110:113], v[78:79], off offset:640
	global_load_dwordx4 v[114:117], v[80:81], off offset:640
	global_load_dwordx4 v[118:121], v[82:83], off offset:640
	global_load_dwordx4 v[122:125], v[84:85], off offset:640
	global_load_dwordx4 v[126:129], v[86:87], off offset:640
	global_load_dwordx4 v[136:139], v[88:89], off offset:640
	ds_read_b128 v[212:215], v245 offset:55296
	ds_read_b128 v[196:199], v244 offset:18432
	ds_read_b128 v[216:219], v245 offset:57600
	ds_read_b128 v[220:223], v245 offset:59904
	ds_read_b128 v[224:227], v245 offset:62208
	ds_read_b128 v[200:203], v244 offset:20736
	ds_read_b128 v[204:207], v244 offset:23040
	ds_read_b128 v[208:211], v244 offset:25344
	s_waitcnt lgkmcnt(6)
	v_mfma_f32_16x16x32_bf16 v[50:53], v[196:199], v[212:215], v[50:53]
	ds_read_b128 v[228:231], v245 offset:55360
	s_waitcnt lgkmcnt(6)
	v_mfma_f32_16x16x32_bf16 v[54:57], v[196:199], v[216:219], v[54:57]
	ds_read_b128 v[232:235], v245 offset:57664
	s_waitcnt lgkmcnt(6)
	v_mfma_f32_16x16x32_bf16 v[18:21], v[196:199], v[220:223], v[18:21]
	ds_read_b128 v[236:239], v245 offset:59968
	s_waitcnt lgkmcnt(6)
	v_mfma_f32_16x16x32_bf16 v[22:25], v[196:199], v[224:227], v[22:25]
	ds_read_b128 v[240:243], v245 offset:62272
	ds_read_b128 v[196:199], v244 offset:18496
	s_waitcnt lgkmcnt(7)
	v_mfma_f32_16x16x32_bf16 v[58:61], v[200:203], v[212:215], v[58:61]
	v_mfma_f32_16x16x32_bf16 v[62:65], v[200:203], v[216:219], v[62:65]
	v_mfma_f32_16x16x32_bf16 v[26:29], v[200:203], v[220:223], v[26:29]
	v_mfma_f32_16x16x32_bf16 v[30:33], v[200:203], v[224:227], v[30:33]
	ds_read_b128 v[200:203], v244 offset:20800
	s_waitcnt lgkmcnt(7)
	v_mfma_f32_16x16x32_bf16 v[34:37], v[204:207], v[212:215], v[34:37]
	v_mfma_f32_16x16x32_bf16 v[38:41], v[204:207], v[216:219], v[38:41]
	v_mfma_f32_16x16x32_bf16 v[2:5], v[204:207], v[220:223], v[2:5]
	v_mfma_f32_16x16x32_bf16 v[6:9], v[204:207], v[224:227], v[6:9]
	ds_read_b128 v[204:207], v244 offset:23104
	s_waitcnt vmcnt(15)
	ds_write_b128 v98, v[140:143]
	s_waitcnt vmcnt(14)
	ds_write_b128 v98, v[144:147] offset:4608
	s_waitcnt lgkmcnt(9)
	v_mfma_f32_16x16x32_bf16 v[42:45], v[208:211], v[212:215], v[42:45]
	v_mfma_f32_16x16x32_bf16 v[46:49], v[208:211], v[216:219], v[46:49]
	v_mfma_f32_16x16x32_bf16 v[10:13], v[208:211], v[220:223], v[10:13]
	v_mfma_f32_16x16x32_bf16 v[14:17], v[208:211], v[224:227], v[14:17]
	ds_read_b128 v[208:211], v244 offset:25408
	s_waitcnt vmcnt(13)
	ds_write_b128 v98, v[148:151] offset:9216
	s_waitcnt vmcnt(12)
	ds_write_b128 v98, v[152:155] offset:13824
	s_waitcnt lgkmcnt(7)
	v_mfma_f32_16x16x32_bf16 v[50:53], v[196:199], v[228:231], v[50:53]
	v_mfma_f32_16x16x32_bf16 v[54:57], v[196:199], v[232:235], v[54:57]
	v_mfma_f32_16x16x32_bf16 v[18:21], v[196:199], v[236:239], v[18:21]
	v_mfma_f32_16x16x32_bf16 v[22:25], v[196:199], v[240:243], v[22:25]
	s_waitcnt vmcnt(11)
	ds_write_b128 v98, v[156:159] offset:36864
	s_waitcnt vmcnt(10)
	ds_write_b128 v98, v[160:163] offset:41472
	s_waitcnt lgkmcnt(8)
	v_mfma_f32_16x16x32_bf16 v[58:61], v[200:203], v[228:231], v[58:61]
	v_mfma_f32_16x16x32_bf16 v[62:65], v[200:203], v[232:235], v[62:65]
	v_mfma_f32_16x16x32_bf16 v[26:29], v[200:203], v[236:239], v[26:29]
	v_mfma_f32_16x16x32_bf16 v[30:33], v[200:203], v[240:243], v[30:33]
	s_waitcnt vmcnt(9)
	ds_write_b128 v98, v[164:167] offset:46080
	s_waitcnt vmcnt(8)
	ds_write_b128 v98, v[168:171] offset:50688
	s_waitcnt lgkmcnt(9)
	v_mfma_f32_16x16x32_bf16 v[34:37], v[204:207], v[228:231], v[34:37]
	v_mfma_f32_16x16x32_bf16 v[38:41], v[204:207], v[232:235], v[38:41]
	v_mfma_f32_16x16x32_bf16 v[2:5], v[204:207], v[236:239], v[2:5]
	v_mfma_f32_16x16x32_bf16 v[6:9], v[204:207], v[240:243], v[6:9]
	s_waitcnt lgkmcnt(6)
	v_mfma_f32_16x16x32_bf16 v[42:45], v[208:211], v[228:231], v[42:45]
	v_mfma_f32_16x16x32_bf16 v[46:49], v[208:211], v[232:235], v[46:49]
	v_mfma_f32_16x16x32_bf16 v[10:13], v[208:211], v[236:239], v[10:13]
	v_mfma_f32_16x16x32_bf16 v[14:17], v[208:211], v[240:243], v[14:17]
	s_waitcnt lgkmcnt(0)
	s_barrier
	global_load_dwordx4 v[140:143], v[74:75], off offset:768
	global_load_dwordx4 v[144:147], v[76:77], off offset:768
	global_load_dwordx4 v[148:151], v[78:79], off offset:768
	global_load_dwordx4 v[152:155], v[80:81], off offset:768
	global_load_dwordx4 v[156:159], v[82:83], off offset:768
	global_load_dwordx4 v[160:163], v[84:85], off offset:768
	global_load_dwordx4 v[164:167], v[86:87], off offset:768
	global_load_dwordx4 v[168:171], v[88:89], off offset:768
	ds_read_b128 v[212:215], v245 offset:36864
	ds_read_b128 v[196:199], v244
	ds_read_b128 v[216:219], v245 offset:39168
	ds_read_b128 v[220:223], v245 offset:41472
	ds_read_b128 v[224:227], v245 offset:43776
	ds_read_b128 v[200:203], v244 offset:2304
	ds_read_b128 v[204:207], v244 offset:4608
	ds_read_b128 v[208:211], v244 offset:6912
	s_waitcnt lgkmcnt(6)
	v_mfma_f32_16x16x32_bf16 v[50:53], v[196:199], v[212:215], v[50:53]
	ds_read_b128 v[228:231], v245 offset:36928
	s_waitcnt lgkmcnt(6)
	v_mfma_f32_16x16x32_bf16 v[54:57], v[196:199], v[216:219], v[54:57]
	ds_read_b128 v[232:235], v245 offset:39232
	s_waitcnt lgkmcnt(6)
	v_mfma_f32_16x16x32_bf16 v[18:21], v[196:199], v[220:223], v[18:21]
	ds_read_b128 v[236:239], v245 offset:41536
	s_waitcnt lgkmcnt(6)
	v_mfma_f32_16x16x32_bf16 v[22:25], v[196:199], v[224:227], v[22:25]
	ds_read_b128 v[240:243], v245 offset:43840
	ds_read_b128 v[196:199], v244 offset:64
	s_waitcnt lgkmcnt(7)
	v_mfma_f32_16x16x32_bf16 v[58:61], v[200:203], v[212:215], v[58:61]
	v_mfma_f32_16x16x32_bf16 v[62:65], v[200:203], v[216:219], v[62:65]
	v_mfma_f32_16x16x32_bf16 v[26:29], v[200:203], v[220:223], v[26:29]
	v_mfma_f32_16x16x32_bf16 v[30:33], v[200:203], v[224:227], v[30:33]
	ds_read_b128 v[200:203], v244 offset:2368
	s_waitcnt lgkmcnt(7)
	v_mfma_f32_16x16x32_bf16 v[34:37], v[204:207], v[212:215], v[34:37]
	v_mfma_f32_16x16x32_bf16 v[38:41], v[204:207], v[216:219], v[38:41]
	v_mfma_f32_16x16x32_bf16 v[2:5], v[204:207], v[220:223], v[2:5]
	v_mfma_f32_16x16x32_bf16 v[6:9], v[204:207], v[224:227], v[6:9]
	ds_read_b128 v[204:207], v244 offset:4672
	s_waitcnt vmcnt(15)
	ds_write_b128 v98, v[102:105] offset:18432
	s_waitcnt vmcnt(14)
	ds_write_b128 v98, v[106:109] offset:23040
	s_waitcnt lgkmcnt(9)
	v_mfma_f32_16x16x32_bf16 v[42:45], v[208:211], v[212:215], v[42:45]
	v_mfma_f32_16x16x32_bf16 v[46:49], v[208:211], v[216:219], v[46:49]
	v_mfma_f32_16x16x32_bf16 v[10:13], v[208:211], v[220:223], v[10:13]
	v_mfma_f32_16x16x32_bf16 v[14:17], v[208:211], v[224:227], v[14:17]
	ds_read_b128 v[208:211], v244 offset:6976
	s_waitcnt vmcnt(13)
	ds_write_b128 v98, v[110:113] offset:27648
	s_waitcnt vmcnt(12)
	ds_write_b128 v98, v[114:117] offset:32256
	s_waitcnt lgkmcnt(7)
	v_mfma_f32_16x16x32_bf16 v[50:53], v[196:199], v[228:231], v[50:53]
	v_mfma_f32_16x16x32_bf16 v[54:57], v[196:199], v[232:235], v[54:57]
	v_mfma_f32_16x16x32_bf16 v[18:21], v[196:199], v[236:239], v[18:21]
	v_mfma_f32_16x16x32_bf16 v[22:25], v[196:199], v[240:243], v[22:25]
	s_waitcnt vmcnt(11)
	ds_write_b128 v98, v[118:121] offset:55296
	s_waitcnt vmcnt(10)
	ds_write_b128 v98, v[122:125] offset:59904
	s_waitcnt lgkmcnt(8)
	v_mfma_f32_16x16x32_bf16 v[58:61], v[200:203], v[228:231], v[58:61]
	v_mfma_f32_16x16x32_bf16 v[62:65], v[200:203], v[232:235], v[62:65]
	v_mfma_f32_16x16x32_bf16 v[26:29], v[200:203], v[236:239], v[26:29]
	v_mfma_f32_16x16x32_bf16 v[30:33], v[200:203], v[240:243], v[30:33]
	s_waitcnt vmcnt(9)
	ds_write_b128 v98, v[126:129] offset:64512
	s_waitcnt vmcnt(8)
	ds_write_b128 v99, v[136:139] offset:32256
	s_waitcnt lgkmcnt(9)
	v_mfma_f32_16x16x32_bf16 v[34:37], v[204:207], v[228:231], v[34:37]
	v_mfma_f32_16x16x32_bf16 v[38:41], v[204:207], v[232:235], v[38:41]
	v_mfma_f32_16x16x32_bf16 v[2:5], v[204:207], v[236:239], v[2:5]
	v_mfma_f32_16x16x32_bf16 v[6:9], v[204:207], v[240:243], v[6:9]
	s_waitcnt lgkmcnt(6)
	v_mfma_f32_16x16x32_bf16 v[42:45], v[208:211], v[228:231], v[42:45]
	v_mfma_f32_16x16x32_bf16 v[46:49], v[208:211], v[232:235], v[46:49]
	v_mfma_f32_16x16x32_bf16 v[10:13], v[208:211], v[236:239], v[10:13]
	v_mfma_f32_16x16x32_bf16 v[14:17], v[208:211], v[240:243], v[14:17]
	s_waitcnt lgkmcnt(0)
	s_barrier
	global_load_dwordx4 v[102:105], v[74:75], off offset:896
	global_load_dwordx4 v[106:109], v[76:77], off offset:896
	global_load_dwordx4 v[110:113], v[78:79], off offset:896
	global_load_dwordx4 v[114:117], v[80:81], off offset:896
	global_load_dwordx4 v[118:121], v[82:83], off offset:896
	global_load_dwordx4 v[122:125], v[84:85], off offset:896
	global_load_dwordx4 v[126:129], v[86:87], off offset:896
	global_load_dwordx4 v[136:139], v[88:89], off offset:896
	ds_read_b128 v[212:215], v245 offset:55296
	ds_read_b128 v[196:199], v244 offset:18432
	ds_read_b128 v[216:219], v245 offset:57600
	ds_read_b128 v[220:223], v245 offset:59904
	ds_read_b128 v[224:227], v245 offset:62208
	ds_read_b128 v[200:203], v244 offset:20736
	ds_read_b128 v[204:207], v244 offset:23040
	ds_read_b128 v[208:211], v244 offset:25344
	s_waitcnt lgkmcnt(6)
	v_mfma_f32_16x16x32_bf16 v[50:53], v[196:199], v[212:215], v[50:53]
	ds_read_b128 v[228:231], v245 offset:55360
	s_waitcnt lgkmcnt(6)
	v_mfma_f32_16x16x32_bf16 v[54:57], v[196:199], v[216:219], v[54:57]
	ds_read_b128 v[232:235], v245 offset:57664
	s_waitcnt lgkmcnt(6)
	v_mfma_f32_16x16x32_bf16 v[18:21], v[196:199], v[220:223], v[18:21]
	ds_read_b128 v[236:239], v245 offset:59968
	s_waitcnt lgkmcnt(6)
	v_mfma_f32_16x16x32_bf16 v[22:25], v[196:199], v[224:227], v[22:25]
	ds_read_b128 v[240:243], v245 offset:62272
	ds_read_b128 v[196:199], v244 offset:18496
	s_waitcnt lgkmcnt(7)
	v_mfma_f32_16x16x32_bf16 v[58:61], v[200:203], v[212:215], v[58:61]
	v_mfma_f32_16x16x32_bf16 v[62:65], v[200:203], v[216:219], v[62:65]
	v_mfma_f32_16x16x32_bf16 v[26:29], v[200:203], v[220:223], v[26:29]
	v_mfma_f32_16x16x32_bf16 v[30:33], v[200:203], v[224:227], v[30:33]
	ds_read_b128 v[200:203], v244 offset:20800
	s_waitcnt lgkmcnt(7)
	v_mfma_f32_16x16x32_bf16 v[34:37], v[204:207], v[212:215], v[34:37]
	v_mfma_f32_16x16x32_bf16 v[38:41], v[204:207], v[216:219], v[38:41]
	v_mfma_f32_16x16x32_bf16 v[2:5], v[204:207], v[220:223], v[2:5]
	v_mfma_f32_16x16x32_bf16 v[6:9], v[204:207], v[224:227], v[6:9]
	ds_read_b128 v[204:207], v244 offset:23104
	s_waitcnt vmcnt(15)
	ds_write_b128 v98, v[140:143]
	s_waitcnt vmcnt(14)
	ds_write_b128 v98, v[144:147] offset:4608
	s_waitcnt lgkmcnt(9)
	v_mfma_f32_16x16x32_bf16 v[42:45], v[208:211], v[212:215], v[42:45]
	v_mfma_f32_16x16x32_bf16 v[46:49], v[208:211], v[216:219], v[46:49]
	v_mfma_f32_16x16x32_bf16 v[10:13], v[208:211], v[220:223], v[10:13]
	v_mfma_f32_16x16x32_bf16 v[14:17], v[208:211], v[224:227], v[14:17]
	ds_read_b128 v[208:211], v244 offset:25408
	s_waitcnt vmcnt(13)
	ds_write_b128 v98, v[148:151] offset:9216
	s_waitcnt vmcnt(12)
	ds_write_b128 v98, v[152:155] offset:13824
	s_waitcnt lgkmcnt(7)
	v_mfma_f32_16x16x32_bf16 v[50:53], v[196:199], v[228:231], v[50:53]
	v_mfma_f32_16x16x32_bf16 v[54:57], v[196:199], v[232:235], v[54:57]
	v_mfma_f32_16x16x32_bf16 v[18:21], v[196:199], v[236:239], v[18:21]
	v_mfma_f32_16x16x32_bf16 v[22:25], v[196:199], v[240:243], v[22:25]
	s_waitcnt vmcnt(11)
	ds_write_b128 v98, v[156:159] offset:36864
	s_waitcnt vmcnt(10)
	ds_write_b128 v98, v[160:163] offset:41472
	s_waitcnt lgkmcnt(8)
	v_mfma_f32_16x16x32_bf16 v[58:61], v[200:203], v[228:231], v[58:61]
	v_mfma_f32_16x16x32_bf16 v[62:65], v[200:203], v[232:235], v[62:65]
	v_mfma_f32_16x16x32_bf16 v[26:29], v[200:203], v[236:239], v[26:29]
	v_mfma_f32_16x16x32_bf16 v[30:33], v[200:203], v[240:243], v[30:33]
	s_waitcnt vmcnt(9)
	ds_write_b128 v98, v[164:167] offset:46080
	s_waitcnt vmcnt(8)
	ds_write_b128 v98, v[168:171] offset:50688
	s_waitcnt lgkmcnt(9)
	v_mfma_f32_16x16x32_bf16 v[34:37], v[204:207], v[228:231], v[34:37]
	v_mfma_f32_16x16x32_bf16 v[38:41], v[204:207], v[232:235], v[38:41]
	v_mfma_f32_16x16x32_bf16 v[2:5], v[204:207], v[236:239], v[2:5]
	v_mfma_f32_16x16x32_bf16 v[6:9], v[204:207], v[240:243], v[6:9]
	s_waitcnt lgkmcnt(6)
	v_mfma_f32_16x16x32_bf16 v[42:45], v[208:211], v[228:231], v[42:45]
	v_mfma_f32_16x16x32_bf16 v[46:49], v[208:211], v[232:235], v[46:49]
	v_mfma_f32_16x16x32_bf16 v[10:13], v[208:211], v[236:239], v[10:13]
	v_mfma_f32_16x16x32_bf16 v[14:17], v[208:211], v[240:243], v[14:17]
	s_waitcnt lgkmcnt(0)
	s_barrier
	global_load_dwordx4 v[140:143], v[74:75], off offset:1024
	global_load_dwordx4 v[144:147], v[76:77], off offset:1024
	global_load_dwordx4 v[148:151], v[78:79], off offset:1024
	global_load_dwordx4 v[152:155], v[80:81], off offset:1024
	global_load_dwordx4 v[156:159], v[82:83], off offset:1024
	global_load_dwordx4 v[160:163], v[84:85], off offset:1024
	global_load_dwordx4 v[164:167], v[86:87], off offset:1024
	global_load_dwordx4 v[168:171], v[88:89], off offset:1024
	ds_read_b128 v[212:215], v245 offset:36864
	ds_read_b128 v[196:199], v244
	ds_read_b128 v[216:219], v245 offset:39168
	ds_read_b128 v[220:223], v245 offset:41472
	ds_read_b128 v[224:227], v245 offset:43776
	ds_read_b128 v[200:203], v244 offset:2304
	ds_read_b128 v[204:207], v244 offset:4608
	ds_read_b128 v[208:211], v244 offset:6912
	s_waitcnt lgkmcnt(6)
	v_mfma_f32_16x16x32_bf16 v[50:53], v[196:199], v[212:215], v[50:53]
	ds_read_b128 v[228:231], v245 offset:36928
	s_waitcnt lgkmcnt(6)
	v_mfma_f32_16x16x32_bf16 v[54:57], v[196:199], v[216:219], v[54:57]
	ds_read_b128 v[232:235], v245 offset:39232
	s_waitcnt lgkmcnt(6)
	v_mfma_f32_16x16x32_bf16 v[18:21], v[196:199], v[220:223], v[18:21]
	ds_read_b128 v[236:239], v245 offset:41536
	s_waitcnt lgkmcnt(6)
	v_mfma_f32_16x16x32_bf16 v[22:25], v[196:199], v[224:227], v[22:25]
	ds_read_b128 v[240:243], v245 offset:43840
	ds_read_b128 v[196:199], v244 offset:64
	s_waitcnt lgkmcnt(7)
	v_mfma_f32_16x16x32_bf16 v[58:61], v[200:203], v[212:215], v[58:61]
	v_mfma_f32_16x16x32_bf16 v[62:65], v[200:203], v[216:219], v[62:65]
	v_mfma_f32_16x16x32_bf16 v[26:29], v[200:203], v[220:223], v[26:29]
	v_mfma_f32_16x16x32_bf16 v[30:33], v[200:203], v[224:227], v[30:33]
	ds_read_b128 v[200:203], v244 offset:2368
	s_waitcnt lgkmcnt(7)
	v_mfma_f32_16x16x32_bf16 v[34:37], v[204:207], v[212:215], v[34:37]
	v_mfma_f32_16x16x32_bf16 v[38:41], v[204:207], v[216:219], v[38:41]
	v_mfma_f32_16x16x32_bf16 v[2:5], v[204:207], v[220:223], v[2:5]
	v_mfma_f32_16x16x32_bf16 v[6:9], v[204:207], v[224:227], v[6:9]
	ds_read_b128 v[204:207], v244 offset:4672
	s_waitcnt vmcnt(15)
	ds_write_b128 v98, v[102:105] offset:18432
	s_waitcnt vmcnt(14)
	ds_write_b128 v98, v[106:109] offset:23040
	s_waitcnt lgkmcnt(9)
	v_mfma_f32_16x16x32_bf16 v[42:45], v[208:211], v[212:215], v[42:45]
	v_mfma_f32_16x16x32_bf16 v[46:49], v[208:211], v[216:219], v[46:49]
	v_mfma_f32_16x16x32_bf16 v[10:13], v[208:211], v[220:223], v[10:13]
	v_mfma_f32_16x16x32_bf16 v[14:17], v[208:211], v[224:227], v[14:17]
	ds_read_b128 v[208:211], v244 offset:6976
	s_waitcnt vmcnt(13)
	ds_write_b128 v98, v[110:113] offset:27648
	s_waitcnt vmcnt(12)
	ds_write_b128 v98, v[114:117] offset:32256
	s_waitcnt lgkmcnt(7)
	v_mfma_f32_16x16x32_bf16 v[50:53], v[196:199], v[228:231], v[50:53]
	v_mfma_f32_16x16x32_bf16 v[54:57], v[196:199], v[232:235], v[54:57]
	v_mfma_f32_16x16x32_bf16 v[18:21], v[196:199], v[236:239], v[18:21]
	v_mfma_f32_16x16x32_bf16 v[22:25], v[196:199], v[240:243], v[22:25]
	s_waitcnt vmcnt(11)
	ds_write_b128 v98, v[118:121] offset:55296
	s_waitcnt vmcnt(10)
	ds_write_b128 v98, v[122:125] offset:59904
	s_waitcnt lgkmcnt(8)
	v_mfma_f32_16x16x32_bf16 v[58:61], v[200:203], v[228:231], v[58:61]
	v_mfma_f32_16x16x32_bf16 v[62:65], v[200:203], v[232:235], v[62:65]
	v_mfma_f32_16x16x32_bf16 v[26:29], v[200:203], v[236:239], v[26:29]
	v_mfma_f32_16x16x32_bf16 v[30:33], v[200:203], v[240:243], v[30:33]
	s_waitcnt vmcnt(9)
	ds_write_b128 v98, v[126:129] offset:64512
	s_waitcnt vmcnt(8)
	ds_write_b128 v99, v[136:139] offset:32256
	s_waitcnt lgkmcnt(9)
	v_mfma_f32_16x16x32_bf16 v[34:37], v[204:207], v[228:231], v[34:37]
	v_mfma_f32_16x16x32_bf16 v[38:41], v[204:207], v[232:235], v[38:41]
	v_mfma_f32_16x16x32_bf16 v[2:5], v[204:207], v[236:239], v[2:5]
	v_mfma_f32_16x16x32_bf16 v[6:9], v[204:207], v[240:243], v[6:9]
	s_waitcnt lgkmcnt(6)
	v_mfma_f32_16x16x32_bf16 v[42:45], v[208:211], v[228:231], v[42:45]
	v_mfma_f32_16x16x32_bf16 v[46:49], v[208:211], v[232:235], v[46:49]
	v_mfma_f32_16x16x32_bf16 v[10:13], v[208:211], v[236:239], v[10:13]
	v_mfma_f32_16x16x32_bf16 v[14:17], v[208:211], v[240:243], v[14:17]
	s_waitcnt lgkmcnt(0)
	s_barrier
	global_load_dwordx4 v[102:105], v[74:75], off offset:1152
	global_load_dwordx4 v[106:109], v[76:77], off offset:1152
	global_load_dwordx4 v[110:113], v[78:79], off offset:1152
	global_load_dwordx4 v[114:117], v[80:81], off offset:1152
	global_load_dwordx4 v[118:121], v[82:83], off offset:1152
	global_load_dwordx4 v[122:125], v[84:85], off offset:1152
	global_load_dwordx4 v[126:129], v[86:87], off offset:1152
	global_load_dwordx4 v[136:139], v[88:89], off offset:1152
	ds_read_b128 v[212:215], v245 offset:55296
	ds_read_b128 v[196:199], v244 offset:18432
	ds_read_b128 v[216:219], v245 offset:57600
	ds_read_b128 v[220:223], v245 offset:59904
	ds_read_b128 v[224:227], v245 offset:62208
	ds_read_b128 v[200:203], v244 offset:20736
	ds_read_b128 v[204:207], v244 offset:23040
	ds_read_b128 v[208:211], v244 offset:25344
	s_waitcnt lgkmcnt(6)
	v_mfma_f32_16x16x32_bf16 v[50:53], v[196:199], v[212:215], v[50:53]
	ds_read_b128 v[228:231], v245 offset:55360
	s_waitcnt lgkmcnt(6)
	v_mfma_f32_16x16x32_bf16 v[54:57], v[196:199], v[216:219], v[54:57]
	ds_read_b128 v[232:235], v245 offset:57664
	s_waitcnt lgkmcnt(6)
	v_mfma_f32_16x16x32_bf16 v[18:21], v[196:199], v[220:223], v[18:21]
	ds_read_b128 v[236:239], v245 offset:59968
	s_waitcnt lgkmcnt(6)
	v_mfma_f32_16x16x32_bf16 v[22:25], v[196:199], v[224:227], v[22:25]
	ds_read_b128 v[240:243], v245 offset:62272
	ds_read_b128 v[196:199], v244 offset:18496
	s_waitcnt lgkmcnt(7)
	v_mfma_f32_16x16x32_bf16 v[58:61], v[200:203], v[212:215], v[58:61]
	v_mfma_f32_16x16x32_bf16 v[62:65], v[200:203], v[216:219], v[62:65]
	v_mfma_f32_16x16x32_bf16 v[26:29], v[200:203], v[220:223], v[26:29]
	v_mfma_f32_16x16x32_bf16 v[30:33], v[200:203], v[224:227], v[30:33]
	ds_read_b128 v[200:203], v244 offset:20800
	s_waitcnt lgkmcnt(7)
	v_mfma_f32_16x16x32_bf16 v[34:37], v[204:207], v[212:215], v[34:37]
	v_mfma_f32_16x16x32_bf16 v[38:41], v[204:207], v[216:219], v[38:41]
	v_mfma_f32_16x16x32_bf16 v[2:5], v[204:207], v[220:223], v[2:5]
	v_mfma_f32_16x16x32_bf16 v[6:9], v[204:207], v[224:227], v[6:9]
	ds_read_b128 v[204:207], v244 offset:23104
	s_waitcnt vmcnt(15)
	ds_write_b128 v98, v[140:143]
	s_waitcnt vmcnt(14)
	ds_write_b128 v98, v[144:147] offset:4608
	s_waitcnt lgkmcnt(9)
	v_mfma_f32_16x16x32_bf16 v[42:45], v[208:211], v[212:215], v[42:45]
	v_mfma_f32_16x16x32_bf16 v[46:49], v[208:211], v[216:219], v[46:49]
	v_mfma_f32_16x16x32_bf16 v[10:13], v[208:211], v[220:223], v[10:13]
	v_mfma_f32_16x16x32_bf16 v[14:17], v[208:211], v[224:227], v[14:17]
	ds_read_b128 v[208:211], v244 offset:25408
	s_waitcnt vmcnt(13)
	ds_write_b128 v98, v[148:151] offset:9216
	s_waitcnt vmcnt(12)
	ds_write_b128 v98, v[152:155] offset:13824
	s_waitcnt lgkmcnt(7)
	v_mfma_f32_16x16x32_bf16 v[50:53], v[196:199], v[228:231], v[50:53]
	v_mfma_f32_16x16x32_bf16 v[54:57], v[196:199], v[232:235], v[54:57]
	v_mfma_f32_16x16x32_bf16 v[18:21], v[196:199], v[236:239], v[18:21]
	v_mfma_f32_16x16x32_bf16 v[22:25], v[196:199], v[240:243], v[22:25]
	s_waitcnt vmcnt(11)
	ds_write_b128 v98, v[156:159] offset:36864
	s_waitcnt vmcnt(10)
	ds_write_b128 v98, v[160:163] offset:41472
	s_waitcnt lgkmcnt(8)
	v_mfma_f32_16x16x32_bf16 v[58:61], v[200:203], v[228:231], v[58:61]
	v_mfma_f32_16x16x32_bf16 v[62:65], v[200:203], v[232:235], v[62:65]
	v_mfma_f32_16x16x32_bf16 v[26:29], v[200:203], v[236:239], v[26:29]
	v_mfma_f32_16x16x32_bf16 v[30:33], v[200:203], v[240:243], v[30:33]
	s_waitcnt vmcnt(9)
	ds_write_b128 v98, v[164:167] offset:46080
	s_waitcnt vmcnt(8)
	ds_write_b128 v98, v[168:171] offset:50688
	s_waitcnt lgkmcnt(9)
	v_mfma_f32_16x16x32_bf16 v[34:37], v[204:207], v[228:231], v[34:37]
	v_mfma_f32_16x16x32_bf16 v[38:41], v[204:207], v[232:235], v[38:41]
	v_mfma_f32_16x16x32_bf16 v[2:5], v[204:207], v[236:239], v[2:5]
	v_mfma_f32_16x16x32_bf16 v[6:9], v[204:207], v[240:243], v[6:9]
	s_waitcnt lgkmcnt(6)
	v_mfma_f32_16x16x32_bf16 v[42:45], v[208:211], v[228:231], v[42:45]
	v_mfma_f32_16x16x32_bf16 v[46:49], v[208:211], v[232:235], v[46:49]
	v_mfma_f32_16x16x32_bf16 v[10:13], v[208:211], v[236:239], v[10:13]
	v_mfma_f32_16x16x32_bf16 v[14:17], v[208:211], v[240:243], v[14:17]
	s_waitcnt lgkmcnt(0)
	s_barrier
	global_load_dwordx4 v[140:143], v[74:75], off offset:1280
	global_load_dwordx4 v[144:147], v[76:77], off offset:1280
	global_load_dwordx4 v[148:151], v[78:79], off offset:1280
	global_load_dwordx4 v[152:155], v[80:81], off offset:1280
	global_load_dwordx4 v[156:159], v[82:83], off offset:1280
	global_load_dwordx4 v[160:163], v[84:85], off offset:1280
	global_load_dwordx4 v[164:167], v[86:87], off offset:1280
	global_load_dwordx4 v[168:171], v[88:89], off offset:1280
	ds_read_b128 v[212:215], v245 offset:36864
	ds_read_b128 v[196:199], v244
	ds_read_b128 v[216:219], v245 offset:39168
	ds_read_b128 v[220:223], v245 offset:41472
	ds_read_b128 v[224:227], v245 offset:43776
	ds_read_b128 v[200:203], v244 offset:2304
	ds_read_b128 v[204:207], v244 offset:4608
	ds_read_b128 v[208:211], v244 offset:6912
	s_waitcnt lgkmcnt(6)
	v_mfma_f32_16x16x32_bf16 v[50:53], v[196:199], v[212:215], v[50:53]
	ds_read_b128 v[228:231], v245 offset:36928
	s_waitcnt lgkmcnt(6)
	v_mfma_f32_16x16x32_bf16 v[54:57], v[196:199], v[216:219], v[54:57]
	ds_read_b128 v[232:235], v245 offset:39232
	s_waitcnt lgkmcnt(6)
	v_mfma_f32_16x16x32_bf16 v[18:21], v[196:199], v[220:223], v[18:21]
	ds_read_b128 v[236:239], v245 offset:41536
	s_waitcnt lgkmcnt(6)
	v_mfma_f32_16x16x32_bf16 v[22:25], v[196:199], v[224:227], v[22:25]
	ds_read_b128 v[240:243], v245 offset:43840
	ds_read_b128 v[196:199], v244 offset:64
	s_waitcnt lgkmcnt(7)
	v_mfma_f32_16x16x32_bf16 v[58:61], v[200:203], v[212:215], v[58:61]
	v_mfma_f32_16x16x32_bf16 v[62:65], v[200:203], v[216:219], v[62:65]
	v_mfma_f32_16x16x32_bf16 v[26:29], v[200:203], v[220:223], v[26:29]
	v_mfma_f32_16x16x32_bf16 v[30:33], v[200:203], v[224:227], v[30:33]
	ds_read_b128 v[200:203], v244 offset:2368
	s_waitcnt lgkmcnt(7)
	v_mfma_f32_16x16x32_bf16 v[34:37], v[204:207], v[212:215], v[34:37]
	v_mfma_f32_16x16x32_bf16 v[38:41], v[204:207], v[216:219], v[38:41]
	v_mfma_f32_16x16x32_bf16 v[2:5], v[204:207], v[220:223], v[2:5]
	v_mfma_f32_16x16x32_bf16 v[6:9], v[204:207], v[224:227], v[6:9]
	ds_read_b128 v[204:207], v244 offset:4672
	s_waitcnt vmcnt(15)
	ds_write_b128 v98, v[102:105] offset:18432
	s_waitcnt vmcnt(14)
	ds_write_b128 v98, v[106:109] offset:23040
	s_waitcnt lgkmcnt(9)
	v_mfma_f32_16x16x32_bf16 v[42:45], v[208:211], v[212:215], v[42:45]
	v_mfma_f32_16x16x32_bf16 v[46:49], v[208:211], v[216:219], v[46:49]
	v_mfma_f32_16x16x32_bf16 v[10:13], v[208:211], v[220:223], v[10:13]
	v_mfma_f32_16x16x32_bf16 v[14:17], v[208:211], v[224:227], v[14:17]
	ds_read_b128 v[208:211], v244 offset:6976
	s_waitcnt vmcnt(13)
	ds_write_b128 v98, v[110:113] offset:27648
	s_waitcnt vmcnt(12)
	ds_write_b128 v98, v[114:117] offset:32256
	s_waitcnt lgkmcnt(7)
	v_mfma_f32_16x16x32_bf16 v[50:53], v[196:199], v[228:231], v[50:53]
	v_mfma_f32_16x16x32_bf16 v[54:57], v[196:199], v[232:235], v[54:57]
	v_mfma_f32_16x16x32_bf16 v[18:21], v[196:199], v[236:239], v[18:21]
	v_mfma_f32_16x16x32_bf16 v[22:25], v[196:199], v[240:243], v[22:25]
	s_waitcnt vmcnt(11)
	ds_write_b128 v98, v[118:121] offset:55296
	s_waitcnt vmcnt(10)
	ds_write_b128 v98, v[122:125] offset:59904
	s_waitcnt lgkmcnt(8)
	v_mfma_f32_16x16x32_bf16 v[58:61], v[200:203], v[228:231], v[58:61]
	v_mfma_f32_16x16x32_bf16 v[62:65], v[200:203], v[232:235], v[62:65]
	v_mfma_f32_16x16x32_bf16 v[26:29], v[200:203], v[236:239], v[26:29]
	v_mfma_f32_16x16x32_bf16 v[30:33], v[200:203], v[240:243], v[30:33]
	s_waitcnt vmcnt(9)
	ds_write_b128 v98, v[126:129] offset:64512
	s_waitcnt vmcnt(8)
	ds_write_b128 v99, v[136:139] offset:32256
	s_waitcnt lgkmcnt(9)
	v_mfma_f32_16x16x32_bf16 v[34:37], v[204:207], v[228:231], v[34:37]
	v_mfma_f32_16x16x32_bf16 v[38:41], v[204:207], v[232:235], v[38:41]
	v_mfma_f32_16x16x32_bf16 v[2:5], v[204:207], v[236:239], v[2:5]
	v_mfma_f32_16x16x32_bf16 v[6:9], v[204:207], v[240:243], v[6:9]
	s_waitcnt lgkmcnt(6)
	v_mfma_f32_16x16x32_bf16 v[42:45], v[208:211], v[228:231], v[42:45]
	v_mfma_f32_16x16x32_bf16 v[46:49], v[208:211], v[232:235], v[46:49]
	v_mfma_f32_16x16x32_bf16 v[10:13], v[208:211], v[236:239], v[10:13]
	v_mfma_f32_16x16x32_bf16 v[14:17], v[208:211], v[240:243], v[14:17]
	s_waitcnt lgkmcnt(0)
	s_barrier
	global_load_dwordx4 v[102:105], v[74:75], off offset:1408
	global_load_dwordx4 v[106:109], v[76:77], off offset:1408
	global_load_dwordx4 v[110:113], v[78:79], off offset:1408
	global_load_dwordx4 v[114:117], v[80:81], off offset:1408
	global_load_dwordx4 v[118:121], v[82:83], off offset:1408
	global_load_dwordx4 v[122:125], v[84:85], off offset:1408
	global_load_dwordx4 v[126:129], v[86:87], off offset:1408
	global_load_dwordx4 v[136:139], v[88:89], off offset:1408
	ds_read_b128 v[212:215], v245 offset:55296
	ds_read_b128 v[196:199], v244 offset:18432
	ds_read_b128 v[216:219], v245 offset:57600
	ds_read_b128 v[220:223], v245 offset:59904
	ds_read_b128 v[224:227], v245 offset:62208
	ds_read_b128 v[200:203], v244 offset:20736
	ds_read_b128 v[204:207], v244 offset:23040
	ds_read_b128 v[208:211], v244 offset:25344
	s_waitcnt lgkmcnt(6)
	v_mfma_f32_16x16x32_bf16 v[50:53], v[196:199], v[212:215], v[50:53]
	ds_read_b128 v[228:231], v245 offset:55360
	s_waitcnt lgkmcnt(6)
	v_mfma_f32_16x16x32_bf16 v[54:57], v[196:199], v[216:219], v[54:57]
	ds_read_b128 v[232:235], v245 offset:57664
	s_waitcnt lgkmcnt(6)
	v_mfma_f32_16x16x32_bf16 v[18:21], v[196:199], v[220:223], v[18:21]
	ds_read_b128 v[236:239], v245 offset:59968
	s_waitcnt lgkmcnt(6)
	v_mfma_f32_16x16x32_bf16 v[22:25], v[196:199], v[224:227], v[22:25]
	ds_read_b128 v[240:243], v245 offset:62272
	ds_read_b128 v[196:199], v244 offset:18496
	s_waitcnt lgkmcnt(7)
	v_mfma_f32_16x16x32_bf16 v[58:61], v[200:203], v[212:215], v[58:61]
	v_mfma_f32_16x16x32_bf16 v[62:65], v[200:203], v[216:219], v[62:65]
	v_mfma_f32_16x16x32_bf16 v[26:29], v[200:203], v[220:223], v[26:29]
	v_mfma_f32_16x16x32_bf16 v[30:33], v[200:203], v[224:227], v[30:33]
	ds_read_b128 v[200:203], v244 offset:20800
	s_waitcnt lgkmcnt(7)
	v_mfma_f32_16x16x32_bf16 v[34:37], v[204:207], v[212:215], v[34:37]
	v_mfma_f32_16x16x32_bf16 v[38:41], v[204:207], v[216:219], v[38:41]
	v_mfma_f32_16x16x32_bf16 v[2:5], v[204:207], v[220:223], v[2:5]
	v_mfma_f32_16x16x32_bf16 v[6:9], v[204:207], v[224:227], v[6:9]
	ds_read_b128 v[204:207], v244 offset:23104
	s_waitcnt vmcnt(15)
	ds_write_b128 v98, v[140:143]
	s_waitcnt vmcnt(14)
	ds_write_b128 v98, v[144:147] offset:4608
	s_waitcnt lgkmcnt(9)
	v_mfma_f32_16x16x32_bf16 v[42:45], v[208:211], v[212:215], v[42:45]
	v_mfma_f32_16x16x32_bf16 v[46:49], v[208:211], v[216:219], v[46:49]
	v_mfma_f32_16x16x32_bf16 v[10:13], v[208:211], v[220:223], v[10:13]
	v_mfma_f32_16x16x32_bf16 v[14:17], v[208:211], v[224:227], v[14:17]
	ds_read_b128 v[208:211], v244 offset:25408
	s_waitcnt vmcnt(13)
	ds_write_b128 v98, v[148:151] offset:9216
	s_waitcnt vmcnt(12)
	ds_write_b128 v98, v[152:155] offset:13824
	s_waitcnt lgkmcnt(7)
	v_mfma_f32_16x16x32_bf16 v[50:53], v[196:199], v[228:231], v[50:53]
	v_mfma_f32_16x16x32_bf16 v[54:57], v[196:199], v[232:235], v[54:57]
	v_mfma_f32_16x16x32_bf16 v[18:21], v[196:199], v[236:239], v[18:21]
	v_mfma_f32_16x16x32_bf16 v[22:25], v[196:199], v[240:243], v[22:25]
	s_waitcnt vmcnt(11)
	ds_write_b128 v98, v[156:159] offset:36864
	s_waitcnt vmcnt(10)
	ds_write_b128 v98, v[160:163] offset:41472
	s_waitcnt lgkmcnt(8)
	v_mfma_f32_16x16x32_bf16 v[58:61], v[200:203], v[228:231], v[58:61]
	v_mfma_f32_16x16x32_bf16 v[62:65], v[200:203], v[232:235], v[62:65]
	v_mfma_f32_16x16x32_bf16 v[26:29], v[200:203], v[236:239], v[26:29]
	v_mfma_f32_16x16x32_bf16 v[30:33], v[200:203], v[240:243], v[30:33]
	s_waitcnt vmcnt(9)
	ds_write_b128 v98, v[164:167] offset:46080
	s_waitcnt vmcnt(8)
	ds_write_b128 v98, v[168:171] offset:50688
	s_waitcnt lgkmcnt(9)
	v_mfma_f32_16x16x32_bf16 v[34:37], v[204:207], v[228:231], v[34:37]
	v_mfma_f32_16x16x32_bf16 v[38:41], v[204:207], v[232:235], v[38:41]
	v_mfma_f32_16x16x32_bf16 v[2:5], v[204:207], v[236:239], v[2:5]
	v_mfma_f32_16x16x32_bf16 v[6:9], v[204:207], v[240:243], v[6:9]
	s_waitcnt lgkmcnt(6)
	v_mfma_f32_16x16x32_bf16 v[42:45], v[208:211], v[228:231], v[42:45]
	v_mfma_f32_16x16x32_bf16 v[46:49], v[208:211], v[232:235], v[46:49]
	v_mfma_f32_16x16x32_bf16 v[10:13], v[208:211], v[236:239], v[10:13]
	v_mfma_f32_16x16x32_bf16 v[14:17], v[208:211], v[240:243], v[14:17]
	s_waitcnt lgkmcnt(0)
	s_barrier
	global_load_dwordx4 v[140:143], v[74:75], off offset:1536
	global_load_dwordx4 v[144:147], v[76:77], off offset:1536
	global_load_dwordx4 v[148:151], v[78:79], off offset:1536
	global_load_dwordx4 v[152:155], v[80:81], off offset:1536
	global_load_dwordx4 v[156:159], v[82:83], off offset:1536
	global_load_dwordx4 v[160:163], v[84:85], off offset:1536
	global_load_dwordx4 v[164:167], v[86:87], off offset:1536
	global_load_dwordx4 v[168:171], v[88:89], off offset:1536
	ds_read_b128 v[212:215], v245 offset:36864
	ds_read_b128 v[196:199], v244
	ds_read_b128 v[216:219], v245 offset:39168
	ds_read_b128 v[220:223], v245 offset:41472
	ds_read_b128 v[224:227], v245 offset:43776
	ds_read_b128 v[200:203], v244 offset:2304
	ds_read_b128 v[204:207], v244 offset:4608
	ds_read_b128 v[208:211], v244 offset:6912
	s_waitcnt lgkmcnt(6)
	v_mfma_f32_16x16x32_bf16 v[50:53], v[196:199], v[212:215], v[50:53]
	ds_read_b128 v[228:231], v245 offset:36928
	s_waitcnt lgkmcnt(6)
	v_mfma_f32_16x16x32_bf16 v[54:57], v[196:199], v[216:219], v[54:57]
	ds_read_b128 v[232:235], v245 offset:39232
	s_waitcnt lgkmcnt(6)
	v_mfma_f32_16x16x32_bf16 v[18:21], v[196:199], v[220:223], v[18:21]
	ds_read_b128 v[236:239], v245 offset:41536
	s_waitcnt lgkmcnt(6)
	v_mfma_f32_16x16x32_bf16 v[22:25], v[196:199], v[224:227], v[22:25]
	ds_read_b128 v[240:243], v245 offset:43840
	ds_read_b128 v[196:199], v244 offset:64
	s_waitcnt lgkmcnt(7)
	v_mfma_f32_16x16x32_bf16 v[58:61], v[200:203], v[212:215], v[58:61]
	v_mfma_f32_16x16x32_bf16 v[62:65], v[200:203], v[216:219], v[62:65]
	v_mfma_f32_16x16x32_bf16 v[26:29], v[200:203], v[220:223], v[26:29]
	v_mfma_f32_16x16x32_bf16 v[30:33], v[200:203], v[224:227], v[30:33]
	ds_read_b128 v[200:203], v244 offset:2368
	s_waitcnt lgkmcnt(7)
	v_mfma_f32_16x16x32_bf16 v[34:37], v[204:207], v[212:215], v[34:37]
	v_mfma_f32_16x16x32_bf16 v[38:41], v[204:207], v[216:219], v[38:41]
	v_mfma_f32_16x16x32_bf16 v[2:5], v[204:207], v[220:223], v[2:5]
	v_mfma_f32_16x16x32_bf16 v[6:9], v[204:207], v[224:227], v[6:9]
	ds_read_b128 v[204:207], v244 offset:4672
	s_waitcnt vmcnt(15)
	ds_write_b128 v98, v[102:105] offset:18432
	s_waitcnt vmcnt(14)
	ds_write_b128 v98, v[106:109] offset:23040
	s_waitcnt lgkmcnt(9)
	v_mfma_f32_16x16x32_bf16 v[42:45], v[208:211], v[212:215], v[42:45]
	v_mfma_f32_16x16x32_bf16 v[46:49], v[208:211], v[216:219], v[46:49]
	v_mfma_f32_16x16x32_bf16 v[10:13], v[208:211], v[220:223], v[10:13]
	v_mfma_f32_16x16x32_bf16 v[14:17], v[208:211], v[224:227], v[14:17]
	ds_read_b128 v[208:211], v244 offset:6976
	s_waitcnt vmcnt(13)
	ds_write_b128 v98, v[110:113] offset:27648
	s_waitcnt vmcnt(12)
	ds_write_b128 v98, v[114:117] offset:32256
	s_waitcnt lgkmcnt(7)
	v_mfma_f32_16x16x32_bf16 v[50:53], v[196:199], v[228:231], v[50:53]
	v_mfma_f32_16x16x32_bf16 v[54:57], v[196:199], v[232:235], v[54:57]
	v_mfma_f32_16x16x32_bf16 v[18:21], v[196:199], v[236:239], v[18:21]
	v_mfma_f32_16x16x32_bf16 v[22:25], v[196:199], v[240:243], v[22:25]
	s_waitcnt vmcnt(11)
	ds_write_b128 v98, v[118:121] offset:55296
	s_waitcnt vmcnt(10)
	ds_write_b128 v98, v[122:125] offset:59904
	s_waitcnt lgkmcnt(8)
	v_mfma_f32_16x16x32_bf16 v[58:61], v[200:203], v[228:231], v[58:61]
	v_mfma_f32_16x16x32_bf16 v[62:65], v[200:203], v[232:235], v[62:65]
	v_mfma_f32_16x16x32_bf16 v[26:29], v[200:203], v[236:239], v[26:29]
	v_mfma_f32_16x16x32_bf16 v[30:33], v[200:203], v[240:243], v[30:33]
	s_waitcnt vmcnt(9)
	ds_write_b128 v98, v[126:129] offset:64512
	s_waitcnt vmcnt(8)
	ds_write_b128 v99, v[136:139] offset:32256
	s_waitcnt lgkmcnt(9)
	v_mfma_f32_16x16x32_bf16 v[34:37], v[204:207], v[228:231], v[34:37]
	v_mfma_f32_16x16x32_bf16 v[38:41], v[204:207], v[232:235], v[38:41]
	v_mfma_f32_16x16x32_bf16 v[2:5], v[204:207], v[236:239], v[2:5]
	v_mfma_f32_16x16x32_bf16 v[6:9], v[204:207], v[240:243], v[6:9]
	s_waitcnt lgkmcnt(6)
	v_mfma_f32_16x16x32_bf16 v[42:45], v[208:211], v[228:231], v[42:45]
	v_mfma_f32_16x16x32_bf16 v[46:49], v[208:211], v[232:235], v[46:49]
	v_mfma_f32_16x16x32_bf16 v[10:13], v[208:211], v[236:239], v[10:13]
	v_mfma_f32_16x16x32_bf16 v[14:17], v[208:211], v[240:243], v[14:17]
	s_waitcnt lgkmcnt(0)
	s_barrier
	global_load_dwordx4 v[102:105], v[74:75], off offset:1664
	global_load_dwordx4 v[106:109], v[76:77], off offset:1664
	global_load_dwordx4 v[110:113], v[78:79], off offset:1664
	global_load_dwordx4 v[114:117], v[80:81], off offset:1664
	global_load_dwordx4 v[118:121], v[82:83], off offset:1664
	global_load_dwordx4 v[122:125], v[84:85], off offset:1664
	global_load_dwordx4 v[126:129], v[86:87], off offset:1664
	global_load_dwordx4 v[136:139], v[88:89], off offset:1664
	ds_read_b128 v[212:215], v245 offset:55296
	ds_read_b128 v[196:199], v244 offset:18432
	ds_read_b128 v[216:219], v245 offset:57600
	ds_read_b128 v[220:223], v245 offset:59904
	ds_read_b128 v[224:227], v245 offset:62208
	ds_read_b128 v[200:203], v244 offset:20736
	ds_read_b128 v[204:207], v244 offset:23040
	ds_read_b128 v[208:211], v244 offset:25344
	s_waitcnt lgkmcnt(6)
	v_mfma_f32_16x16x32_bf16 v[50:53], v[196:199], v[212:215], v[50:53]
	ds_read_b128 v[228:231], v245 offset:55360
	s_waitcnt lgkmcnt(6)
	v_mfma_f32_16x16x32_bf16 v[54:57], v[196:199], v[216:219], v[54:57]
	ds_read_b128 v[232:235], v245 offset:57664
	s_waitcnt lgkmcnt(6)
	v_mfma_f32_16x16x32_bf16 v[18:21], v[196:199], v[220:223], v[18:21]
	ds_read_b128 v[236:239], v245 offset:59968
	s_waitcnt lgkmcnt(6)
	v_mfma_f32_16x16x32_bf16 v[22:25], v[196:199], v[224:227], v[22:25]
	ds_read_b128 v[240:243], v245 offset:62272
	ds_read_b128 v[196:199], v244 offset:18496
	s_waitcnt lgkmcnt(7)
	v_mfma_f32_16x16x32_bf16 v[58:61], v[200:203], v[212:215], v[58:61]
	v_mfma_f32_16x16x32_bf16 v[62:65], v[200:203], v[216:219], v[62:65]
	v_mfma_f32_16x16x32_bf16 v[26:29], v[200:203], v[220:223], v[26:29]
	v_mfma_f32_16x16x32_bf16 v[30:33], v[200:203], v[224:227], v[30:33]
	ds_read_b128 v[200:203], v244 offset:20800
	s_waitcnt lgkmcnt(7)
	v_mfma_f32_16x16x32_bf16 v[34:37], v[204:207], v[212:215], v[34:37]
	v_mfma_f32_16x16x32_bf16 v[38:41], v[204:207], v[216:219], v[38:41]
	v_mfma_f32_16x16x32_bf16 v[2:5], v[204:207], v[220:223], v[2:5]
	v_mfma_f32_16x16x32_bf16 v[6:9], v[204:207], v[224:227], v[6:9]
	ds_read_b128 v[204:207], v244 offset:23104
	s_waitcnt vmcnt(15)
	ds_write_b128 v98, v[140:143]
	s_waitcnt vmcnt(14)
	ds_write_b128 v98, v[144:147] offset:4608
	s_waitcnt lgkmcnt(9)
	v_mfma_f32_16x16x32_bf16 v[42:45], v[208:211], v[212:215], v[42:45]
	v_mfma_f32_16x16x32_bf16 v[46:49], v[208:211], v[216:219], v[46:49]
	v_mfma_f32_16x16x32_bf16 v[10:13], v[208:211], v[220:223], v[10:13]
	v_mfma_f32_16x16x32_bf16 v[14:17], v[208:211], v[224:227], v[14:17]
	ds_read_b128 v[208:211], v244 offset:25408
	s_waitcnt vmcnt(13)
	ds_write_b128 v98, v[148:151] offset:9216
	s_waitcnt vmcnt(12)
	ds_write_b128 v98, v[152:155] offset:13824
	s_waitcnt lgkmcnt(7)
	v_mfma_f32_16x16x32_bf16 v[50:53], v[196:199], v[228:231], v[50:53]
	v_mfma_f32_16x16x32_bf16 v[54:57], v[196:199], v[232:235], v[54:57]
	v_mfma_f32_16x16x32_bf16 v[18:21], v[196:199], v[236:239], v[18:21]
	v_mfma_f32_16x16x32_bf16 v[22:25], v[196:199], v[240:243], v[22:25]
	s_waitcnt vmcnt(11)
	ds_write_b128 v98, v[156:159] offset:36864
	s_waitcnt vmcnt(10)
	ds_write_b128 v98, v[160:163] offset:41472
	s_waitcnt lgkmcnt(8)
	v_mfma_f32_16x16x32_bf16 v[58:61], v[200:203], v[228:231], v[58:61]
	v_mfma_f32_16x16x32_bf16 v[62:65], v[200:203], v[232:235], v[62:65]
	v_mfma_f32_16x16x32_bf16 v[26:29], v[200:203], v[236:239], v[26:29]
	v_mfma_f32_16x16x32_bf16 v[30:33], v[200:203], v[240:243], v[30:33]
	s_waitcnt vmcnt(9)
	ds_write_b128 v98, v[164:167] offset:46080
	s_waitcnt vmcnt(8)
	ds_write_b128 v98, v[168:171] offset:50688
	s_waitcnt lgkmcnt(9)
	v_mfma_f32_16x16x32_bf16 v[34:37], v[204:207], v[228:231], v[34:37]
	v_mfma_f32_16x16x32_bf16 v[38:41], v[204:207], v[232:235], v[38:41]
	v_mfma_f32_16x16x32_bf16 v[2:5], v[204:207], v[236:239], v[2:5]
	v_mfma_f32_16x16x32_bf16 v[6:9], v[204:207], v[240:243], v[6:9]
	s_waitcnt lgkmcnt(6)
	v_mfma_f32_16x16x32_bf16 v[42:45], v[208:211], v[228:231], v[42:45]
	v_mfma_f32_16x16x32_bf16 v[46:49], v[208:211], v[232:235], v[46:49]
	v_mfma_f32_16x16x32_bf16 v[10:13], v[208:211], v[236:239], v[10:13]
	v_mfma_f32_16x16x32_bf16 v[14:17], v[208:211], v[240:243], v[14:17]
	s_waitcnt lgkmcnt(0)
	s_barrier
	global_load_dwordx4 v[140:143], v[74:75], off offset:1792
	global_load_dwordx4 v[144:147], v[76:77], off offset:1792
	global_load_dwordx4 v[148:151], v[78:79], off offset:1792
	global_load_dwordx4 v[152:155], v[80:81], off offset:1792
	global_load_dwordx4 v[156:159], v[82:83], off offset:1792
	global_load_dwordx4 v[160:163], v[84:85], off offset:1792
	global_load_dwordx4 v[164:167], v[86:87], off offset:1792
	global_load_dwordx4 v[168:171], v[88:89], off offset:1792
	ds_read_b128 v[212:215], v245 offset:36864
	ds_read_b128 v[196:199], v244
	ds_read_b128 v[216:219], v245 offset:39168
	ds_read_b128 v[220:223], v245 offset:41472
	ds_read_b128 v[224:227], v245 offset:43776
	ds_read_b128 v[200:203], v244 offset:2304
	ds_read_b128 v[204:207], v244 offset:4608
	ds_read_b128 v[208:211], v244 offset:6912
	s_waitcnt lgkmcnt(6)
	v_mfma_f32_16x16x32_bf16 v[50:53], v[196:199], v[212:215], v[50:53]
	ds_read_b128 v[228:231], v245 offset:36928
	s_waitcnt lgkmcnt(6)
	v_mfma_f32_16x16x32_bf16 v[54:57], v[196:199], v[216:219], v[54:57]
	ds_read_b128 v[232:235], v245 offset:39232
	s_waitcnt lgkmcnt(6)
	v_mfma_f32_16x16x32_bf16 v[18:21], v[196:199], v[220:223], v[18:21]
	ds_read_b128 v[236:239], v245 offset:41536
	s_waitcnt lgkmcnt(6)
	v_mfma_f32_16x16x32_bf16 v[22:25], v[196:199], v[224:227], v[22:25]
	ds_read_b128 v[240:243], v245 offset:43840
	ds_read_b128 v[196:199], v244 offset:64
	s_waitcnt lgkmcnt(7)
	v_mfma_f32_16x16x32_bf16 v[58:61], v[200:203], v[212:215], v[58:61]
	v_mfma_f32_16x16x32_bf16 v[62:65], v[200:203], v[216:219], v[62:65]
	v_mfma_f32_16x16x32_bf16 v[26:29], v[200:203], v[220:223], v[26:29]
	v_mfma_f32_16x16x32_bf16 v[30:33], v[200:203], v[224:227], v[30:33]
	ds_read_b128 v[200:203], v244 offset:2368
	s_waitcnt lgkmcnt(7)
	v_mfma_f32_16x16x32_bf16 v[34:37], v[204:207], v[212:215], v[34:37]
	v_mfma_f32_16x16x32_bf16 v[38:41], v[204:207], v[216:219], v[38:41]
	v_mfma_f32_16x16x32_bf16 v[2:5], v[204:207], v[220:223], v[2:5]
	v_mfma_f32_16x16x32_bf16 v[6:9], v[204:207], v[224:227], v[6:9]
	ds_read_b128 v[204:207], v244 offset:4672
	s_waitcnt vmcnt(15)
	ds_write_b128 v98, v[102:105] offset:18432
	s_waitcnt vmcnt(14)
	ds_write_b128 v98, v[106:109] offset:23040
	s_waitcnt lgkmcnt(9)
	v_mfma_f32_16x16x32_bf16 v[42:45], v[208:211], v[212:215], v[42:45]
	v_mfma_f32_16x16x32_bf16 v[46:49], v[208:211], v[216:219], v[46:49]
	v_mfma_f32_16x16x32_bf16 v[10:13], v[208:211], v[220:223], v[10:13]
	v_mfma_f32_16x16x32_bf16 v[14:17], v[208:211], v[224:227], v[14:17]
	ds_read_b128 v[208:211], v244 offset:6976
	s_waitcnt vmcnt(13)
	ds_write_b128 v98, v[110:113] offset:27648
	s_waitcnt vmcnt(12)
	ds_write_b128 v98, v[114:117] offset:32256
	s_waitcnt lgkmcnt(7)
	v_mfma_f32_16x16x32_bf16 v[50:53], v[196:199], v[228:231], v[50:53]
	v_mfma_f32_16x16x32_bf16 v[54:57], v[196:199], v[232:235], v[54:57]
	v_mfma_f32_16x16x32_bf16 v[18:21], v[196:199], v[236:239], v[18:21]
	v_mfma_f32_16x16x32_bf16 v[22:25], v[196:199], v[240:243], v[22:25]
	s_waitcnt vmcnt(11)
	ds_write_b128 v98, v[118:121] offset:55296
	s_waitcnt vmcnt(10)
	ds_write_b128 v98, v[122:125] offset:59904
	s_waitcnt lgkmcnt(8)
	v_mfma_f32_16x16x32_bf16 v[58:61], v[200:203], v[228:231], v[58:61]
	v_mfma_f32_16x16x32_bf16 v[62:65], v[200:203], v[232:235], v[62:65]
	v_mfma_f32_16x16x32_bf16 v[26:29], v[200:203], v[236:239], v[26:29]
	v_mfma_f32_16x16x32_bf16 v[30:33], v[200:203], v[240:243], v[30:33]
	s_waitcnt vmcnt(9)
	ds_write_b128 v98, v[126:129] offset:64512
	s_waitcnt vmcnt(8)
	ds_write_b128 v99, v[136:139] offset:32256
	s_waitcnt lgkmcnt(9)
	v_mfma_f32_16x16x32_bf16 v[34:37], v[204:207], v[228:231], v[34:37]
	v_mfma_f32_16x16x32_bf16 v[38:41], v[204:207], v[232:235], v[38:41]
	v_mfma_f32_16x16x32_bf16 v[2:5], v[204:207], v[236:239], v[2:5]
	v_mfma_f32_16x16x32_bf16 v[6:9], v[204:207], v[240:243], v[6:9]
	s_waitcnt lgkmcnt(6)
	v_mfma_f32_16x16x32_bf16 v[42:45], v[208:211], v[228:231], v[42:45]
	v_mfma_f32_16x16x32_bf16 v[46:49], v[208:211], v[232:235], v[46:49]
	v_mfma_f32_16x16x32_bf16 v[10:13], v[208:211], v[236:239], v[10:13]
	v_mfma_f32_16x16x32_bf16 v[14:17], v[208:211], v[240:243], v[14:17]
	s_waitcnt lgkmcnt(0)
	s_barrier
	global_load_dwordx4 v[102:105], v[74:75], off offset:1920
	s_nop 0
	global_load_dwordx4 v[74:77], v[76:77], off offset:1920
	s_nop 0
	global_load_dwordx4 v[106:109], v[78:79], off offset:1920
	s_nop 0
	global_load_dwordx4 v[78:81], v[80:81], off offset:1920
	s_nop 0
	global_load_dwordx4 v[110:113], v[82:83], off offset:1920
	s_nop 0
	global_load_dwordx4 v[82:85], v[84:85], off offset:1920
	s_nop 0
	global_load_dwordx4 v[114:117], v[86:87], off offset:1920
	s_nop 0
	global_load_dwordx4 v[86:89], v[88:89], off offset:1920
	ds_read_b128 v[212:215], v245 offset:55296
	ds_read_b128 v[196:199], v244 offset:18432
	ds_read_b128 v[216:219], v245 offset:57600
	ds_read_b128 v[220:223], v245 offset:59904
	ds_read_b128 v[224:227], v245 offset:62208
	ds_read_b128 v[200:203], v244 offset:20736
	ds_read_b128 v[204:207], v244 offset:23040
	ds_read_b128 v[208:211], v244 offset:25344
	s_waitcnt lgkmcnt(6)
	v_mfma_f32_16x16x32_bf16 v[50:53], v[196:199], v[212:215], v[50:53]
	ds_read_b128 v[228:231], v245 offset:55360
	s_waitcnt lgkmcnt(6)
	v_mfma_f32_16x16x32_bf16 v[54:57], v[196:199], v[216:219], v[54:57]
	ds_read_b128 v[232:235], v245 offset:57664
	s_waitcnt lgkmcnt(6)
	v_mfma_f32_16x16x32_bf16 v[18:21], v[196:199], v[220:223], v[18:21]
	ds_read_b128 v[236:239], v245 offset:59968
	s_waitcnt lgkmcnt(6)
	v_mfma_f32_16x16x32_bf16 v[22:25], v[196:199], v[224:227], v[22:25]
	ds_read_b128 v[240:243], v245 offset:62272
	ds_read_b128 v[196:199], v244 offset:18496
	s_waitcnt lgkmcnt(7)
	v_mfma_f32_16x16x32_bf16 v[58:61], v[200:203], v[212:215], v[58:61]
	v_mfma_f32_16x16x32_bf16 v[62:65], v[200:203], v[216:219], v[62:65]
	v_mfma_f32_16x16x32_bf16 v[26:29], v[200:203], v[220:223], v[26:29]
	v_mfma_f32_16x16x32_bf16 v[30:33], v[200:203], v[224:227], v[30:33]
	ds_read_b128 v[200:203], v244 offset:20800
	s_waitcnt lgkmcnt(7)
	v_mfma_f32_16x16x32_bf16 v[34:37], v[204:207], v[212:215], v[34:37]
	v_mfma_f32_16x16x32_bf16 v[38:41], v[204:207], v[216:219], v[38:41]
	v_mfma_f32_16x16x32_bf16 v[2:5], v[204:207], v[220:223], v[2:5]
	v_mfma_f32_16x16x32_bf16 v[6:9], v[204:207], v[224:227], v[6:9]
	ds_read_b128 v[204:207], v244 offset:23104
	s_waitcnt vmcnt(15)
	ds_write_b128 v98, v[140:143]
	s_waitcnt vmcnt(14)
	ds_write_b128 v98, v[144:147] offset:4608
	s_waitcnt lgkmcnt(9)
	v_mfma_f32_16x16x32_bf16 v[42:45], v[208:211], v[212:215], v[42:45]
	v_mfma_f32_16x16x32_bf16 v[46:49], v[208:211], v[216:219], v[46:49]
	v_mfma_f32_16x16x32_bf16 v[10:13], v[208:211], v[220:223], v[10:13]
	v_mfma_f32_16x16x32_bf16 v[14:17], v[208:211], v[224:227], v[14:17]
	ds_read_b128 v[208:211], v244 offset:25408
	s_waitcnt vmcnt(13)
	ds_write_b128 v98, v[148:151] offset:9216
	s_waitcnt vmcnt(12)
	ds_write_b128 v98, v[152:155] offset:13824
	s_waitcnt lgkmcnt(7)
	v_mfma_f32_16x16x32_bf16 v[50:53], v[196:199], v[228:231], v[50:53]
	v_mfma_f32_16x16x32_bf16 v[54:57], v[196:199], v[232:235], v[54:57]
	v_mfma_f32_16x16x32_bf16 v[18:21], v[196:199], v[236:239], v[18:21]
	v_mfma_f32_16x16x32_bf16 v[22:25], v[196:199], v[240:243], v[22:25]
	s_waitcnt vmcnt(11)
	ds_write_b128 v98, v[156:159] offset:36864
	s_waitcnt vmcnt(10)
	ds_write_b128 v98, v[160:163] offset:41472
	s_waitcnt lgkmcnt(8)
	v_mfma_f32_16x16x32_bf16 v[58:61], v[200:203], v[228:231], v[58:61]
	v_mfma_f32_16x16x32_bf16 v[62:65], v[200:203], v[232:235], v[62:65]
	v_mfma_f32_16x16x32_bf16 v[26:29], v[200:203], v[236:239], v[26:29]
	v_mfma_f32_16x16x32_bf16 v[30:33], v[200:203], v[240:243], v[30:33]
	s_waitcnt vmcnt(9)
	ds_write_b128 v98, v[164:167] offset:46080
	s_waitcnt vmcnt(8)
	ds_write_b128 v98, v[168:171] offset:50688
	s_waitcnt lgkmcnt(9)
	v_mfma_f32_16x16x32_bf16 v[34:37], v[204:207], v[228:231], v[34:37]
	v_mfma_f32_16x16x32_bf16 v[38:41], v[204:207], v[232:235], v[38:41]
	v_mfma_f32_16x16x32_bf16 v[2:5], v[204:207], v[236:239], v[2:5]
	v_mfma_f32_16x16x32_bf16 v[6:9], v[204:207], v[240:243], v[6:9]
	s_waitcnt lgkmcnt(6)
	v_mfma_f32_16x16x32_bf16 v[42:45], v[208:211], v[228:231], v[42:45]
	v_mfma_f32_16x16x32_bf16 v[46:49], v[208:211], v[232:235], v[46:49]
	v_mfma_f32_16x16x32_bf16 v[10:13], v[208:211], v[236:239], v[10:13]
	v_mfma_f32_16x16x32_bf16 v[14:17], v[208:211], v[240:243], v[14:17]
	s_waitcnt lgkmcnt(0)
	s_barrier
	ds_read_b128 v[212:215], v245 offset:36864
	ds_read_b128 v[196:199], v244
	ds_read_b128 v[216:219], v245 offset:39168
	ds_read_b128 v[220:223], v245 offset:41472
	ds_read_b128 v[224:227], v245 offset:43776
	ds_read_b128 v[200:203], v244 offset:2304
	ds_read_b128 v[204:207], v244 offset:4608
	ds_read_b128 v[208:211], v244 offset:6912
	s_waitcnt lgkmcnt(6)
	v_mfma_f32_16x16x32_bf16 v[50:53], v[196:199], v[212:215], v[50:53]
	ds_read_b128 v[228:231], v245 offset:36928
	s_waitcnt lgkmcnt(6)
	v_mfma_f32_16x16x32_bf16 v[54:57], v[196:199], v[216:219], v[54:57]
	ds_read_b128 v[232:235], v245 offset:39232
	s_waitcnt lgkmcnt(6)
	v_mfma_f32_16x16x32_bf16 v[18:21], v[196:199], v[220:223], v[18:21]
	ds_read_b128 v[236:239], v245 offset:41536
	s_waitcnt lgkmcnt(6)
	v_mfma_f32_16x16x32_bf16 v[22:25], v[196:199], v[224:227], v[22:25]
	ds_read_b128 v[240:243], v245 offset:43840
	ds_read_b128 v[196:199], v244 offset:64
	s_waitcnt lgkmcnt(7)
	v_mfma_f32_16x16x32_bf16 v[58:61], v[200:203], v[212:215], v[58:61]
	v_mfma_f32_16x16x32_bf16 v[62:65], v[200:203], v[216:219], v[62:65]
	v_mfma_f32_16x16x32_bf16 v[26:29], v[200:203], v[220:223], v[26:29]
	v_mfma_f32_16x16x32_bf16 v[30:33], v[200:203], v[224:227], v[30:33]
	ds_read_b128 v[200:203], v244 offset:2368
	s_waitcnt lgkmcnt(7)
	v_mfma_f32_16x16x32_bf16 v[34:37], v[204:207], v[212:215], v[34:37]
	v_mfma_f32_16x16x32_bf16 v[38:41], v[204:207], v[216:219], v[38:41]
	v_mfma_f32_16x16x32_bf16 v[2:5], v[204:207], v[220:223], v[2:5]
	v_mfma_f32_16x16x32_bf16 v[6:9], v[204:207], v[224:227], v[6:9]
	ds_read_b128 v[204:207], v244 offset:4672
	s_waitcnt vmcnt(7)
	ds_write_b128 v98, v[102:105] offset:18432
	s_waitcnt vmcnt(6)
	ds_write_b128 v98, v[74:77] offset:23040
	s_waitcnt lgkmcnt(9)
	v_mfma_f32_16x16x32_bf16 v[42:45], v[208:211], v[212:215], v[42:45]
	v_mfma_f32_16x16x32_bf16 v[46:49], v[208:211], v[216:219], v[46:49]
	v_mfma_f32_16x16x32_bf16 v[10:13], v[208:211], v[220:223], v[10:13]
	v_mfma_f32_16x16x32_bf16 v[14:17], v[208:211], v[224:227], v[14:17]
	ds_read_b128 v[208:211], v244 offset:6976
	s_waitcnt vmcnt(5)
	ds_write_b128 v98, v[106:109] offset:27648
	s_waitcnt vmcnt(4)
	ds_write_b128 v98, v[78:81] offset:32256
	s_waitcnt lgkmcnt(7)
	v_mfma_f32_16x16x32_bf16 v[50:53], v[196:199], v[228:231], v[50:53]
	v_mfma_f32_16x16x32_bf16 v[54:57], v[196:199], v[232:235], v[54:57]
	v_mfma_f32_16x16x32_bf16 v[18:21], v[196:199], v[236:239], v[18:21]
	v_mfma_f32_16x16x32_bf16 v[22:25], v[196:199], v[240:243], v[22:25]
	s_waitcnt vmcnt(3)
	ds_write_b128 v98, v[110:113] offset:55296
	s_waitcnt vmcnt(2)
	ds_write_b128 v98, v[82:85] offset:59904
	s_waitcnt lgkmcnt(8)
	v_mfma_f32_16x16x32_bf16 v[58:61], v[200:203], v[228:231], v[58:61]
	v_mfma_f32_16x16x32_bf16 v[62:65], v[200:203], v[232:235], v[62:65]
	v_mfma_f32_16x16x32_bf16 v[26:29], v[200:203], v[236:239], v[26:29]
	v_mfma_f32_16x16x32_bf16 v[30:33], v[200:203], v[240:243], v[30:33]
	s_waitcnt vmcnt(1)
	ds_write_b128 v98, v[114:117] offset:64512
	s_waitcnt vmcnt(0)
	ds_write_b128 v99, v[86:89] offset:32256
	s_waitcnt lgkmcnt(9)
	v_mfma_f32_16x16x32_bf16 v[34:37], v[204:207], v[228:231], v[34:37]
	v_mfma_f32_16x16x32_bf16 v[38:41], v[204:207], v[232:235], v[38:41]
	v_mfma_f32_16x16x32_bf16 v[2:5], v[204:207], v[236:239], v[2:5]
	v_mfma_f32_16x16x32_bf16 v[6:9], v[204:207], v[240:243], v[6:9]
	s_waitcnt lgkmcnt(6)
	v_mfma_f32_16x16x32_bf16 v[42:45], v[208:211], v[228:231], v[42:45]
	v_mfma_f32_16x16x32_bf16 v[46:49], v[208:211], v[232:235], v[46:49]
	v_mfma_f32_16x16x32_bf16 v[10:13], v[208:211], v[236:239], v[10:13]
	v_mfma_f32_16x16x32_bf16 v[14:17], v[208:211], v[240:243], v[14:17]
	s_waitcnt lgkmcnt(0)
	s_barrier
	ds_read_b128 v[212:215], v245 offset:55296
	ds_read_b128 v[196:199], v244 offset:18432
	ds_read_b128 v[216:219], v245 offset:57600
	ds_read_b128 v[220:223], v245 offset:59904
	ds_read_b128 v[224:227], v245 offset:62208
	ds_read_b128 v[200:203], v244 offset:20736
	ds_read_b128 v[204:207], v244 offset:23040
	ds_read_b128 v[208:211], v244 offset:25344
	s_waitcnt lgkmcnt(6)
	v_mfma_f32_16x16x32_bf16 v[50:53], v[196:199], v[212:215], v[50:53]
	ds_read_b128 v[228:231], v245 offset:55360
	s_waitcnt lgkmcnt(6)
	v_mfma_f32_16x16x32_bf16 v[54:57], v[196:199], v[216:219], v[54:57]
	ds_read_b128 v[232:235], v245 offset:57664
	s_waitcnt lgkmcnt(6)
	v_mfma_f32_16x16x32_bf16 v[18:21], v[196:199], v[220:223], v[18:21]
	ds_read_b128 v[236:239], v245 offset:59968
	s_waitcnt lgkmcnt(6)
	v_mfma_f32_16x16x32_bf16 v[22:25], v[196:199], v[224:227], v[22:25]
	ds_read_b128 v[240:243], v245 offset:62272
	ds_read_b128 v[196:199], v244 offset:18496
	s_waitcnt lgkmcnt(7)
	v_mfma_f32_16x16x32_bf16 v[58:61], v[200:203], v[212:215], v[58:61]
	v_mfma_f32_16x16x32_bf16 v[62:65], v[200:203], v[216:219], v[62:65]
	v_mfma_f32_16x16x32_bf16 v[26:29], v[200:203], v[220:223], v[26:29]
	v_mfma_f32_16x16x32_bf16 v[30:33], v[200:203], v[224:227], v[30:33]
	ds_read_b128 v[200:203], v244 offset:20800
	s_waitcnt lgkmcnt(7)
	v_mfma_f32_16x16x32_bf16 v[34:37], v[204:207], v[212:215], v[34:37]
	v_mfma_f32_16x16x32_bf16 v[38:41], v[204:207], v[216:219], v[38:41]
	v_mfma_f32_16x16x32_bf16 v[2:5], v[204:207], v[220:223], v[2:5]
	v_mfma_f32_16x16x32_bf16 v[6:9], v[204:207], v[224:227], v[6:9]
	ds_read_b128 v[204:207], v244 offset:23104
	s_waitcnt lgkmcnt(7)
	v_mfma_f32_16x16x32_bf16 v[42:45], v[208:211], v[212:215], v[42:45]
	v_mfma_f32_16x16x32_bf16 v[46:49], v[208:211], v[216:219], v[46:49]
	v_mfma_f32_16x16x32_bf16 v[10:13], v[208:211], v[220:223], v[10:13]
	v_mfma_f32_16x16x32_bf16 v[14:17], v[208:211], v[224:227], v[14:17]
	ds_read_b128 v[208:211], v244 offset:25408
	s_waitcnt lgkmcnt(3)
	v_mfma_f32_16x16x32_bf16 v[50:53], v[196:199], v[228:231], v[50:53]
	v_mfma_f32_16x16x32_bf16 v[54:57], v[196:199], v[232:235], v[54:57]
	v_mfma_f32_16x16x32_bf16 v[18:21], v[196:199], v[236:239], v[18:21]
	v_mfma_f32_16x16x32_bf16 v[22:25], v[196:199], v[240:243], v[22:25]
	s_waitcnt lgkmcnt(2)
	v_mfma_f32_16x16x32_bf16 v[58:61], v[200:203], v[228:231], v[58:61]
	v_mfma_f32_16x16x32_bf16 v[62:65], v[200:203], v[232:235], v[62:65]
	v_mfma_f32_16x16x32_bf16 v[26:29], v[200:203], v[236:239], v[26:29]
	v_mfma_f32_16x16x32_bf16 v[30:33], v[200:203], v[240:243], v[30:33]
	s_waitcnt lgkmcnt(1)
	v_mfma_f32_16x16x32_bf16 v[34:37], v[204:207], v[228:231], v[34:37]
	v_mfma_f32_16x16x32_bf16 v[38:41], v[204:207], v[232:235], v[38:41]
	v_mfma_f32_16x16x32_bf16 v[2:5], v[204:207], v[236:239], v[2:5]
	v_mfma_f32_16x16x32_bf16 v[6:9], v[204:207], v[240:243], v[6:9]
	s_waitcnt lgkmcnt(0)
	v_mfma_f32_16x16x32_bf16 v[42:45], v[208:211], v[228:231], v[42:45]
	v_mfma_f32_16x16x32_bf16 v[46:49], v[208:211], v[232:235], v[46:49]
	v_mfma_f32_16x16x32_bf16 v[10:13], v[208:211], v[236:239], v[10:13]
	v_mfma_f32_16x16x32_bf16 v[14:17], v[208:211], v[240:243], v[14:17]
	s_lshr_b32 s14, s2, 3
	s_bfe_u32 s13, s2, 0x10002
	s_cmp_lt_i32 s14, 1
	s_mov_b64 s[2:3], -1
	s_waitcnt lgkmcnt(0)
	s_barrier
	s_nop 7
	v_permlane16_swap_b32_e32 v50, v54
	v_permlane16_swap_b32_e32 v51, v55
	v_permlane16_swap_b32_e32 v52, v56
	v_permlane16_swap_b32_e32 v53, v57
	v_permlane16_swap_b32_e32 v58, v62
	v_permlane16_swap_b32_e32 v59, v63
	v_permlane16_swap_b32_e32 v60, v64
	v_permlane16_swap_b32_e32 v61, v65
	v_permlane16_swap_b32_e32 v18, v22
	v_permlane16_swap_b32_e32 v19, v23
	v_permlane16_swap_b32_e32 v20, v24
	v_permlane16_swap_b32_e32 v21, v25
	v_permlane16_swap_b32_e32 v26, v30
	v_permlane16_swap_b32_e32 v27, v31
	v_permlane16_swap_b32_e32 v28, v32
	v_permlane16_swap_b32_e32 v29, v33
	v_permlane16_swap_b32_e32 v34, v38
	v_permlane16_swap_b32_e32 v35, v39
	v_permlane16_swap_b32_e32 v36, v40
	v_permlane16_swap_b32_e32 v37, v41
	v_permlane16_swap_b32_e32 v42, v46
	v_permlane16_swap_b32_e32 v43, v47
	v_permlane16_swap_b32_e32 v44, v48
	v_permlane16_swap_b32_e32 v45, v49
	v_permlane16_swap_b32_e32 v2, v6
	v_permlane16_swap_b32_e32 v3, v7
	v_permlane16_swap_b32_e32 v4, v8
	v_permlane16_swap_b32_e32 v5, v9
	v_permlane16_swap_b32_e32 v10, v14
	v_permlane16_swap_b32_e32 v11, v15
	v_permlane16_swap_b32_e32 v12, v16
	v_permlane16_swap_b32_e32 v13, v17
	v_permlane32_swap_b32_e32 v50, v54
	v_permlane32_swap_b32_e32 v51, v55
	v_permlane32_swap_b32_e32 v52, v56
	v_permlane32_swap_b32_e32 v53, v57
	v_permlane32_swap_b32_e32 v58, v62
	v_permlane32_swap_b32_e32 v59, v63
	v_permlane32_swap_b32_e32 v60, v64
	v_permlane32_swap_b32_e32 v61, v65
	v_permlane32_swap_b32_e32 v18, v22
	v_permlane32_swap_b32_e32 v19, v23
	v_permlane32_swap_b32_e32 v20, v24
	v_permlane32_swap_b32_e32 v21, v25
	v_permlane32_swap_b32_e32 v26, v30
	v_permlane32_swap_b32_e32 v27, v31
	v_permlane32_swap_b32_e32 v28, v32
	v_permlane32_swap_b32_e32 v29, v33
	v_permlane32_swap_b32_e32 v34, v38
	v_permlane32_swap_b32_e32 v35, v39
	v_permlane32_swap_b32_e32 v36, v40
	v_permlane32_swap_b32_e32 v37, v41
	v_permlane32_swap_b32_e32 v42, v46
	v_permlane32_swap_b32_e32 v43, v47
	v_permlane32_swap_b32_e32 v44, v48
	v_permlane32_swap_b32_e32 v45, v49
	v_permlane32_swap_b32_e32 v2, v6
	v_permlane32_swap_b32_e32 v3, v7
	v_permlane32_swap_b32_e32 v4, v8
	v_permlane32_swap_b32_e32 v5, v9
	v_permlane32_swap_b32_e32 v10, v14
	v_permlane32_swap_b32_e32 v11, v15
	v_permlane32_swap_b32_e32 v12, v16
	v_permlane32_swap_b32_e32 v13, v17
	s_cbranch_scc1 .LBB0_755
	s_and_b32 s2, 0xffff, s14
	s_cmp_lg_u32 s2, 1
	s_mov_b64 s[2:3], -1
	s_cbranch_scc0 .LBB0_752
	s_cmp_eq_u32 s13, 0
	s_cselect_b32 s12, 3, 10
	s_mov_b64 s[2:3], 0

.LBB0_1641:
	s_and_b32 s3, s2, 0xffff
	s_mul_i32 s3, s3, 0xaaab
	s_lshr_b32 s3, s3, 18
	s_mul_i32 s10, s3, 6
	s_sub_i32 s2, s2, s10
	s_and_b32 s2, s2, 0xffff
	s_add_i32 s2, s6, s2
	s_lshl_b32 s10, s2, 7
	v_or_b32_e32 v2, s10, v91
	v_lshlrev_b32_e32 v66, 11, v2
	v_lshl_add_u64 v[74:75], v[68:69], 0, v[66:67]
	v_add_lshl_u32 v66, s10, v92, 11
	s_add_i32 s3, s8, s3
	v_lshl_add_u64 v[76:77], v[68:69], 0, v[66:67]
	v_add_lshl_u32 v66, s10, v93, 11
	s_lshl_b32 s11, s3, 7
	v_lshl_add_u64 v[78:79], v[68:69], 0, v[66:67]
	v_add_lshl_u32 v66, s10, v94, 11
	v_lshl_add_u64 v[80:81], v[68:69], 0, v[66:67]
	v_or_b32_e32 v66, s11, v91
	v_lshlrev_b64 v[2:3], 11, v[66:67]
	v_add_u32_e32 v66, s11, v92
	v_lshl_add_u64 v[82:83], v[70:71], 0, v[2:3]
	v_lshlrev_b64 v[2:3], 11, v[66:67]
	v_add_u32_e32 v66, s11, v93
	v_lshl_add_u64 v[84:85], v[70:71], 0, v[2:3]
	v_lshlrev_b64 v[2:3], 11, v[66:67]
	v_add_u32_e32 v66, s11, v94
	v_lshl_add_u64 v[86:87], v[70:71], 0, v[2:3]
	v_lshlrev_b64 v[2:3], 11, v[66:67]
	v_lshl_add_u64 v[88:89], v[70:71], 0, v[2:3]
	global_load_dwordx4 v[2:5], v[74:75], off
	global_load_dwordx4 v[6:9], v[76:77], off
	global_load_dwordx4 v[10:13], v[78:79], off
	global_load_dwordx4 v[14:17], v[80:81], off
	global_load_dwordx4 v[18:21], v[82:83], off
	global_load_dwordx4 v[22:25], v[84:85], off
	global_load_dwordx4 v[26:29], v[86:87], off
	global_load_dwordx4 v[30:33], v[88:89], off
	global_load_dwordx4 v[102:105], v[74:75], off offset:128
	global_load_dwordx4 v[106:109], v[76:77], off offset:128
	global_load_dwordx4 v[110:113], v[78:79], off offset:128
	global_load_dwordx4 v[114:117], v[80:81], off offset:128
	global_load_dwordx4 v[118:121], v[82:83], off offset:128
	global_load_dwordx4 v[122:125], v[84:85], off offset:128
	global_load_dwordx4 v[126:129], v[86:87], off offset:128
	global_load_dwordx4 v[132:135], v[88:89], off offset:128
	s_waitcnt vmcnt(15)
	ds_write_b128 v98, v[2:5]
	s_waitcnt vmcnt(14)
	ds_write_b128 v98, v[6:9] offset:4608
	s_waitcnt vmcnt(13)
	ds_write_b128 v98, v[10:13] offset:9216
	s_waitcnt vmcnt(12)
	ds_write_b128 v98, v[14:17] offset:13824
	s_waitcnt vmcnt(11)
	ds_write_b128 v98, v[18:21] offset:36864
	s_waitcnt vmcnt(10)
	ds_write_b128 v98, v[22:25] offset:41472
	s_waitcnt vmcnt(9)
	ds_write_b128 v98, v[26:29] offset:46080
	s_waitcnt vmcnt(8)
	ds_write_b128 v98, v[30:33] offset:50688
	s_waitcnt lgkmcnt(0)
	s_barrier
	global_load_dwordx4 v[136:139], v[74:75], off offset:256
	global_load_dwordx4 v[140:143], v[76:77], off offset:256
	global_load_dwordx4 v[144:147], v[78:79], off offset:256
	global_load_dwordx4 v[148:151], v[80:81], off offset:256
	global_load_dwordx4 v[152:155], v[82:83], off offset:256
	global_load_dwordx4 v[156:159], v[84:85], off offset:256
	global_load_dwordx4 v[160:163], v[86:87], off offset:256
	global_load_dwordx4 v[164:167], v[88:89], off offset:256
	v_and_b32_e32 v246, 15, v1
	v_add_u32_e32 v246, 4, v246
	v_bfe_u32 v246, v246, 3, 1
	v_bfe_u32 v249, v1, 4, 2
	v_xor_b32_e32 v246, v246, v249
	v_bfe_u32 v249, v1, 5, 1
	v_sub_u32_e32 v246, v246, v249
	v_lshlrev_b32_e32 v246, 4, v246
	v_bfe_u32 v249, v1, 4, 1
	v_mul_u32_u24_e32 v249, 0x900, v249
	v_sub_u32_e32 v246, v246, v249
	v_add_u32_e32 v244, v246, v96
	v_add_u32_e32 v245, v246, v97
	ds_read_b128 v[212:215], v245 offset:36864
	ds_read_b128 v[196:199], v244
	ds_read_b128 v[216:219], v245 offset:39168
	ds_read_b128 v[220:223], v245 offset:41472
	ds_read_b128 v[224:227], v245 offset:43776
	ds_read_b128 v[200:203], v244 offset:2304
	ds_read_b128 v[204:207], v244 offset:4608
	ds_read_b128 v[208:211], v244 offset:6912
	s_waitcnt lgkmcnt(6)
	v_mfma_f32_16x16x32_bf16 v[50:53], v[196:199], v[212:215], 0
	ds_read_b128 v[228:231], v245 offset:36928
	s_waitcnt lgkmcnt(6)
	v_mfma_f32_16x16x32_bf16 v[54:57], v[196:199], v[216:219], 0
	ds_read_b128 v[232:235], v245 offset:39232
	s_waitcnt lgkmcnt(6)
	v_mfma_f32_16x16x32_bf16 v[18:21], v[196:199], v[220:223], 0
	ds_read_b128 v[236:239], v245 offset:41536
	s_waitcnt lgkmcnt(6)
	v_mfma_f32_16x16x32_bf16 v[22:25], v[196:199], v[224:227], 0
	ds_read_b128 v[240:243], v245 offset:43840
	ds_read_b128 v[196:199], v244 offset:64
	s_waitcnt lgkmcnt(7)
	v_mfma_f32_16x16x32_bf16 v[58:61], v[200:203], v[212:215], 0
	v_mfma_f32_16x16x32_bf16 v[62:65], v[200:203], v[216:219], 0
	v_mfma_f32_16x16x32_bf16 v[26:29], v[200:203], v[220:223], 0
	v_mfma_f32_16x16x32_bf16 v[30:33], v[200:203], v[224:227], 0
	ds_read_b128 v[200:203], v244 offset:2368
	s_waitcnt lgkmcnt(7)
	v_mfma_f32_16x16x32_bf16 v[34:37], v[204:207], v[212:215], 0
	v_mfma_f32_16x16x32_bf16 v[38:41], v[204:207], v[216:219], 0
	v_mfma_f32_16x16x32_bf16 v[2:5], v[204:207], v[220:223], 0
	v_mfma_f32_16x16x32_bf16 v[6:9], v[204:207], v[224:227], 0
	ds_read_b128 v[204:207], v244 offset:4672
	s_waitcnt vmcnt(15)
	ds_write_b128 v98, v[102:105] offset:18432
	s_waitcnt vmcnt(14)
	ds_write_b128 v98, v[106:109] offset:23040
	s_waitcnt lgkmcnt(9)
	v_mfma_f32_16x16x32_bf16 v[42:45], v[208:211], v[212:215], 0
	v_mfma_f32_16x16x32_bf16 v[46:49], v[208:211], v[216:219], 0
	v_mfma_f32_16x16x32_bf16 v[10:13], v[208:211], v[220:223], 0
	v_mfma_f32_16x16x32_bf16 v[14:17], v[208:211], v[224:227], 0
	ds_read_b128 v[208:211], v244 offset:6976
	s_waitcnt vmcnt(13)
	ds_write_b128 v98, v[110:113] offset:27648
	s_waitcnt vmcnt(12)
	ds_write_b128 v98, v[114:117] offset:32256
	s_waitcnt lgkmcnt(7)
	v_mfma_f32_16x16x32_bf16 v[50:53], v[196:199], v[228:231], v[50:53]
	v_mfma_f32_16x16x32_bf16 v[54:57], v[196:199], v[232:235], v[54:57]
	v_mfma_f32_16x16x32_bf16 v[18:21], v[196:199], v[236:239], v[18:21]
	v_mfma_f32_16x16x32_bf16 v[22:25], v[196:199], v[240:243], v[22:25]
	s_waitcnt vmcnt(11)
	ds_write_b128 v98, v[118:121] offset:55296
	s_waitcnt vmcnt(10)
	ds_write_b128 v98, v[122:125] offset:59904
	s_waitcnt lgkmcnt(8)
	v_mfma_f32_16x16x32_bf16 v[58:61], v[200:203], v[228:231], v[58:61]
	v_mfma_f32_16x16x32_bf16 v[62:65], v[200:203], v[232:235], v[62:65]
	v_mfma_f32_16x16x32_bf16 v[26:29], v[200:203], v[236:239], v[26:29]
	v_mfma_f32_16x16x32_bf16 v[30:33], v[200:203], v[240:243], v[30:33]
	s_waitcnt vmcnt(9)
	ds_write_b128 v98, v[126:129] offset:64512
	s_waitcnt vmcnt(8)
	ds_write_b128 v99, v[132:135] offset:32256
	s_waitcnt lgkmcnt(9)
	v_mfma_f32_16x16x32_bf16 v[34:37], v[204:207], v[228:231], v[34:37]
	v_mfma_f32_16x16x32_bf16 v[38:41], v[204:207], v[232:235], v[38:41]
	v_mfma_f32_16x16x32_bf16 v[2:5], v[204:207], v[236:239], v[2:5]
	v_mfma_f32_16x16x32_bf16 v[6:9], v[204:207], v[240:243], v[6:9]
	s_waitcnt lgkmcnt(6)
	v_mfma_f32_16x16x32_bf16 v[42:45], v[208:211], v[228:231], v[42:45]
	v_mfma_f32_16x16x32_bf16 v[46:49], v[208:211], v[232:235], v[46:49]
	v_mfma_f32_16x16x32_bf16 v[10:13], v[208:211], v[236:239], v[10:13]
	v_mfma_f32_16x16x32_bf16 v[14:17], v[208:211], v[240:243], v[14:17]
	s_waitcnt lgkmcnt(0)
	s_barrier
	global_load_dwordx4 v[102:105], v[74:75], off offset:384
	global_load_dwordx4 v[106:109], v[76:77], off offset:384
	global_load_dwordx4 v[110:113], v[78:79], off offset:384
	global_load_dwordx4 v[114:117], v[80:81], off offset:384
	global_load_dwordx4 v[118:121], v[82:83], off offset:384
	global_load_dwordx4 v[122:125], v[84:85], off offset:384
	global_load_dwordx4 v[126:129], v[86:87], off offset:384
	global_load_dwordx4 v[132:135], v[88:89], off offset:384
	ds_read_b128 v[212:215], v245 offset:55296
	ds_read_b128 v[196:199], v244 offset:18432
	ds_read_b128 v[216:219], v245 offset:57600
	ds_read_b128 v[220:223], v245 offset:59904
	ds_read_b128 v[224:227], v245 offset:62208
	ds_read_b128 v[200:203], v244 offset:20736
	ds_read_b128 v[204:207], v244 offset:23040
	ds_read_b128 v[208:211], v244 offset:25344
	s_waitcnt lgkmcnt(6)
	v_mfma_f32_16x16x32_bf16 v[50:53], v[196:199], v[212:215], v[50:53]
	ds_read_b128 v[228:231], v245 offset:55360
	s_waitcnt lgkmcnt(6)
	v_mfma_f32_16x16x32_bf16 v[54:57], v[196:199], v[216:219], v[54:57]
	ds_read_b128 v[232:235], v245 offset:57664
	s_waitcnt lgkmcnt(6)
	v_mfma_f32_16x16x32_bf16 v[18:21], v[196:199], v[220:223], v[18:21]
	ds_read_b128 v[236:239], v245 offset:59968
	s_waitcnt lgkmcnt(6)
	v_mfma_f32_16x16x32_bf16 v[22:25], v[196:199], v[224:227], v[22:25]
	ds_read_b128 v[240:243], v245 offset:62272
	ds_read_b128 v[196:199], v244 offset:18496
	s_waitcnt lgkmcnt(7)
	v_mfma_f32_16x16x32_bf16 v[58:61], v[200:203], v[212:215], v[58:61]
	v_mfma_f32_16x16x32_bf16 v[62:65], v[200:203], v[216:219], v[62:65]
	v_mfma_f32_16x16x32_bf16 v[26:29], v[200:203], v[220:223], v[26:29]
	v_mfma_f32_16x16x32_bf16 v[30:33], v[200:203], v[224:227], v[30:33]
	ds_read_b128 v[200:203], v244 offset:20800
	s_waitcnt lgkmcnt(7)
	v_mfma_f32_16x16x32_bf16 v[34:37], v[204:207], v[212:215], v[34:37]
	v_mfma_f32_16x16x32_bf16 v[38:41], v[204:207], v[216:219], v[38:41]
	v_mfma_f32_16x16x32_bf16 v[2:5], v[204:207], v[220:223], v[2:5]
	v_mfma_f32_16x16x32_bf16 v[6:9], v[204:207], v[224:227], v[6:9]
	ds_read_b128 v[204:207], v244 offset:23104
	s_waitcnt vmcnt(15)
	ds_write_b128 v98, v[136:139]
	s_waitcnt vmcnt(14)
	ds_write_b128 v98, v[140:143] offset:4608
	s_waitcnt lgkmcnt(9)
	v_mfma_f32_16x16x32_bf16 v[42:45], v[208:211], v[212:215], v[42:45]
	v_mfma_f32_16x16x32_bf16 v[46:49], v[208:211], v[216:219], v[46:49]
	v_mfma_f32_16x16x32_bf16 v[10:13], v[208:211], v[220:223], v[10:13]
	v_mfma_f32_16x16x32_bf16 v[14:17], v[208:211], v[224:227], v[14:17]
	ds_read_b128 v[208:211], v244 offset:25408
	s_waitcnt vmcnt(13)
	ds_write_b128 v98, v[144:147] offset:9216
	s_waitcnt vmcnt(12)
	ds_write_b128 v98, v[148:151] offset:13824
	s_waitcnt lgkmcnt(7)
	v_mfma_f32_16x16x32_bf16 v[50:53], v[196:199], v[228:231], v[50:53]
	v_mfma_f32_16x16x32_bf16 v[54:57], v[196:199], v[232:235], v[54:57]
	v_mfma_f32_16x16x32_bf16 v[18:21], v[196:199], v[236:239], v[18:21]
	v_mfma_f32_16x16x32_bf16 v[22:25], v[196:199], v[240:243], v[22:25]
	s_waitcnt vmcnt(11)
	ds_write_b128 v98, v[152:155] offset:36864
	s_waitcnt vmcnt(10)
	ds_write_b128 v98, v[156:159] offset:41472
	s_waitcnt lgkmcnt(8)
	v_mfma_f32_16x16x32_bf16 v[58:61], v[200:203], v[228:231], v[58:61]
	v_mfma_f32_16x16x32_bf16 v[62:65], v[200:203], v[232:235], v[62:65]
	v_mfma_f32_16x16x32_bf16 v[26:29], v[200:203], v[236:239], v[26:29]
	v_mfma_f32_16x16x32_bf16 v[30:33], v[200:203], v[240:243], v[30:33]
	s_waitcnt vmcnt(9)
	ds_write_b128 v98, v[160:163] offset:46080
	s_waitcnt vmcnt(8)
	ds_write_b128 v98, v[164:167] offset:50688
	s_waitcnt lgkmcnt(9)
	v_mfma_f32_16x16x32_bf16 v[34:37], v[204:207], v[228:231], v[34:37]
	v_mfma_f32_16x16x32_bf16 v[38:41], v[204:207], v[232:235], v[38:41]
	v_mfma_f32_16x16x32_bf16 v[2:5], v[204:207], v[236:239], v[2:5]
	v_mfma_f32_16x16x32_bf16 v[6:9], v[204:207], v[240:243], v[6:9]
	s_waitcnt lgkmcnt(6)
	v_mfma_f32_16x16x32_bf16 v[42:45], v[208:211], v[228:231], v[42:45]
	v_mfma_f32_16x16x32_bf16 v[46:49], v[208:211], v[232:235], v[46:49]
	v_mfma_f32_16x16x32_bf16 v[10:13], v[208:211], v[236:239], v[10:13]
	v_mfma_f32_16x16x32_bf16 v[14:17], v[208:211], v[240:243], v[14:17]
	s_waitcnt lgkmcnt(0)
	s_barrier
	global_load_dwordx4 v[136:139], v[74:75], off offset:512
	global_load_dwordx4 v[140:143], v[76:77], off offset:512
	global_load_dwordx4 v[144:147], v[78:79], off offset:512
	global_load_dwordx4 v[148:151], v[80:81], off offset:512
	global_load_dwordx4 v[152:155], v[82:83], off offset:512
	global_load_dwordx4 v[156:159], v[84:85], off offset:512
	global_load_dwordx4 v[160:163], v[86:87], off offset:512
	global_load_dwordx4 v[164:167], v[88:89], off offset:512
	ds_read_b128 v[212:215], v245 offset:36864
	ds_read_b128 v[196:199], v244
	ds_read_b128 v[216:219], v245 offset:39168
	ds_read_b128 v[220:223], v245 offset:41472
	ds_read_b128 v[224:227], v245 offset:43776
	ds_read_b128 v[200:203], v244 offset:2304
	ds_read_b128 v[204:207], v244 offset:4608
	ds_read_b128 v[208:211], v244 offset:6912
	s_waitcnt lgkmcnt(6)
	v_mfma_f32_16x16x32_bf16 v[50:53], v[196:199], v[212:215], v[50:53]
	ds_read_b128 v[228:231], v245 offset:36928
	s_waitcnt lgkmcnt(6)
	v_mfma_f32_16x16x32_bf16 v[54:57], v[196:199], v[216:219], v[54:57]
	ds_read_b128 v[232:235], v245 offset:39232
	s_waitcnt lgkmcnt(6)
	v_mfma_f32_16x16x32_bf16 v[18:21], v[196:199], v[220:223], v[18:21]
	ds_read_b128 v[236:239], v245 offset:41536
	s_waitcnt lgkmcnt(6)
	v_mfma_f32_16x16x32_bf16 v[22:25], v[196:199], v[224:227], v[22:25]
	ds_read_b128 v[240:243], v245 offset:43840
	ds_read_b128 v[196:199], v244 offset:64
	s_waitcnt lgkmcnt(7)
	v_mfma_f32_16x16x32_bf16 v[58:61], v[200:203], v[212:215], v[58:61]
	v_mfma_f32_16x16x32_bf16 v[62:65], v[200:203], v[216:219], v[62:65]
	v_mfma_f32_16x16x32_bf16 v[26:29], v[200:203], v[220:223], v[26:29]
	v_mfma_f32_16x16x32_bf16 v[30:33], v[200:203], v[224:227], v[30:33]
	ds_read_b128 v[200:203], v244 offset:2368
	s_waitcnt lgkmcnt(7)
	v_mfma_f32_16x16x32_bf16 v[34:37], v[204:207], v[212:215], v[34:37]
	v_mfma_f32_16x16x32_bf16 v[38:41], v[204:207], v[216:219], v[38:41]
	v_mfma_f32_16x16x32_bf16 v[2:5], v[204:207], v[220:223], v[2:5]
	v_mfma_f32_16x16x32_bf16 v[6:9], v[204:207], v[224:227], v[6:9]
	ds_read_b128 v[204:207], v244 offset:4672
	s_waitcnt vmcnt(15)
	ds_write_b128 v98, v[102:105] offset:18432
	s_waitcnt vmcnt(14)
	ds_write_b128 v98, v[106:109] offset:23040
	s_waitcnt lgkmcnt(9)
	v_mfma_f32_16x16x32_bf16 v[42:45], v[208:211], v[212:215], v[42:45]
	v_mfma_f32_16x16x32_bf16 v[46:49], v[208:211], v[216:219], v[46:49]
	v_mfma_f32_16x16x32_bf16 v[10:13], v[208:211], v[220:223], v[10:13]
	v_mfma_f32_16x16x32_bf16 v[14:17], v[208:211], v[224:227], v[14:17]
	ds_read_b128 v[208:211], v244 offset:6976
	s_waitcnt vmcnt(13)
	ds_write_b128 v98, v[110:113] offset:27648
	s_waitcnt vmcnt(12)
	ds_write_b128 v98, v[114:117] offset:32256
	s_waitcnt lgkmcnt(7)
	v_mfma_f32_16x16x32_bf16 v[50:53], v[196:199], v[228:231], v[50:53]
	v_mfma_f32_16x16x32_bf16 v[54:57], v[196:199], v[232:235], v[54:57]
	v_mfma_f32_16x16x32_bf16 v[18:21], v[196:199], v[236:239], v[18:21]
	v_mfma_f32_16x16x32_bf16 v[22:25], v[196:199], v[240:243], v[22:25]
	s_waitcnt vmcnt(11)
	ds_write_b128 v98, v[118:121] offset:55296
	s_waitcnt vmcnt(10)
	ds_write_b128 v98, v[122:125] offset:59904
	s_waitcnt lgkmcnt(8)
	v_mfma_f32_16x16x32_bf16 v[58:61], v[200:203], v[228:231], v[58:61]
	v_mfma_f32_16x16x32_bf16 v[62:65], v[200:203], v[232:235], v[62:65]
	v_mfma_f32_16x16x32_bf16 v[26:29], v[200:203], v[236:239], v[26:29]
	v_mfma_f32_16x16x32_bf16 v[30:33], v[200:203], v[240:243], v[30:33]
	s_waitcnt vmcnt(9)
	ds_write_b128 v98, v[126:129] offset:64512
	s_waitcnt vmcnt(8)
	ds_write_b128 v99, v[132:135] offset:32256
	s_waitcnt lgkmcnt(9)
	v_mfma_f32_16x16x32_bf16 v[34:37], v[204:207], v[228:231], v[34:37]
	v_mfma_f32_16x16x32_bf16 v[38:41], v[204:207], v[232:235], v[38:41]
	v_mfma_f32_16x16x32_bf16 v[2:5], v[204:207], v[236:239], v[2:5]
	v_mfma_f32_16x16x32_bf16 v[6:9], v[204:207], v[240:243], v[6:9]
	s_waitcnt lgkmcnt(6)
	v_mfma_f32_16x16x32_bf16 v[42:45], v[208:211], v[228:231], v[42:45]
	v_mfma_f32_16x16x32_bf16 v[46:49], v[208:211], v[232:235], v[46:49]
	v_mfma_f32_16x16x32_bf16 v[10:13], v[208:211], v[236:239], v[10:13]
	v_mfma_f32_16x16x32_bf16 v[14:17], v[208:211], v[240:243], v[14:17]
	s_waitcnt lgkmcnt(0)
	s_barrier
	global_load_dwordx4 v[102:105], v[74:75], off offset:640
	global_load_dwordx4 v[106:109], v[76:77], off offset:640
	global_load_dwordx4 v[110:113], v[78:79], off offset:640
	global_load_dwordx4 v[114:117], v[80:81], off offset:640
	global_load_dwordx4 v[118:121], v[82:83], off offset:640
	global_load_dwordx4 v[122:125], v[84:85], off offset:640
	global_load_dwordx4 v[126:129], v[86:87], off offset:640
	global_load_dwordx4 v[132:135], v[88:89], off offset:640
	ds_read_b128 v[212:215], v245 offset:55296
	ds_read_b128 v[196:199], v244 offset:18432
	ds_read_b128 v[216:219], v245 offset:57600
	ds_read_b128 v[220:223], v245 offset:59904
	ds_read_b128 v[224:227], v245 offset:62208
	ds_read_b128 v[200:203], v244 offset:20736
	ds_read_b128 v[204:207], v244 offset:23040
	ds_read_b128 v[208:211], v244 offset:25344
	s_waitcnt lgkmcnt(6)
	v_mfma_f32_16x16x32_bf16 v[50:53], v[196:199], v[212:215], v[50:53]
	ds_read_b128 v[228:231], v245 offset:55360
	s_waitcnt lgkmcnt(6)
	v_mfma_f32_16x16x32_bf16 v[54:57], v[196:199], v[216:219], v[54:57]
	ds_read_b128 v[232:235], v245 offset:57664
	s_waitcnt lgkmcnt(6)
	v_mfma_f32_16x16x32_bf16 v[18:21], v[196:199], v[220:223], v[18:21]
	ds_read_b128 v[236:239], v245 offset:59968
	s_waitcnt lgkmcnt(6)
	v_mfma_f32_16x16x32_bf16 v[22:25], v[196:199], v[224:227], v[22:25]
	ds_read_b128 v[240:243], v245 offset:62272
	ds_read_b128 v[196:199], v244 offset:18496
	s_waitcnt lgkmcnt(7)
	v_mfma_f32_16x16x32_bf16 v[58:61], v[200:203], v[212:215], v[58:61]
	v_mfma_f32_16x16x32_bf16 v[62:65], v[200:203], v[216:219], v[62:65]
	v_mfma_f32_16x16x32_bf16 v[26:29], v[200:203], v[220:223], v[26:29]
	v_mfma_f32_16x16x32_bf16 v[30:33], v[200:203], v[224:227], v[30:33]
	ds_read_b128 v[200:203], v244 offset:20800
	s_waitcnt lgkmcnt(7)
	v_mfma_f32_16x16x32_bf16 v[34:37], v[204:207], v[212:215], v[34:37]
	v_mfma_f32_16x16x32_bf16 v[38:41], v[204:207], v[216:219], v[38:41]
	v_mfma_f32_16x16x32_bf16 v[2:5], v[204:207], v[220:223], v[2:5]
	v_mfma_f32_16x16x32_bf16 v[6:9], v[204:207], v[224:227], v[6:9]
	ds_read_b128 v[204:207], v244 offset:23104
	s_waitcnt vmcnt(15)
	ds_write_b128 v98, v[136:139]
	s_waitcnt vmcnt(14)
	ds_write_b128 v98, v[140:143] offset:4608
	s_waitcnt lgkmcnt(9)
	v_mfma_f32_16x16x32_bf16 v[42:45], v[208:211], v[212:215], v[42:45]
	v_mfma_f32_16x16x32_bf16 v[46:49], v[208:211], v[216:219], v[46:49]
	v_mfma_f32_16x16x32_bf16 v[10:13], v[208:211], v[220:223], v[10:13]
	v_mfma_f32_16x16x32_bf16 v[14:17], v[208:211], v[224:227], v[14:17]
	ds_read_b128 v[208:211], v244 offset:25408
	s_waitcnt vmcnt(13)
	ds_write_b128 v98, v[144:147] offset:9216
	s_waitcnt vmcnt(12)
	ds_write_b128 v98, v[148:151] offset:13824
	s_waitcnt lgkmcnt(7)
	v_mfma_f32_16x16x32_bf16 v[50:53], v[196:199], v[228:231], v[50:53]
	v_mfma_f32_16x16x32_bf16 v[54:57], v[196:199], v[232:235], v[54:57]
	v_mfma_f32_16x16x32_bf16 v[18:21], v[196:199], v[236:239], v[18:21]
	v_mfma_f32_16x16x32_bf16 v[22:25], v[196:199], v[240:243], v[22:25]
	s_waitcnt vmcnt(11)
	ds_write_b128 v98, v[152:155] offset:36864
	s_waitcnt vmcnt(10)
	ds_write_b128 v98, v[156:159] offset:41472
	s_waitcnt lgkmcnt(8)
	v_mfma_f32_16x16x32_bf16 v[58:61], v[200:203], v[228:231], v[58:61]
	v_mfma_f32_16x16x32_bf16 v[62:65], v[200:203], v[232:235], v[62:65]
	v_mfma_f32_16x16x32_bf16 v[26:29], v[200:203], v[236:239], v[26:29]
	v_mfma_f32_16x16x32_bf16 v[30:33], v[200:203], v[240:243], v[30:33]
	s_waitcnt vmcnt(9)
	ds_write_b128 v98, v[160:163] offset:46080
	s_waitcnt vmcnt(8)
	ds_write_b128 v98, v[164:167] offset:50688
	s_waitcnt lgkmcnt(9)
	v_mfma_f32_16x16x32_bf16 v[34:37], v[204:207], v[228:231], v[34:37]
	v_mfma_f32_16x16x32_bf16 v[38:41], v[204:207], v[232:235], v[38:41]
	v_mfma_f32_16x16x32_bf16 v[2:5], v[204:207], v[236:239], v[2:5]
	v_mfma_f32_16x16x32_bf16 v[6:9], v[204:207], v[240:243], v[6:9]
	s_waitcnt lgkmcnt(6)
	v_mfma_f32_16x16x32_bf16 v[42:45], v[208:211], v[228:231], v[42:45]
	v_mfma_f32_16x16x32_bf16 v[46:49], v[208:211], v[232:235], v[46:49]
	v_mfma_f32_16x16x32_bf16 v[10:13], v[208:211], v[236:239], v[10:13]
	v_mfma_f32_16x16x32_bf16 v[14:17], v[208:211], v[240:243], v[14:17]
	s_waitcnt lgkmcnt(0)
	s_barrier
	global_load_dwordx4 v[136:139], v[74:75], off offset:768
	global_load_dwordx4 v[140:143], v[76:77], off offset:768
	global_load_dwordx4 v[144:147], v[78:79], off offset:768
	global_load_dwordx4 v[148:151], v[80:81], off offset:768
	global_load_dwordx4 v[152:155], v[82:83], off offset:768
	global_load_dwordx4 v[156:159], v[84:85], off offset:768
	global_load_dwordx4 v[160:163], v[86:87], off offset:768
	global_load_dwordx4 v[164:167], v[88:89], off offset:768
	ds_read_b128 v[212:215], v245 offset:36864
	ds_read_b128 v[196:199], v244
	ds_read_b128 v[216:219], v245 offset:39168
	ds_read_b128 v[220:223], v245 offset:41472
	ds_read_b128 v[224:227], v245 offset:43776
	ds_read_b128 v[200:203], v244 offset:2304
	ds_read_b128 v[204:207], v244 offset:4608
	ds_read_b128 v[208:211], v244 offset:6912
	s_waitcnt lgkmcnt(6)
	v_mfma_f32_16x16x32_bf16 v[50:53], v[196:199], v[212:215], v[50:53]
	ds_read_b128 v[228:231], v245 offset:36928
	s_waitcnt lgkmcnt(6)
	v_mfma_f32_16x16x32_bf16 v[54:57], v[196:199], v[216:219], v[54:57]
	ds_read_b128 v[232:235], v245 offset:39232
	s_waitcnt lgkmcnt(6)
	v_mfma_f32_16x16x32_bf16 v[18:21], v[196:199], v[220:223], v[18:21]
	ds_read_b128 v[236:239], v245 offset:41536
	s_waitcnt lgkmcnt(6)
	v_mfma_f32_16x16x32_bf16 v[22:25], v[196:199], v[224:227], v[22:25]
	ds_read_b128 v[240:243], v245 offset:43840
	ds_read_b128 v[196:199], v244 offset:64
	s_waitcnt lgkmcnt(7)
	v_mfma_f32_16x16x32_bf16 v[58:61], v[200:203], v[212:215], v[58:61]
	v_mfma_f32_16x16x32_bf16 v[62:65], v[200:203], v[216:219], v[62:65]
	v_mfma_f32_16x16x32_bf16 v[26:29], v[200:203], v[220:223], v[26:29]
	v_mfma_f32_16x16x32_bf16 v[30:33], v[200:203], v[224:227], v[30:33]
	ds_read_b128 v[200:203], v244 offset:2368
	s_waitcnt lgkmcnt(7)
	v_mfma_f32_16x16x32_bf16 v[34:37], v[204:207], v[212:215], v[34:37]
	v_mfma_f32_16x16x32_bf16 v[38:41], v[204:207], v[216:219], v[38:41]
	v_mfma_f32_16x16x32_bf16 v[2:5], v[204:207], v[220:223], v[2:5]
	v_mfma_f32_16x16x32_bf16 v[6:9], v[204:207], v[224:227], v[6:9]
	ds_read_b128 v[204:207], v244 offset:4672
	s_waitcnt vmcnt(15)
	ds_write_b128 v98, v[102:105] offset:18432
	s_waitcnt vmcnt(14)
	ds_write_b128 v98, v[106:109] offset:23040
	s_waitcnt lgkmcnt(9)
	v_mfma_f32_16x16x32_bf16 v[42:45], v[208:211], v[212:215], v[42:45]
	v_mfma_f32_16x16x32_bf16 v[46:49], v[208:211], v[216:219], v[46:49]
	v_mfma_f32_16x16x32_bf16 v[10:13], v[208:211], v[220:223], v[10:13]
	v_mfma_f32_16x16x32_bf16 v[14:17], v[208:211], v[224:227], v[14:17]
	ds_read_b128 v[208:211], v244 offset:6976
	s_waitcnt vmcnt(13)
	ds_write_b128 v98, v[110:113] offset:27648
	s_waitcnt vmcnt(12)
	ds_write_b128 v98, v[114:117] offset:32256
	s_waitcnt lgkmcnt(7)
	v_mfma_f32_16x16x32_bf16 v[50:53], v[196:199], v[228:231], v[50:53]
	v_mfma_f32_16x16x32_bf16 v[54:57], v[196:199], v[232:235], v[54:57]
	v_mfma_f32_16x16x32_bf16 v[18:21], v[196:199], v[236:239], v[18:21]
	v_mfma_f32_16x16x32_bf16 v[22:25], v[196:199], v[240:243], v[22:25]
	s_waitcnt vmcnt(11)
	ds_write_b128 v98, v[118:121] offset:55296
	s_waitcnt vmcnt(10)
	ds_write_b128 v98, v[122:125] offset:59904
	s_waitcnt lgkmcnt(8)
	v_mfma_f32_16x16x32_bf16 v[58:61], v[200:203], v[228:231], v[58:61]
	v_mfma_f32_16x16x32_bf16 v[62:65], v[200:203], v[232:235], v[62:65]
	v_mfma_f32_16x16x32_bf16 v[26:29], v[200:203], v[236:239], v[26:29]
	v_mfma_f32_16x16x32_bf16 v[30:33], v[200:203], v[240:243], v[30:33]
	s_waitcnt vmcnt(9)
	ds_write_b128 v98, v[126:129] offset:64512
	s_waitcnt vmcnt(8)
	ds_write_b128 v99, v[132:135] offset:32256
	s_waitcnt lgkmcnt(9)
	v_mfma_f32_16x16x32_bf16 v[34:37], v[204:207], v[228:231], v[34:37]
	v_mfma_f32_16x16x32_bf16 v[38:41], v[204:207], v[232:235], v[38:41]
	v_mfma_f32_16x16x32_bf16 v[2:5], v[204:207], v[236:239], v[2:5]
	v_mfma_f32_16x16x32_bf16 v[6:9], v[204:207], v[240:243], v[6:9]
	s_waitcnt lgkmcnt(6)
	v_mfma_f32_16x16x32_bf16 v[42:45], v[208:211], v[228:231], v[42:45]
	v_mfma_f32_16x16x32_bf16 v[46:49], v[208:211], v[232:235], v[46:49]
	v_mfma_f32_16x16x32_bf16 v[10:13], v[208:211], v[236:239], v[10:13]
	v_mfma_f32_16x16x32_bf16 v[14:17], v[208:211], v[240:243], v[14:17]
	s_waitcnt lgkmcnt(0)
	s_barrier
	global_load_dwordx4 v[102:105], v[74:75], off offset:896
	global_load_dwordx4 v[106:109], v[76:77], off offset:896
	global_load_dwordx4 v[110:113], v[78:79], off offset:896
	global_load_dwordx4 v[114:117], v[80:81], off offset:896
	global_load_dwordx4 v[118:121], v[82:83], off offset:896
	global_load_dwordx4 v[122:125], v[84:85], off offset:896
	global_load_dwordx4 v[126:129], v[86:87], off offset:896
	global_load_dwordx4 v[132:135], v[88:89], off offset:896
	ds_read_b128 v[212:215], v245 offset:55296
	ds_read_b128 v[196:199], v244 offset:18432
	ds_read_b128 v[216:219], v245 offset:57600
	ds_read_b128 v[220:223], v245 offset:59904
	ds_read_b128 v[224:227], v245 offset:62208
	ds_read_b128 v[200:203], v244 offset:20736
	ds_read_b128 v[204:207], v244 offset:23040
	ds_read_b128 v[208:211], v244 offset:25344
	s_waitcnt lgkmcnt(6)
	v_mfma_f32_16x16x32_bf16 v[50:53], v[196:199], v[212:215], v[50:53]
	ds_read_b128 v[228:231], v245 offset:55360
	s_waitcnt lgkmcnt(6)
	v_mfma_f32_16x16x32_bf16 v[54:57], v[196:199], v[216:219], v[54:57]
	ds_read_b128 v[232:235], v245 offset:57664
	s_waitcnt lgkmcnt(6)
	v_mfma_f32_16x16x32_bf16 v[18:21], v[196:199], v[220:223], v[18:21]
	ds_read_b128 v[236:239], v245 offset:59968
	s_waitcnt lgkmcnt(6)
	v_mfma_f32_16x16x32_bf16 v[22:25], v[196:199], v[224:227], v[22:25]
	ds_read_b128 v[240:243], v245 offset:62272
	ds_read_b128 v[196:199], v244 offset:18496
	s_waitcnt lgkmcnt(7)
	v_mfma_f32_16x16x32_bf16 v[58:61], v[200:203], v[212:215], v[58:61]
	v_mfma_f32_16x16x32_bf16 v[62:65], v[200:203], v[216:219], v[62:65]
	v_mfma_f32_16x16x32_bf16 v[26:29], v[200:203], v[220:223], v[26:29]
	v_mfma_f32_16x16x32_bf16 v[30:33], v[200:203], v[224:227], v[30:33]
	ds_read_b128 v[200:203], v244 offset:20800
	s_waitcnt lgkmcnt(7)
	v_mfma_f32_16x16x32_bf16 v[34:37], v[204:207], v[212:215], v[34:37]
	v_mfma_f32_16x16x32_bf16 v[38:41], v[204:207], v[216:219], v[38:41]
	v_mfma_f32_16x16x32_bf16 v[2:5], v[204:207], v[220:223], v[2:5]
	v_mfma_f32_16x16x32_bf16 v[6:9], v[204:207], v[224:227], v[6:9]
	ds_read_b128 v[204:207], v244 offset:23104
	s_waitcnt vmcnt(15)
	ds_write_b128 v98, v[136:139]
	s_waitcnt vmcnt(14)
	ds_write_b128 v98, v[140:143] offset:4608
	s_waitcnt lgkmcnt(9)
	v_mfma_f32_16x16x32_bf16 v[42:45], v[208:211], v[212:215], v[42:45]
	v_mfma_f32_16x16x32_bf16 v[46:49], v[208:211], v[216:219], v[46:49]
	v_mfma_f32_16x16x32_bf16 v[10:13], v[208:211], v[220:223], v[10:13]
	v_mfma_f32_16x16x32_bf16 v[14:17], v[208:211], v[224:227], v[14:17]
	ds_read_b128 v[208:211], v244 offset:25408
	s_waitcnt vmcnt(13)
	ds_write_b128 v98, v[144:147] offset:9216
	s_waitcnt vmcnt(12)
	ds_write_b128 v98, v[148:151] offset:13824
	s_waitcnt lgkmcnt(7)
	v_mfma_f32_16x16x32_bf16 v[50:53], v[196:199], v[228:231], v[50:53]
	v_mfma_f32_16x16x32_bf16 v[54:57], v[196:199], v[232:235], v[54:57]
	v_mfma_f32_16x16x32_bf16 v[18:21], v[196:199], v[236:239], v[18:21]
	v_mfma_f32_16x16x32_bf16 v[22:25], v[196:199], v[240:243], v[22:25]
	s_waitcnt vmcnt(11)
	ds_write_b128 v98, v[152:155] offset:36864
	s_waitcnt vmcnt(10)
	ds_write_b128 v98, v[156:159] offset:41472
	s_waitcnt lgkmcnt(8)
	v_mfma_f32_16x16x32_bf16 v[58:61], v[200:203], v[228:231], v[58:61]
	v_mfma_f32_16x16x32_bf16 v[62:65], v[200:203], v[232:235], v[62:65]
	v_mfma_f32_16x16x32_bf16 v[26:29], v[200:203], v[236:239], v[26:29]
	v_mfma_f32_16x16x32_bf16 v[30:33], v[200:203], v[240:243], v[30:33]
	s_waitcnt vmcnt(9)
	ds_write_b128 v98, v[160:163] offset:46080
	s_waitcnt vmcnt(8)
	ds_write_b128 v98, v[164:167] offset:50688
	s_waitcnt lgkmcnt(9)
	v_mfma_f32_16x16x32_bf16 v[34:37], v[204:207], v[228:231], v[34:37]
	v_mfma_f32_16x16x32_bf16 v[38:41], v[204:207], v[232:235], v[38:41]
	v_mfma_f32_16x16x32_bf16 v[2:5], v[204:207], v[236:239], v[2:5]
	v_mfma_f32_16x16x32_bf16 v[6:9], v[204:207], v[240:243], v[6:9]
	s_waitcnt lgkmcnt(6)
	v_mfma_f32_16x16x32_bf16 v[42:45], v[208:211], v[228:231], v[42:45]
	v_mfma_f32_16x16x32_bf16 v[46:49], v[208:211], v[232:235], v[46:49]
	v_mfma_f32_16x16x32_bf16 v[10:13], v[208:211], v[236:239], v[10:13]
	v_mfma_f32_16x16x32_bf16 v[14:17], v[208:211], v[240:243], v[14:17]
	s_waitcnt lgkmcnt(0)
	s_barrier
	global_load_dwordx4 v[136:139], v[74:75], off offset:1024
	global_load_dwordx4 v[140:143], v[76:77], off offset:1024
	global_load_dwordx4 v[144:147], v[78:79], off offset:1024
	global_load_dwordx4 v[148:151], v[80:81], off offset:1024
	global_load_dwordx4 v[152:155], v[82:83], off offset:1024
	global_load_dwordx4 v[156:159], v[84:85], off offset:1024
	global_load_dwordx4 v[160:163], v[86:87], off offset:1024
	global_load_dwordx4 v[164:167], v[88:89], off offset:1024
	ds_read_b128 v[212:215], v245 offset:36864
	ds_read_b128 v[196:199], v244
	ds_read_b128 v[216:219], v245 offset:39168
	ds_read_b128 v[220:223], v245 offset:41472
	ds_read_b128 v[224:227], v245 offset:43776
	ds_read_b128 v[200:203], v244 offset:2304
	ds_read_b128 v[204:207], v244 offset:4608
	ds_read_b128 v[208:211], v244 offset:6912
	s_waitcnt lgkmcnt(6)
	v_mfma_f32_16x16x32_bf16 v[50:53], v[196:199], v[212:215], v[50:53]
	ds_read_b128 v[228:231], v245 offset:36928
	s_waitcnt lgkmcnt(6)
	v_mfma_f32_16x16x32_bf16 v[54:57], v[196:199], v[216:219], v[54:57]
	ds_read_b128 v[232:235], v245 offset:39232
	s_waitcnt lgkmcnt(6)
	v_mfma_f32_16x16x32_bf16 v[18:21], v[196:199], v[220:223], v[18:21]
	ds_read_b128 v[236:239], v245 offset:41536
	s_waitcnt lgkmcnt(6)
	v_mfma_f32_16x16x32_bf16 v[22:25], v[196:199], v[224:227], v[22:25]
	ds_read_b128 v[240:243], v245 offset:43840
	ds_read_b128 v[196:199], v244 offset:64
	s_waitcnt lgkmcnt(7)
	v_mfma_f32_16x16x32_bf16 v[58:61], v[200:203], v[212:215], v[58:61]
	v_mfma_f32_16x16x32_bf16 v[62:65], v[200:203], v[216:219], v[62:65]
	v_mfma_f32_16x16x32_bf16 v[26:29], v[200:203], v[220:223], v[26:29]
	v_mfma_f32_16x16x32_bf16 v[30:33], v[200:203], v[224:227], v[30:33]
	ds_read_b128 v[200:203], v244 offset:2368
	s_waitcnt lgkmcnt(7)
	v_mfma_f32_16x16x32_bf16 v[34:37], v[204:207], v[212:215], v[34:37]
	v_mfma_f32_16x16x32_bf16 v[38:41], v[204:207], v[216:219], v[38:41]
	v_mfma_f32_16x16x32_bf16 v[2:5], v[204:207], v[220:223], v[2:5]
	v_mfma_f32_16x16x32_bf16 v[6:9], v[204:207], v[224:227], v[6:9]
	ds_read_b128 v[204:207], v244 offset:4672
	s_waitcnt vmcnt(15)
	ds_write_b128 v98, v[102:105] offset:18432
	s_waitcnt vmcnt(14)
	ds_write_b128 v98, v[106:109] offset:23040
	s_waitcnt lgkmcnt(9)
	v_mfma_f32_16x16x32_bf16 v[42:45], v[208:211], v[212:215], v[42:45]
	v_mfma_f32_16x16x32_bf16 v[46:49], v[208:211], v[216:219], v[46:49]
	v_mfma_f32_16x16x32_bf16 v[10:13], v[208:211], v[220:223], v[10:13]
	v_mfma_f32_16x16x32_bf16 v[14:17], v[208:211], v[224:227], v[14:17]
	ds_read_b128 v[208:211], v244 offset:6976
	s_waitcnt vmcnt(13)
	ds_write_b128 v98, v[110:113] offset:27648
	s_waitcnt vmcnt(12)
	ds_write_b128 v98, v[114:117] offset:32256
	s_waitcnt lgkmcnt(7)
	v_mfma_f32_16x16x32_bf16 v[50:53], v[196:199], v[228:231], v[50:53]
	v_mfma_f32_16x16x32_bf16 v[54:57], v[196:199], v[232:235], v[54:57]
	v_mfma_f32_16x16x32_bf16 v[18:21], v[196:199], v[236:239], v[18:21]
	v_mfma_f32_16x16x32_bf16 v[22:25], v[196:199], v[240:243], v[22:25]
	s_waitcnt vmcnt(11)
	ds_write_b128 v98, v[118:121] offset:55296
	s_waitcnt vmcnt(10)
	ds_write_b128 v98, v[122:125] offset:59904
	s_waitcnt lgkmcnt(8)
	v_mfma_f32_16x16x32_bf16 v[58:61], v[200:203], v[228:231], v[58:61]
	v_mfma_f32_16x16x32_bf16 v[62:65], v[200:203], v[232:235], v[62:65]
	v_mfma_f32_16x16x32_bf16 v[26:29], v[200:203], v[236:239], v[26:29]
	v_mfma_f32_16x16x32_bf16 v[30:33], v[200:203], v[240:243], v[30:33]
	s_waitcnt vmcnt(9)
	ds_write_b128 v98, v[126:129] offset:64512
	s_waitcnt vmcnt(8)
	ds_write_b128 v99, v[132:135] offset:32256
	s_waitcnt lgkmcnt(9)
	v_mfma_f32_16x16x32_bf16 v[34:37], v[204:207], v[228:231], v[34:37]
	v_mfma_f32_16x16x32_bf16 v[38:41], v[204:207], v[232:235], v[38:41]
	v_mfma_f32_16x16x32_bf16 v[2:5], v[204:207], v[236:239], v[2:5]
	v_mfma_f32_16x16x32_bf16 v[6:9], v[204:207], v[240:243], v[6:9]
	s_waitcnt lgkmcnt(6)
	v_mfma_f32_16x16x32_bf16 v[42:45], v[208:211], v[228:231], v[42:45]
	v_mfma_f32_16x16x32_bf16 v[46:49], v[208:211], v[232:235], v[46:49]
	v_mfma_f32_16x16x32_bf16 v[10:13], v[208:211], v[236:239], v[10:13]
	v_mfma_f32_16x16x32_bf16 v[14:17], v[208:211], v[240:243], v[14:17]
	s_waitcnt lgkmcnt(0)
	s_barrier
	global_load_dwordx4 v[102:105], v[74:75], off offset:1152
	global_load_dwordx4 v[106:109], v[76:77], off offset:1152
	global_load_dwordx4 v[110:113], v[78:79], off offset:1152
	global_load_dwordx4 v[114:117], v[80:81], off offset:1152
	global_load_dwordx4 v[118:121], v[82:83], off offset:1152
	global_load_dwordx4 v[122:125], v[84:85], off offset:1152
	global_load_dwordx4 v[126:129], v[86:87], off offset:1152
	global_load_dwordx4 v[132:135], v[88:89], off offset:1152
	ds_read_b128 v[212:215], v245 offset:55296
	ds_read_b128 v[196:199], v244 offset:18432
	ds_read_b128 v[216:219], v245 offset:57600
	ds_read_b128 v[220:223], v245 offset:59904
	ds_read_b128 v[224:227], v245 offset:62208
	ds_read_b128 v[200:203], v244 offset:20736
	ds_read_b128 v[204:207], v244 offset:23040
	ds_read_b128 v[208:211], v244 offset:25344
	s_waitcnt lgkmcnt(6)
	v_mfma_f32_16x16x32_bf16 v[50:53], v[196:199], v[212:215], v[50:53]
	ds_read_b128 v[228:231], v245 offset:55360
	s_waitcnt lgkmcnt(6)
	v_mfma_f32_16x16x32_bf16 v[54:57], v[196:199], v[216:219], v[54:57]
	ds_read_b128 v[232:235], v245 offset:57664
	s_waitcnt lgkmcnt(6)
	v_mfma_f32_16x16x32_bf16 v[18:21], v[196:199], v[220:223], v[18:21]
	ds_read_b128 v[236:239], v245 offset:59968
	s_waitcnt lgkmcnt(6)
	v_mfma_f32_16x16x32_bf16 v[22:25], v[196:199], v[224:227], v[22:25]
	ds_read_b128 v[240:243], v245 offset:62272
	ds_read_b128 v[196:199], v244 offset:18496
	s_waitcnt lgkmcnt(7)
	v_mfma_f32_16x16x32_bf16 v[58:61], v[200:203], v[212:215], v[58:61]
	v_mfma_f32_16x16x32_bf16 v[62:65], v[200:203], v[216:219], v[62:65]
	v_mfma_f32_16x16x32_bf16 v[26:29], v[200:203], v[220:223], v[26:29]
	v_mfma_f32_16x16x32_bf16 v[30:33], v[200:203], v[224:227], v[30:33]
	ds_read_b128 v[200:203], v244 offset:20800
	s_waitcnt lgkmcnt(7)
	v_mfma_f32_16x16x32_bf16 v[34:37], v[204:207], v[212:215], v[34:37]
	v_mfma_f32_16x16x32_bf16 v[38:41], v[204:207], v[216:219], v[38:41]
	v_mfma_f32_16x16x32_bf16 v[2:5], v[204:207], v[220:223], v[2:5]
	v_mfma_f32_16x16x32_bf16 v[6:9], v[204:207], v[224:227], v[6:9]
	ds_read_b128 v[204:207], v244 offset:23104
	s_waitcnt vmcnt(15)
	ds_write_b128 v98, v[136:139]
	s_waitcnt vmcnt(14)
	ds_write_b128 v98, v[140:143] offset:4608
	s_waitcnt lgkmcnt(9)
	v_mfma_f32_16x16x32_bf16 v[42:45], v[208:211], v[212:215], v[42:45]
	v_mfma_f32_16x16x32_bf16 v[46:49], v[208:211], v[216:219], v[46:49]
	v_mfma_f32_16x16x32_bf16 v[10:13], v[208:211], v[220:223], v[10:13]
	v_mfma_f32_16x16x32_bf16 v[14:17], v[208:211], v[224:227], v[14:17]
	ds_read_b128 v[208:211], v244 offset:25408
	s_waitcnt vmcnt(13)
	ds_write_b128 v98, v[144:147] offset:9216
	s_waitcnt vmcnt(12)
	ds_write_b128 v98, v[148:151] offset:13824
	s_waitcnt lgkmcnt(7)
	v_mfma_f32_16x16x32_bf16 v[50:53], v[196:199], v[228:231], v[50:53]
	v_mfma_f32_16x16x32_bf16 v[54:57], v[196:199], v[232:235], v[54:57]
	v_mfma_f32_16x16x32_bf16 v[18:21], v[196:199], v[236:239], v[18:21]
	v_mfma_f32_16x16x32_bf16 v[22:25], v[196:199], v[240:243], v[22:25]
	s_waitcnt vmcnt(11)
	ds_write_b128 v98, v[152:155] offset:36864
	s_waitcnt vmcnt(10)
	ds_write_b128 v98, v[156:159] offset:41472
	s_waitcnt lgkmcnt(8)
	v_mfma_f32_16x16x32_bf16 v[58:61], v[200:203], v[228:231], v[58:61]
	v_mfma_f32_16x16x32_bf16 v[62:65], v[200:203], v[232:235], v[62:65]
	v_mfma_f32_16x16x32_bf16 v[26:29], v[200:203], v[236:239], v[26:29]
	v_mfma_f32_16x16x32_bf16 v[30:33], v[200:203], v[240:243], v[30:33]
	s_waitcnt vmcnt(9)
	ds_write_b128 v98, v[160:163] offset:46080
	s_waitcnt vmcnt(8)
	ds_write_b128 v98, v[164:167] offset:50688
	s_waitcnt lgkmcnt(9)
	v_mfma_f32_16x16x32_bf16 v[34:37], v[204:207], v[228:231], v[34:37]
	v_mfma_f32_16x16x32_bf16 v[38:41], v[204:207], v[232:235], v[38:41]
	v_mfma_f32_16x16x32_bf16 v[2:5], v[204:207], v[236:239], v[2:5]
	v_mfma_f32_16x16x32_bf16 v[6:9], v[204:207], v[240:243], v[6:9]
	s_waitcnt lgkmcnt(6)
	v_mfma_f32_16x16x32_bf16 v[42:45], v[208:211], v[228:231], v[42:45]
	v_mfma_f32_16x16x32_bf16 v[46:49], v[208:211], v[232:235], v[46:49]
	v_mfma_f32_16x16x32_bf16 v[10:13], v[208:211], v[236:239], v[10:13]
	v_mfma_f32_16x16x32_bf16 v[14:17], v[208:211], v[240:243], v[14:17]
	s_waitcnt lgkmcnt(0)
	s_barrier
	global_load_dwordx4 v[136:139], v[74:75], off offset:1280
	global_load_dwordx4 v[140:143], v[76:77], off offset:1280
	global_load_dwordx4 v[144:147], v[78:79], off offset:1280
	global_load_dwordx4 v[148:151], v[80:81], off offset:1280
	global_load_dwordx4 v[152:155], v[82:83], off offset:1280
	global_load_dwordx4 v[156:159], v[84:85], off offset:1280
	global_load_dwordx4 v[160:163], v[86:87], off offset:1280
	global_load_dwordx4 v[164:167], v[88:89], off offset:1280
	ds_read_b128 v[212:215], v245 offset:36864
	ds_read_b128 v[196:199], v244
	ds_read_b128 v[216:219], v245 offset:39168
	ds_read_b128 v[220:223], v245 offset:41472
	ds_read_b128 v[224:227], v245 offset:43776
	ds_read_b128 v[200:203], v244 offset:2304
	ds_read_b128 v[204:207], v244 offset:4608
	ds_read_b128 v[208:211], v244 offset:6912
	s_waitcnt lgkmcnt(6)
	v_mfma_f32_16x16x32_bf16 v[50:53], v[196:199], v[212:215], v[50:53]
	ds_read_b128 v[228:231], v245 offset:36928
	s_waitcnt lgkmcnt(6)
	v_mfma_f32_16x16x32_bf16 v[54:57], v[196:199], v[216:219], v[54:57]
	ds_read_b128 v[232:235], v245 offset:39232
	s_waitcnt lgkmcnt(6)
	v_mfma_f32_16x16x32_bf16 v[18:21], v[196:199], v[220:223], v[18:21]
	ds_read_b128 v[236:239], v245 offset:41536
	s_waitcnt lgkmcnt(6)
	v_mfma_f32_16x16x32_bf16 v[22:25], v[196:199], v[224:227], v[22:25]
	ds_read_b128 v[240:243], v245 offset:43840
	ds_read_b128 v[196:199], v244 offset:64
	s_waitcnt lgkmcnt(7)
	v_mfma_f32_16x16x32_bf16 v[58:61], v[200:203], v[212:215], v[58:61]
	v_mfma_f32_16x16x32_bf16 v[62:65], v[200:203], v[216:219], v[62:65]
	v_mfma_f32_16x16x32_bf16 v[26:29], v[200:203], v[220:223], v[26:29]
	v_mfma_f32_16x16x32_bf16 v[30:33], v[200:203], v[224:227], v[30:33]
	ds_read_b128 v[200:203], v244 offset:2368
	s_waitcnt lgkmcnt(7)
	v_mfma_f32_16x16x32_bf16 v[34:37], v[204:207], v[212:215], v[34:37]
	v_mfma_f32_16x16x32_bf16 v[38:41], v[204:207], v[216:219], v[38:41]
	v_mfma_f32_16x16x32_bf16 v[2:5], v[204:207], v[220:223], v[2:5]
	v_mfma_f32_16x16x32_bf16 v[6:9], v[204:207], v[224:227], v[6:9]
	ds_read_b128 v[204:207], v244 offset:4672
	s_waitcnt vmcnt(15)
	ds_write_b128 v98, v[102:105] offset:18432
	s_waitcnt vmcnt(14)
	ds_write_b128 v98, v[106:109] offset:23040
	s_waitcnt lgkmcnt(9)
	v_mfma_f32_16x16x32_bf16 v[42:45], v[208:211], v[212:215], v[42:45]
	v_mfma_f32_16x16x32_bf16 v[46:49], v[208:211], v[216:219], v[46:49]
	v_mfma_f32_16x16x32_bf16 v[10:13], v[208:211], v[220:223], v[10:13]
	v_mfma_f32_16x16x32_bf16 v[14:17], v[208:211], v[224:227], v[14:17]
	ds_read_b128 v[208:211], v244 offset:6976
	s_waitcnt vmcnt(13)
	ds_write_b128 v98, v[110:113] offset:27648
	s_waitcnt vmcnt(12)
	ds_write_b128 v98, v[114:117] offset:32256
	s_waitcnt lgkmcnt(7)
	v_mfma_f32_16x16x32_bf16 v[50:53], v[196:199], v[228:231], v[50:53]
	v_mfma_f32_16x16x32_bf16 v[54:57], v[196:199], v[232:235], v[54:57]
	v_mfma_f32_16x16x32_bf16 v[18:21], v[196:199], v[236:239], v[18:21]
	v_mfma_f32_16x16x32_bf16 v[22:25], v[196:199], v[240:243], v[22:25]
	s_waitcnt vmcnt(11)
	ds_write_b128 v98, v[118:121] offset:55296
	s_waitcnt vmcnt(10)
	ds_write_b128 v98, v[122:125] offset:59904
	s_waitcnt lgkmcnt(8)
	v_mfma_f32_16x16x32_bf16 v[58:61], v[200:203], v[228:231], v[58:61]
	v_mfma_f32_16x16x32_bf16 v[62:65], v[200:203], v[232:235], v[62:65]
	v_mfma_f32_16x16x32_bf16 v[26:29], v[200:203], v[236:239], v[26:29]
	v_mfma_f32_16x16x32_bf16 v[30:33], v[200:203], v[240:243], v[30:33]
	s_waitcnt vmcnt(9)
	ds_write_b128 v98, v[126:129] offset:64512
	s_waitcnt vmcnt(8)
	ds_write_b128 v99, v[132:135] offset:32256
	s_waitcnt lgkmcnt(9)
	v_mfma_f32_16x16x32_bf16 v[34:37], v[204:207], v[228:231], v[34:37]
	v_mfma_f32_16x16x32_bf16 v[38:41], v[204:207], v[232:235], v[38:41]
	v_mfma_f32_16x16x32_bf16 v[2:5], v[204:207], v[236:239], v[2:5]
	v_mfma_f32_16x16x32_bf16 v[6:9], v[204:207], v[240:243], v[6:9]
	s_waitcnt lgkmcnt(6)
	v_mfma_f32_16x16x32_bf16 v[42:45], v[208:211], v[228:231], v[42:45]
	v_mfma_f32_16x16x32_bf16 v[46:49], v[208:211], v[232:235], v[46:49]
	v_mfma_f32_16x16x32_bf16 v[10:13], v[208:211], v[236:239], v[10:13]
	v_mfma_f32_16x16x32_bf16 v[14:17], v[208:211], v[240:243], v[14:17]
	s_waitcnt lgkmcnt(0)
	s_barrier
	global_load_dwordx4 v[102:105], v[74:75], off offset:1408
	global_load_dwordx4 v[106:109], v[76:77], off offset:1408
	global_load_dwordx4 v[110:113], v[78:79], off offset:1408
	global_load_dwordx4 v[114:117], v[80:81], off offset:1408
	global_load_dwordx4 v[118:121], v[82:83], off offset:1408
	global_load_dwordx4 v[122:125], v[84:85], off offset:1408
	global_load_dwordx4 v[126:129], v[86:87], off offset:1408
	global_load_dwordx4 v[132:135], v[88:89], off offset:1408
	ds_read_b128 v[212:215], v245 offset:55296
	ds_read_b128 v[196:199], v244 offset:18432
	ds_read_b128 v[216:219], v245 offset:57600
	ds_read_b128 v[220:223], v245 offset:59904
	ds_read_b128 v[224:227], v245 offset:62208
	ds_read_b128 v[200:203], v244 offset:20736
	ds_read_b128 v[204:207], v244 offset:23040
	ds_read_b128 v[208:211], v244 offset:25344
	s_waitcnt lgkmcnt(6)
	v_mfma_f32_16x16x32_bf16 v[50:53], v[196:199], v[212:215], v[50:53]
	ds_read_b128 v[228:231], v245 offset:55360
	s_waitcnt lgkmcnt(6)
	v_mfma_f32_16x16x32_bf16 v[54:57], v[196:199], v[216:219], v[54:57]
	ds_read_b128 v[232:235], v245 offset:57664
	s_waitcnt lgkmcnt(6)
	v_mfma_f32_16x16x32_bf16 v[18:21], v[196:199], v[220:223], v[18:21]
	ds_read_b128 v[236:239], v245 offset:59968
	s_waitcnt lgkmcnt(6)
	v_mfma_f32_16x16x32_bf16 v[22:25], v[196:199], v[224:227], v[22:25]
	ds_read_b128 v[240:243], v245 offset:62272
	ds_read_b128 v[196:199], v244 offset:18496
	s_waitcnt lgkmcnt(7)
	v_mfma_f32_16x16x32_bf16 v[58:61], v[200:203], v[212:215], v[58:61]
	v_mfma_f32_16x16x32_bf16 v[62:65], v[200:203], v[216:219], v[62:65]
	v_mfma_f32_16x16x32_bf16 v[26:29], v[200:203], v[220:223], v[26:29]
	v_mfma_f32_16x16x32_bf16 v[30:33], v[200:203], v[224:227], v[30:33]
	ds_read_b128 v[200:203], v244 offset:20800
	s_waitcnt lgkmcnt(7)
	v_mfma_f32_16x16x32_bf16 v[34:37], v[204:207], v[212:215], v[34:37]
	v_mfma_f32_16x16x32_bf16 v[38:41], v[204:207], v[216:219], v[38:41]
	v_mfma_f32_16x16x32_bf16 v[2:5], v[204:207], v[220:223], v[2:5]
	v_mfma_f32_16x16x32_bf16 v[6:9], v[204:207], v[224:227], v[6:9]
	ds_read_b128 v[204:207], v244 offset:23104
	s_waitcnt vmcnt(15)
	ds_write_b128 v98, v[136:139]
	s_waitcnt vmcnt(14)
	ds_write_b128 v98, v[140:143] offset:4608
	s_waitcnt lgkmcnt(9)
	v_mfma_f32_16x16x32_bf16 v[42:45], v[208:211], v[212:215], v[42:45]
	v_mfma_f32_16x16x32_bf16 v[46:49], v[208:211], v[216:219], v[46:49]
	v_mfma_f32_16x16x32_bf16 v[10:13], v[208:211], v[220:223], v[10:13]
	v_mfma_f32_16x16x32_bf16 v[14:17], v[208:211], v[224:227], v[14:17]
	ds_read_b128 v[208:211], v244 offset:25408
	s_waitcnt vmcnt(13)
	ds_write_b128 v98, v[144:147] offset:9216
	s_waitcnt vmcnt(12)
	ds_write_b128 v98, v[148:151] offset:13824
	s_waitcnt lgkmcnt(7)
	v_mfma_f32_16x16x32_bf16 v[50:53], v[196:199], v[228:231], v[50:53]
	v_mfma_f32_16x16x32_bf16 v[54:57], v[196:199], v[232:235], v[54:57]
	v_mfma_f32_16x16x32_bf16 v[18:21], v[196:199], v[236:239], v[18:21]
	v_mfma_f32_16x16x32_bf16 v[22:25], v[196:199], v[240:243], v[22:25]
	s_waitcnt vmcnt(11)
	ds_write_b128 v98, v[152:155] offset:36864
	s_waitcnt vmcnt(10)
	ds_write_b128 v98, v[156:159] offset:41472
	s_waitcnt lgkmcnt(8)
	v_mfma_f32_16x16x32_bf16 v[58:61], v[200:203], v[228:231], v[58:61]
	v_mfma_f32_16x16x32_bf16 v[62:65], v[200:203], v[232:235], v[62:65]
	v_mfma_f32_16x16x32_bf16 v[26:29], v[200:203], v[236:239], v[26:29]
	v_mfma_f32_16x16x32_bf16 v[30:33], v[200:203], v[240:243], v[30:33]
	s_waitcnt vmcnt(9)
	ds_write_b128 v98, v[160:163] offset:46080
	s_waitcnt vmcnt(8)
	ds_write_b128 v98, v[164:167] offset:50688
	s_waitcnt lgkmcnt(9)
	v_mfma_f32_16x16x32_bf16 v[34:37], v[204:207], v[228:231], v[34:37]
	v_mfma_f32_16x16x32_bf16 v[38:41], v[204:207], v[232:235], v[38:41]
	v_mfma_f32_16x16x32_bf16 v[2:5], v[204:207], v[236:239], v[2:5]
	v_mfma_f32_16x16x32_bf16 v[6:9], v[204:207], v[240:243], v[6:9]
	s_waitcnt lgkmcnt(6)
	v_mfma_f32_16x16x32_bf16 v[42:45], v[208:211], v[228:231], v[42:45]
	v_mfma_f32_16x16x32_bf16 v[46:49], v[208:211], v[232:235], v[46:49]
	v_mfma_f32_16x16x32_bf16 v[10:13], v[208:211], v[236:239], v[10:13]
	v_mfma_f32_16x16x32_bf16 v[14:17], v[208:211], v[240:243], v[14:17]
	s_waitcnt lgkmcnt(0)
	s_barrier
	global_load_dwordx4 v[136:139], v[74:75], off offset:1536
	global_load_dwordx4 v[140:143], v[76:77], off offset:1536
	global_load_dwordx4 v[144:147], v[78:79], off offset:1536
	global_load_dwordx4 v[148:151], v[80:81], off offset:1536
	global_load_dwordx4 v[152:155], v[82:83], off offset:1536
	global_load_dwordx4 v[156:159], v[84:85], off offset:1536
	global_load_dwordx4 v[160:163], v[86:87], off offset:1536
	global_load_dwordx4 v[164:167], v[88:89], off offset:1536
	ds_read_b128 v[212:215], v245 offset:36864
	ds_read_b128 v[196:199], v244
	ds_read_b128 v[216:219], v245 offset:39168
	ds_read_b128 v[220:223], v245 offset:41472
	ds_read_b128 v[224:227], v245 offset:43776
	ds_read_b128 v[200:203], v244 offset:2304
	ds_read_b128 v[204:207], v244 offset:4608
	ds_read_b128 v[208:211], v244 offset:6912
	s_waitcnt lgkmcnt(6)
	v_mfma_f32_16x16x32_bf16 v[50:53], v[196:199], v[212:215], v[50:53]
	ds_read_b128 v[228:231], v245 offset:36928
	s_waitcnt lgkmcnt(6)
	v_mfma_f32_16x16x32_bf16 v[54:57], v[196:199], v[216:219], v[54:57]
	ds_read_b128 v[232:235], v245 offset:39232
	s_waitcnt lgkmcnt(6)
	v_mfma_f32_16x16x32_bf16 v[18:21], v[196:199], v[220:223], v[18:21]
	ds_read_b128 v[236:239], v245 offset:41536
	s_waitcnt lgkmcnt(6)
	v_mfma_f32_16x16x32_bf16 v[22:25], v[196:199], v[224:227], v[22:25]
	ds_read_b128 v[240:243], v245 offset:43840
	ds_read_b128 v[196:199], v244 offset:64
	s_waitcnt lgkmcnt(7)
	v_mfma_f32_16x16x32_bf16 v[58:61], v[200:203], v[212:215], v[58:61]
	v_mfma_f32_16x16x32_bf16 v[62:65], v[200:203], v[216:219], v[62:65]
	v_mfma_f32_16x16x32_bf16 v[26:29], v[200:203], v[220:223], v[26:29]
	v_mfma_f32_16x16x32_bf16 v[30:33], v[200:203], v[224:227], v[30:33]
	ds_read_b128 v[200:203], v244 offset:2368
	s_waitcnt lgkmcnt(7)
	v_mfma_f32_16x16x32_bf16 v[34:37], v[204:207], v[212:215], v[34:37]
	v_mfma_f32_16x16x32_bf16 v[38:41], v[204:207], v[216:219], v[38:41]
	v_mfma_f32_16x16x32_bf16 v[2:5], v[204:207], v[220:223], v[2:5]
	v_mfma_f32_16x16x32_bf16 v[6:9], v[204:207], v[224:227], v[6:9]
	ds_read_b128 v[204:207], v244 offset:4672
	s_waitcnt vmcnt(15)
	ds_write_b128 v98, v[102:105] offset:18432
	s_waitcnt vmcnt(14)
	ds_write_b128 v98, v[106:109] offset:23040
	s_waitcnt lgkmcnt(9)
	v_mfma_f32_16x16x32_bf16 v[42:45], v[208:211], v[212:215], v[42:45]
	v_mfma_f32_16x16x32_bf16 v[46:49], v[208:211], v[216:219], v[46:49]
	v_mfma_f32_16x16x32_bf16 v[10:13], v[208:211], v[220:223], v[10:13]
	v_mfma_f32_16x16x32_bf16 v[14:17], v[208:211], v[224:227], v[14:17]
	ds_read_b128 v[208:211], v244 offset:6976
	s_waitcnt vmcnt(13)
	ds_write_b128 v98, v[110:113] offset:27648
	s_waitcnt vmcnt(12)
	ds_write_b128 v98, v[114:117] offset:32256
	s_waitcnt lgkmcnt(7)
	v_mfma_f32_16x16x32_bf16 v[50:53], v[196:199], v[228:231], v[50:53]
	v_mfma_f32_16x16x32_bf16 v[54:57], v[196:199], v[232:235], v[54:57]
	v_mfma_f32_16x16x32_bf16 v[18:21], v[196:199], v[236:239], v[18:21]
	v_mfma_f32_16x16x32_bf16 v[22:25], v[196:199], v[240:243], v[22:25]
	s_waitcnt vmcnt(11)
	ds_write_b128 v98, v[118:121] offset:55296
	s_waitcnt vmcnt(10)
	ds_write_b128 v98, v[122:125] offset:59904
	s_waitcnt lgkmcnt(8)
	v_mfma_f32_16x16x32_bf16 v[58:61], v[200:203], v[228:231], v[58:61]
	v_mfma_f32_16x16x32_bf16 v[62:65], v[200:203], v[232:235], v[62:65]
	v_mfma_f32_16x16x32_bf16 v[26:29], v[200:203], v[236:239], v[26:29]
	v_mfma_f32_16x16x32_bf16 v[30:33], v[200:203], v[240:243], v[30:33]
	s_waitcnt vmcnt(9)
	ds_write_b128 v98, v[126:129] offset:64512
	s_waitcnt vmcnt(8)
	ds_write_b128 v99, v[132:135] offset:32256
	s_waitcnt lgkmcnt(9)
	v_mfma_f32_16x16x32_bf16 v[34:37], v[204:207], v[228:231], v[34:37]
	v_mfma_f32_16x16x32_bf16 v[38:41], v[204:207], v[232:235], v[38:41]
	v_mfma_f32_16x16x32_bf16 v[2:5], v[204:207], v[236:239], v[2:5]
	v_mfma_f32_16x16x32_bf16 v[6:9], v[204:207], v[240:243], v[6:9]
	s_waitcnt lgkmcnt(6)
	v_mfma_f32_16x16x32_bf16 v[42:45], v[208:211], v[228:231], v[42:45]
	v_mfma_f32_16x16x32_bf16 v[46:49], v[208:211], v[232:235], v[46:49]
	v_mfma_f32_16x16x32_bf16 v[10:13], v[208:211], v[236:239], v[10:13]
	v_mfma_f32_16x16x32_bf16 v[14:17], v[208:211], v[240:243], v[14:17]
	s_waitcnt lgkmcnt(0)
	s_barrier
	global_load_dwordx4 v[102:105], v[74:75], off offset:1664
	global_load_dwordx4 v[106:109], v[76:77], off offset:1664
	global_load_dwordx4 v[110:113], v[78:79], off offset:1664
	global_load_dwordx4 v[114:117], v[80:81], off offset:1664
	global_load_dwordx4 v[118:121], v[82:83], off offset:1664
	global_load_dwordx4 v[122:125], v[84:85], off offset:1664
	global_load_dwordx4 v[126:129], v[86:87], off offset:1664
	global_load_dwordx4 v[132:135], v[88:89], off offset:1664
	ds_read_b128 v[212:215], v245 offset:55296
	ds_read_b128 v[196:199], v244 offset:18432
	ds_read_b128 v[216:219], v245 offset:57600
	ds_read_b128 v[220:223], v245 offset:59904
	ds_read_b128 v[224:227], v245 offset:62208
	ds_read_b128 v[200:203], v244 offset:20736
	ds_read_b128 v[204:207], v244 offset:23040
	ds_read_b128 v[208:211], v244 offset:25344
	s_waitcnt lgkmcnt(6)
	v_mfma_f32_16x16x32_bf16 v[50:53], v[196:199], v[212:215], v[50:53]
	ds_read_b128 v[228:231], v245 offset:55360
	s_waitcnt lgkmcnt(6)
	v_mfma_f32_16x16x32_bf16 v[54:57], v[196:199], v[216:219], v[54:57]
	ds_read_b128 v[232:235], v245 offset:57664
	s_waitcnt lgkmcnt(6)
	v_mfma_f32_16x16x32_bf16 v[18:21], v[196:199], v[220:223], v[18:21]
	ds_read_b128 v[236:239], v245 offset:59968
	s_waitcnt lgkmcnt(6)
	v_mfma_f32_16x16x32_bf16 v[22:25], v[196:199], v[224:227], v[22:25]
	ds_read_b128 v[240:243], v245 offset:62272
	ds_read_b128 v[196:199], v244 offset:18496
	s_waitcnt lgkmcnt(7)
	v_mfma_f32_16x16x32_bf16 v[58:61], v[200:203], v[212:215], v[58:61]
	v_mfma_f32_16x16x32_bf16 v[62:65], v[200:203], v[216:219], v[62:65]
	v_mfma_f32_16x16x32_bf16 v[26:29], v[200:203], v[220:223], v[26:29]
	v_mfma_f32_16x16x32_bf16 v[30:33], v[200:203], v[224:227], v[30:33]
	ds_read_b128 v[200:203], v244 offset:20800
	s_waitcnt lgkmcnt(7)
	v_mfma_f32_16x16x32_bf16 v[34:37], v[204:207], v[212:215], v[34:37]
	v_mfma_f32_16x16x32_bf16 v[38:41], v[204:207], v[216:219], v[38:41]
	v_mfma_f32_16x16x32_bf16 v[2:5], v[204:207], v[220:223], v[2:5]
	v_mfma_f32_16x16x32_bf16 v[6:9], v[204:207], v[224:227], v[6:9]
	ds_read_b128 v[204:207], v244 offset:23104
	s_waitcnt vmcnt(15)
	ds_write_b128 v98, v[136:139]
	s_waitcnt vmcnt(14)
	ds_write_b128 v98, v[140:143] offset:4608
	s_waitcnt lgkmcnt(9)
	v_mfma_f32_16x16x32_bf16 v[42:45], v[208:211], v[212:215], v[42:45]
	v_mfma_f32_16x16x32_bf16 v[46:49], v[208:211], v[216:219], v[46:49]
	v_mfma_f32_16x16x32_bf16 v[10:13], v[208:211], v[220:223], v[10:13]
	v_mfma_f32_16x16x32_bf16 v[14:17], v[208:211], v[224:227], v[14:17]
	ds_read_b128 v[208:211], v244 offset:25408
	s_waitcnt vmcnt(13)
	ds_write_b128 v98, v[144:147] offset:9216
	s_waitcnt vmcnt(12)
	ds_write_b128 v98, v[148:151] offset:13824
	s_waitcnt lgkmcnt(7)
	v_mfma_f32_16x16x32_bf16 v[50:53], v[196:199], v[228:231], v[50:53]
	v_mfma_f32_16x16x32_bf16 v[54:57], v[196:199], v[232:235], v[54:57]
	v_mfma_f32_16x16x32_bf16 v[18:21], v[196:199], v[236:239], v[18:21]
	v_mfma_f32_16x16x32_bf16 v[22:25], v[196:199], v[240:243], v[22:25]
	s_waitcnt vmcnt(11)
	ds_write_b128 v98, v[152:155] offset:36864
	s_waitcnt vmcnt(10)
	ds_write_b128 v98, v[156:159] offset:41472
	s_waitcnt lgkmcnt(8)
	v_mfma_f32_16x16x32_bf16 v[58:61], v[200:203], v[228:231], v[58:61]
	v_mfma_f32_16x16x32_bf16 v[62:65], v[200:203], v[232:235], v[62:65]
	v_mfma_f32_16x16x32_bf16 v[26:29], v[200:203], v[236:239], v[26:29]
	v_mfma_f32_16x16x32_bf16 v[30:33], v[200:203], v[240:243], v[30:33]
	s_waitcnt vmcnt(9)
	ds_write_b128 v98, v[160:163] offset:46080
	s_waitcnt vmcnt(8)
	ds_write_b128 v98, v[164:167] offset:50688
	s_waitcnt lgkmcnt(9)
	v_mfma_f32_16x16x32_bf16 v[34:37], v[204:207], v[228:231], v[34:37]
	v_mfma_f32_16x16x32_bf16 v[38:41], v[204:207], v[232:235], v[38:41]
	v_mfma_f32_16x16x32_bf16 v[2:5], v[204:207], v[236:239], v[2:5]
	v_mfma_f32_16x16x32_bf16 v[6:9], v[204:207], v[240:243], v[6:9]
	s_waitcnt lgkmcnt(6)
	v_mfma_f32_16x16x32_bf16 v[42:45], v[208:211], v[228:231], v[42:45]
	v_mfma_f32_16x16x32_bf16 v[46:49], v[208:211], v[232:235], v[46:49]
	v_mfma_f32_16x16x32_bf16 v[10:13], v[208:211], v[236:239], v[10:13]
	v_mfma_f32_16x16x32_bf16 v[14:17], v[208:211], v[240:243], v[14:17]
	s_waitcnt lgkmcnt(0)
	s_barrier
	global_load_dwordx4 v[136:139], v[74:75], off offset:1792
	global_load_dwordx4 v[140:143], v[76:77], off offset:1792
	global_load_dwordx4 v[144:147], v[78:79], off offset:1792
	global_load_dwordx4 v[148:151], v[80:81], off offset:1792
	global_load_dwordx4 v[152:155], v[82:83], off offset:1792
	global_load_dwordx4 v[156:159], v[84:85], off offset:1792
	global_load_dwordx4 v[160:163], v[86:87], off offset:1792
	global_load_dwordx4 v[164:167], v[88:89], off offset:1792
	ds_read_b128 v[212:215], v245 offset:36864
	ds_read_b128 v[196:199], v244
	ds_read_b128 v[216:219], v245 offset:39168
	ds_read_b128 v[220:223], v245 offset:41472
	ds_read_b128 v[224:227], v245 offset:43776
	ds_read_b128 v[200:203], v244 offset:2304
	ds_read_b128 v[204:207], v244 offset:4608
	ds_read_b128 v[208:211], v244 offset:6912
	s_waitcnt lgkmcnt(6)
	v_mfma_f32_16x16x32_bf16 v[50:53], v[196:199], v[212:215], v[50:53]
	ds_read_b128 v[228:231], v245 offset:36928
	s_waitcnt lgkmcnt(6)
	v_mfma_f32_16x16x32_bf16 v[54:57], v[196:199], v[216:219], v[54:57]
	ds_read_b128 v[232:235], v245 offset:39232
	s_waitcnt lgkmcnt(6)
	v_mfma_f32_16x16x32_bf16 v[18:21], v[196:199], v[220:223], v[18:21]
	ds_read_b128 v[236:239], v245 offset:41536
	s_waitcnt lgkmcnt(6)
	v_mfma_f32_16x16x32_bf16 v[22:25], v[196:199], v[224:227], v[22:25]
	ds_read_b128 v[240:243], v245 offset:43840
	ds_read_b128 v[196:199], v244 offset:64
	s_waitcnt lgkmcnt(7)
	v_mfma_f32_16x16x32_bf16 v[58:61], v[200:203], v[212:215], v[58:61]
	v_mfma_f32_16x16x32_bf16 v[62:65], v[200:203], v[216:219], v[62:65]
	v_mfma_f32_16x16x32_bf16 v[26:29], v[200:203], v[220:223], v[26:29]
	v_mfma_f32_16x16x32_bf16 v[30:33], v[200:203], v[224:227], v[30:33]
	ds_read_b128 v[200:203], v244 offset:2368
	s_waitcnt lgkmcnt(7)
	v_mfma_f32_16x16x32_bf16 v[34:37], v[204:207], v[212:215], v[34:37]
	v_mfma_f32_16x16x32_bf16 v[38:41], v[204:207], v[216:219], v[38:41]
	v_mfma_f32_16x16x32_bf16 v[2:5], v[204:207], v[220:223], v[2:5]
	v_mfma_f32_16x16x32_bf16 v[6:9], v[204:207], v[224:227], v[6:9]
	ds_read_b128 v[204:207], v244 offset:4672
	s_waitcnt vmcnt(15)
	ds_write_b128 v98, v[102:105] offset:18432
	s_waitcnt vmcnt(14)
	ds_write_b128 v98, v[106:109] offset:23040
	s_waitcnt lgkmcnt(9)
	v_mfma_f32_16x16x32_bf16 v[42:45], v[208:211], v[212:215], v[42:45]
	v_mfma_f32_16x16x32_bf16 v[46:49], v[208:211], v[216:219], v[46:49]
	v_mfma_f32_16x16x32_bf16 v[10:13], v[208:211], v[220:223], v[10:13]
	v_mfma_f32_16x16x32_bf16 v[14:17], v[208:211], v[224:227], v[14:17]
	ds_read_b128 v[208:211], v244 offset:6976
	s_waitcnt vmcnt(13)
	ds_write_b128 v98, v[110:113] offset:27648
	s_waitcnt vmcnt(12)
	ds_write_b128 v98, v[114:117] offset:32256
	s_waitcnt lgkmcnt(7)
	v_mfma_f32_16x16x32_bf16 v[50:53], v[196:199], v[228:231], v[50:53]
	v_mfma_f32_16x16x32_bf16 v[54:57], v[196:199], v[232:235], v[54:57]
	v_mfma_f32_16x16x32_bf16 v[18:21], v[196:199], v[236:239], v[18:21]
	v_mfma_f32_16x16x32_bf16 v[22:25], v[196:199], v[240:243], v[22:25]
	s_waitcnt vmcnt(11)
	ds_write_b128 v98, v[118:121] offset:55296
	s_waitcnt vmcnt(10)
	ds_write_b128 v98, v[122:125] offset:59904
	s_waitcnt lgkmcnt(8)
	v_mfma_f32_16x16x32_bf16 v[58:61], v[200:203], v[228:231], v[58:61]
	v_mfma_f32_16x16x32_bf16 v[62:65], v[200:203], v[232:235], v[62:65]
	v_mfma_f32_16x16x32_bf16 v[26:29], v[200:203], v[236:239], v[26:29]
	v_mfma_f32_16x16x32_bf16 v[30:33], v[200:203], v[240:243], v[30:33]
	s_waitcnt vmcnt(9)
	ds_write_b128 v98, v[126:129] offset:64512
	s_waitcnt vmcnt(8)
	ds_write_b128 v99, v[132:135] offset:32256
	s_waitcnt lgkmcnt(9)
	v_mfma_f32_16x16x32_bf16 v[34:37], v[204:207], v[228:231], v[34:37]
	v_mfma_f32_16x16x32_bf16 v[38:41], v[204:207], v[232:235], v[38:41]
	v_mfma_f32_16x16x32_bf16 v[2:5], v[204:207], v[236:239], v[2:5]
	v_mfma_f32_16x16x32_bf16 v[6:9], v[204:207], v[240:243], v[6:9]
	s_waitcnt lgkmcnt(6)
	v_mfma_f32_16x16x32_bf16 v[42:45], v[208:211], v[228:231], v[42:45]
	v_mfma_f32_16x16x32_bf16 v[46:49], v[208:211], v[232:235], v[46:49]
	v_mfma_f32_16x16x32_bf16 v[10:13], v[208:211], v[236:239], v[10:13]
	v_mfma_f32_16x16x32_bf16 v[14:17], v[208:211], v[240:243], v[14:17]
	s_waitcnt lgkmcnt(0)
	s_barrier
	global_load_dwordx4 v[102:105], v[74:75], off offset:1920
	s_nop 0
	global_load_dwordx4 v[74:77], v[76:77], off offset:1920
	s_nop 0
	global_load_dwordx4 v[106:109], v[78:79], off offset:1920
	s_nop 0
	global_load_dwordx4 v[78:81], v[80:81], off offset:1920
	s_nop 0
	global_load_dwordx4 v[110:113], v[82:83], off offset:1920
	s_nop 0
	global_load_dwordx4 v[82:85], v[84:85], off offset:1920
	s_nop 0
	global_load_dwordx4 v[114:117], v[86:87], off offset:1920
	s_nop 0
	global_load_dwordx4 v[86:89], v[88:89], off offset:1920
	ds_read_b128 v[212:215], v245 offset:55296
	ds_read_b128 v[196:199], v244 offset:18432
	ds_read_b128 v[216:219], v245 offset:57600
	ds_read_b128 v[220:223], v245 offset:59904
	ds_read_b128 v[224:227], v245 offset:62208
	ds_read_b128 v[200:203], v244 offset:20736
	ds_read_b128 v[204:207], v244 offset:23040
	ds_read_b128 v[208:211], v244 offset:25344
	s_waitcnt lgkmcnt(6)
	v_mfma_f32_16x16x32_bf16 v[50:53], v[196:199], v[212:215], v[50:53]
	ds_read_b128 v[228:231], v245 offset:55360
	s_waitcnt lgkmcnt(6)
	v_mfma_f32_16x16x32_bf16 v[54:57], v[196:199], v[216:219], v[54:57]
	ds_read_b128 v[232:235], v245 offset:57664
	s_waitcnt lgkmcnt(6)
	v_mfma_f32_16x16x32_bf16 v[18:21], v[196:199], v[220:223], v[18:21]
	ds_read_b128 v[236:239], v245 offset:59968
	s_waitcnt lgkmcnt(6)
	v_mfma_f32_16x16x32_bf16 v[22:25], v[196:199], v[224:227], v[22:25]
	ds_read_b128 v[240:243], v245 offset:62272
	ds_read_b128 v[196:199], v244 offset:18496
	s_waitcnt lgkmcnt(7)
	v_mfma_f32_16x16x32_bf16 v[58:61], v[200:203], v[212:215], v[58:61]
	v_mfma_f32_16x16x32_bf16 v[62:65], v[200:203], v[216:219], v[62:65]
	v_mfma_f32_16x16x32_bf16 v[26:29], v[200:203], v[220:223], v[26:29]
	v_mfma_f32_16x16x32_bf16 v[30:33], v[200:203], v[224:227], v[30:33]
	ds_read_b128 v[200:203], v244 offset:20800
	s_waitcnt lgkmcnt(7)
	v_mfma_f32_16x16x32_bf16 v[34:37], v[204:207], v[212:215], v[34:37]
	v_mfma_f32_16x16x32_bf16 v[38:41], v[204:207], v[216:219], v[38:41]
	v_mfma_f32_16x16x32_bf16 v[2:5], v[204:207], v[220:223], v[2:5]
	v_mfma_f32_16x16x32_bf16 v[6:9], v[204:207], v[224:227], v[6:9]
	ds_read_b128 v[204:207], v244 offset:23104
	s_waitcnt vmcnt(15)
	ds_write_b128 v98, v[136:139]
	s_waitcnt vmcnt(14)
	ds_write_b128 v98, v[140:143] offset:4608
	s_waitcnt lgkmcnt(9)
	v_mfma_f32_16x16x32_bf16 v[42:45], v[208:211], v[212:215], v[42:45]
	v_mfma_f32_16x16x32_bf16 v[46:49], v[208:211], v[216:219], v[46:49]
	v_mfma_f32_16x16x32_bf16 v[10:13], v[208:211], v[220:223], v[10:13]
	v_mfma_f32_16x16x32_bf16 v[14:17], v[208:211], v[224:227], v[14:17]
	ds_read_b128 v[208:211], v244 offset:25408
	s_waitcnt vmcnt(13)
	ds_write_b128 v98, v[144:147] offset:9216
	s_waitcnt vmcnt(12)
	ds_write_b128 v98, v[148:151] offset:13824
	s_waitcnt lgkmcnt(7)
	v_mfma_f32_16x16x32_bf16 v[50:53], v[196:199], v[228:231], v[50:53]
	v_mfma_f32_16x16x32_bf16 v[54:57], v[196:199], v[232:235], v[54:57]
	v_mfma_f32_16x16x32_bf16 v[18:21], v[196:199], v[236:239], v[18:21]
	v_mfma_f32_16x16x32_bf16 v[22:25], v[196:199], v[240:243], v[22:25]
	s_waitcnt vmcnt(11)
	ds_write_b128 v98, v[152:155] offset:36864
	s_waitcnt vmcnt(10)
	ds_write_b128 v98, v[156:159] offset:41472
	s_waitcnt lgkmcnt(8)
	v_mfma_f32_16x16x32_bf16 v[58:61], v[200:203], v[228:231], v[58:61]
	v_mfma_f32_16x16x32_bf16 v[62:65], v[200:203], v[232:235], v[62:65]
	v_mfma_f32_16x16x32_bf16 v[26:29], v[200:203], v[236:239], v[26:29]
	v_mfma_f32_16x16x32_bf16 v[30:33], v[200:203], v[240:243], v[30:33]
	s_waitcnt vmcnt(9)
	ds_write_b128 v98, v[160:163] offset:46080
	s_waitcnt vmcnt(8)
	ds_write_b128 v98, v[164:167] offset:50688
	s_waitcnt lgkmcnt(9)
	v_mfma_f32_16x16x32_bf16 v[34:37], v[204:207], v[228:231], v[34:37]
	v_mfma_f32_16x16x32_bf16 v[38:41], v[204:207], v[232:235], v[38:41]
	v_mfma_f32_16x16x32_bf16 v[2:5], v[204:207], v[236:239], v[2:5]
	v_mfma_f32_16x16x32_bf16 v[6:9], v[204:207], v[240:243], v[6:9]
	s_waitcnt lgkmcnt(6)
	v_mfma_f32_16x16x32_bf16 v[42:45], v[208:211], v[228:231], v[42:45]
	v_mfma_f32_16x16x32_bf16 v[46:49], v[208:211], v[232:235], v[46:49]
	v_mfma_f32_16x16x32_bf16 v[10:13], v[208:211], v[236:239], v[10:13]
	v_mfma_f32_16x16x32_bf16 v[14:17], v[208:211], v[240:243], v[14:17]
	s_waitcnt lgkmcnt(0)
	s_barrier
	ds_read_b128 v[212:215], v245 offset:36864
	ds_read_b128 v[196:199], v244
	ds_read_b128 v[216:219], v245 offset:39168
	ds_read_b128 v[220:223], v245 offset:41472
	ds_read_b128 v[224:227], v245 offset:43776
	ds_read_b128 v[200:203], v244 offset:2304
	ds_read_b128 v[204:207], v244 offset:4608
	ds_read_b128 v[208:211], v244 offset:6912
	s_waitcnt lgkmcnt(6)
	v_mfma_f32_16x16x32_bf16 v[50:53], v[196:199], v[212:215], v[50:53]
	ds_read_b128 v[228:231], v245 offset:36928
	s_waitcnt lgkmcnt(6)
	v_mfma_f32_16x16x32_bf16 v[54:57], v[196:199], v[216:219], v[54:57]
	ds_read_b128 v[232:235], v245 offset:39232
	s_waitcnt lgkmcnt(6)
	v_mfma_f32_16x16x32_bf16 v[18:21], v[196:199], v[220:223], v[18:21]
	ds_read_b128 v[236:239], v245 offset:41536
	s_waitcnt lgkmcnt(6)
	v_mfma_f32_16x16x32_bf16 v[22:25], v[196:199], v[224:227], v[22:25]
	ds_read_b128 v[240:243], v245 offset:43840
	ds_read_b128 v[196:199], v244 offset:64
	s_waitcnt lgkmcnt(7)
	v_mfma_f32_16x16x32_bf16 v[58:61], v[200:203], v[212:215], v[58:61]
	v_mfma_f32_16x16x32_bf16 v[62:65], v[200:203], v[216:219], v[62:65]
	v_mfma_f32_16x16x32_bf16 v[26:29], v[200:203], v[220:223], v[26:29]
	v_mfma_f32_16x16x32_bf16 v[30:33], v[200:203], v[224:227], v[30:33]
	ds_read_b128 v[200:203], v244 offset:2368
	s_waitcnt lgkmcnt(7)
	v_mfma_f32_16x16x32_bf16 v[34:37], v[204:207], v[212:215], v[34:37]
	v_mfma_f32_16x16x32_bf16 v[38:41], v[204:207], v[216:219], v[38:41]
	v_mfma_f32_16x16x32_bf16 v[2:5], v[204:207], v[220:223], v[2:5]
	v_mfma_f32_16x16x32_bf16 v[6:9], v[204:207], v[224:227], v[6:9]
	ds_read_b128 v[204:207], v244 offset:4672
	s_waitcnt vmcnt(7)
	ds_write_b128 v98, v[102:105] offset:18432
	s_waitcnt vmcnt(6)
	ds_write_b128 v98, v[74:77] offset:23040
	s_waitcnt lgkmcnt(9)
	v_mfma_f32_16x16x32_bf16 v[42:45], v[208:211], v[212:215], v[42:45]
	v_mfma_f32_16x16x32_bf16 v[46:49], v[208:211], v[216:219], v[46:49]
	v_mfma_f32_16x16x32_bf16 v[10:13], v[208:211], v[220:223], v[10:13]
	v_mfma_f32_16x16x32_bf16 v[14:17], v[208:211], v[224:227], v[14:17]
	ds_read_b128 v[208:211], v244 offset:6976
	s_waitcnt vmcnt(5)
	ds_write_b128 v98, v[106:109] offset:27648
	s_waitcnt vmcnt(4)
	ds_write_b128 v98, v[78:81] offset:32256
	s_waitcnt lgkmcnt(7)
	v_mfma_f32_16x16x32_bf16 v[50:53], v[196:199], v[228:231], v[50:53]
	v_mfma_f32_16x16x32_bf16 v[54:57], v[196:199], v[232:235], v[54:57]
	v_mfma_f32_16x16x32_bf16 v[18:21], v[196:199], v[236:239], v[18:21]
	v_mfma_f32_16x16x32_bf16 v[22:25], v[196:199], v[240:243], v[22:25]
	s_waitcnt vmcnt(3)
	ds_write_b128 v98, v[110:113] offset:55296
	s_waitcnt vmcnt(2)
	ds_write_b128 v98, v[82:85] offset:59904
	s_waitcnt lgkmcnt(8)
	v_mfma_f32_16x16x32_bf16 v[58:61], v[200:203], v[228:231], v[58:61]
	v_mfma_f32_16x16x32_bf16 v[62:65], v[200:203], v[232:235], v[62:65]
	v_mfma_f32_16x16x32_bf16 v[26:29], v[200:203], v[236:239], v[26:29]
	v_mfma_f32_16x16x32_bf16 v[30:33], v[200:203], v[240:243], v[30:33]
	s_waitcnt vmcnt(1)
	ds_write_b128 v98, v[114:117] offset:64512
	s_waitcnt vmcnt(0)
	ds_write_b128 v99, v[86:89] offset:32256
	s_waitcnt lgkmcnt(9)
	v_mfma_f32_16x16x32_bf16 v[34:37], v[204:207], v[228:231], v[34:37]
	v_mfma_f32_16x16x32_bf16 v[38:41], v[204:207], v[232:235], v[38:41]
	v_mfma_f32_16x16x32_bf16 v[2:5], v[204:207], v[236:239], v[2:5]
	v_mfma_f32_16x16x32_bf16 v[6:9], v[204:207], v[240:243], v[6:9]
	s_waitcnt lgkmcnt(6)
	v_mfma_f32_16x16x32_bf16 v[42:45], v[208:211], v[228:231], v[42:45]
	v_mfma_f32_16x16x32_bf16 v[46:49], v[208:211], v[232:235], v[46:49]
	v_mfma_f32_16x16x32_bf16 v[10:13], v[208:211], v[236:239], v[10:13]
	v_mfma_f32_16x16x32_bf16 v[14:17], v[208:211], v[240:243], v[14:17]
	s_waitcnt lgkmcnt(0)
	s_barrier
	ds_read_b128 v[212:215], v245 offset:55296
	ds_read_b128 v[196:199], v244 offset:18432
	ds_read_b128 v[216:219], v245 offset:57600
	ds_read_b128 v[220:223], v245 offset:59904
	ds_read_b128 v[224:227], v245 offset:62208
	ds_read_b128 v[200:203], v244 offset:20736
	ds_read_b128 v[204:207], v244 offset:23040
	ds_read_b128 v[208:211], v244 offset:25344
	s_waitcnt lgkmcnt(6)
	v_mfma_f32_16x16x32_bf16 v[50:53], v[196:199], v[212:215], v[50:53]
	ds_read_b128 v[228:231], v245 offset:55360
	s_waitcnt lgkmcnt(6)
	v_mfma_f32_16x16x32_bf16 v[54:57], v[196:199], v[216:219], v[54:57]
	ds_read_b128 v[232:235], v245 offset:57664
	s_waitcnt lgkmcnt(6)
	v_mfma_f32_16x16x32_bf16 v[18:21], v[196:199], v[220:223], v[18:21]
	ds_read_b128 v[236:239], v245 offset:59968
	s_waitcnt lgkmcnt(6)
	v_mfma_f32_16x16x32_bf16 v[22:25], v[196:199], v[224:227], v[22:25]
	ds_read_b128 v[240:243], v245 offset:62272
	ds_read_b128 v[196:199], v244 offset:18496
	s_waitcnt lgkmcnt(7)
	v_mfma_f32_16x16x32_bf16 v[58:61], v[200:203], v[212:215], v[58:61]
	v_mfma_f32_16x16x32_bf16 v[62:65], v[200:203], v[216:219], v[62:65]
	v_mfma_f32_16x16x32_bf16 v[26:29], v[200:203], v[220:223], v[26:29]
	v_mfma_f32_16x16x32_bf16 v[30:33], v[200:203], v[224:227], v[30:33]
	ds_read_b128 v[200:203], v244 offset:20800
	s_waitcnt lgkmcnt(7)
	v_mfma_f32_16x16x32_bf16 v[34:37], v[204:207], v[212:215], v[34:37]
	v_mfma_f32_16x16x32_bf16 v[38:41], v[204:207], v[216:219], v[38:41]
	v_mfma_f32_16x16x32_bf16 v[2:5], v[204:207], v[220:223], v[2:5]
	v_mfma_f32_16x16x32_bf16 v[6:9], v[204:207], v[224:227], v[6:9]
	ds_read_b128 v[204:207], v244 offset:23104
	s_waitcnt lgkmcnt(7)
	v_mfma_f32_16x16x32_bf16 v[42:45], v[208:211], v[212:215], v[42:45]
	v_mfma_f32_16x16x32_bf16 v[46:49], v[208:211], v[216:219], v[46:49]
	v_mfma_f32_16x16x32_bf16 v[10:13], v[208:211], v[220:223], v[10:13]
	v_mfma_f32_16x16x32_bf16 v[14:17], v[208:211], v[224:227], v[14:17]
	ds_read_b128 v[208:211], v244 offset:25408
	s_waitcnt lgkmcnt(3)
	v_mfma_f32_16x16x32_bf16 v[50:53], v[196:199], v[228:231], v[50:53]
	v_mfma_f32_16x16x32_bf16 v[54:57], v[196:199], v[232:235], v[54:57]
	v_mfma_f32_16x16x32_bf16 v[18:21], v[196:199], v[236:239], v[18:21]
	v_mfma_f32_16x16x32_bf16 v[22:25], v[196:199], v[240:243], v[22:25]
	s_waitcnt lgkmcnt(2)
	v_mfma_f32_16x16x32_bf16 v[58:61], v[200:203], v[228:231], v[58:61]
	v_mfma_f32_16x16x32_bf16 v[62:65], v[200:203], v[232:235], v[62:65]
	v_mfma_f32_16x16x32_bf16 v[26:29], v[200:203], v[236:239], v[26:29]
	v_mfma_f32_16x16x32_bf16 v[30:33], v[200:203], v[240:243], v[30:33]
	s_waitcnt lgkmcnt(1)
	v_mfma_f32_16x16x32_bf16 v[34:37], v[204:207], v[228:231], v[34:37]
	v_mfma_f32_16x16x32_bf16 v[38:41], v[204:207], v[232:235], v[38:41]
	v_mfma_f32_16x16x32_bf16 v[2:5], v[204:207], v[236:239], v[2:5]
	v_mfma_f32_16x16x32_bf16 v[6:9], v[204:207], v[240:243], v[6:9]
	s_waitcnt lgkmcnt(0)
	v_mfma_f32_16x16x32_bf16 v[42:45], v[208:211], v[228:231], v[42:45]
	v_mfma_f32_16x16x32_bf16 v[46:49], v[208:211], v[232:235], v[46:49]
	v_mfma_f32_16x16x32_bf16 v[10:13], v[208:211], v[236:239], v[10:13]
	v_mfma_f32_16x16x32_bf16 v[14:17], v[208:211], v[240:243], v[14:17]
	s_lshr_b32 s14, s2, 3
	s_bfe_u32 s13, s2, 0x10002
	s_cmp_lt_i32 s14, 1
	s_mov_b64 s[2:3], -1
	s_waitcnt lgkmcnt(0)
	s_barrier
	s_nop 7
	v_permlane16_swap_b32_e32 v50, v54
	v_permlane16_swap_b32_e32 v51, v55
	v_permlane16_swap_b32_e32 v52, v56
	v_permlane16_swap_b32_e32 v53, v57
	v_permlane16_swap_b32_e32 v58, v62
	v_permlane16_swap_b32_e32 v59, v63
	v_permlane16_swap_b32_e32 v60, v64
	v_permlane16_swap_b32_e32 v61, v65
	v_permlane16_swap_b32_e32 v18, v22
	v_permlane16_swap_b32_e32 v19, v23
	v_permlane16_swap_b32_e32 v20, v24
	v_permlane16_swap_b32_e32 v21, v25
	v_permlane16_swap_b32_e32 v26, v30
	v_permlane16_swap_b32_e32 v27, v31
	v_permlane16_swap_b32_e32 v28, v32
	v_permlane16_swap_b32_e32 v29, v33
	v_permlane16_swap_b32_e32 v34, v38
	v_permlane16_swap_b32_e32 v35, v39
	v_permlane16_swap_b32_e32 v36, v40
	v_permlane16_swap_b32_e32 v37, v41
	v_permlane16_swap_b32_e32 v42, v46
	v_permlane16_swap_b32_e32 v43, v47
	v_permlane16_swap_b32_e32 v44, v48
	v_permlane16_swap_b32_e32 v45, v49
	v_permlane16_swap_b32_e32 v2, v6
	v_permlane16_swap_b32_e32 v3, v7
	v_permlane16_swap_b32_e32 v4, v8
	v_permlane16_swap_b32_e32 v5, v9
	v_permlane16_swap_b32_e32 v10, v14
	v_permlane16_swap_b32_e32 v11, v15
	v_permlane16_swap_b32_e32 v12, v16
	v_permlane16_swap_b32_e32 v13, v17
	v_permlane32_swap_b32_e32 v50, v54
	v_permlane32_swap_b32_e32 v51, v55
	v_permlane32_swap_b32_e32 v52, v56
	v_permlane32_swap_b32_e32 v53, v57
	v_permlane32_swap_b32_e32 v58, v62
	v_permlane32_swap_b32_e32 v59, v63
	v_permlane32_swap_b32_e32 v60, v64
	v_permlane32_swap_b32_e32 v61, v65
	v_permlane32_swap_b32_e32 v18, v22
	v_permlane32_swap_b32_e32 v19, v23
	v_permlane32_swap_b32_e32 v20, v24
	v_permlane32_swap_b32_e32 v21, v25
	v_permlane32_swap_b32_e32 v26, v30
	v_permlane32_swap_b32_e32 v27, v31
	v_permlane32_swap_b32_e32 v28, v32
	v_permlane32_swap_b32_e32 v29, v33
	v_permlane32_swap_b32_e32 v34, v38
	v_permlane32_swap_b32_e32 v35, v39
	v_permlane32_swap_b32_e32 v36, v40
	v_permlane32_swap_b32_e32 v37, v41
	v_permlane32_swap_b32_e32 v42, v46
	v_permlane32_swap_b32_e32 v43, v47
	v_permlane32_swap_b32_e32 v44, v48
	v_permlane32_swap_b32_e32 v45, v49
	v_permlane32_swap_b32_e32 v2, v6
	v_permlane32_swap_b32_e32 v3, v7
	v_permlane32_swap_b32_e32 v4, v8
	v_permlane32_swap_b32_e32 v5, v9
	v_permlane32_swap_b32_e32 v10, v14
	v_permlane32_swap_b32_e32 v11, v15
	v_permlane32_swap_b32_e32 v12, v16
	v_permlane32_swap_b32_e32 v13, v17
	s_cbranch_scc1 .LBB0_1647
	s_and_b32 s2, 0xffff, s14
	s_cmp_lg_u32 s2, 1
	s_mov_b64 s[2:3], -1
	s_cbranch_scc0 .LBB0_1644
	s_cmp_eq_u32 s13, 0
	s_cselect_b32 s12, 3, 10
	s_mov_b64 s[2:3], 0
